# speedup vs baseline: 1.0029x; 1.0029x over previous
; #define WAIT_V(n) asm volatile("s_waitcnt vmcnt(" #n ")" ::: "memory")
; #define WAIT_L(n) asm volatile("s_waitcnt lgkmcnt(" #n ")" ::: "memory")
; #define BAR __builtin_amdgcn_s_barrier()
; #define SCHED __builtin_amdgcn_sched_barrier(0)
; template <bool HS>
; __device__ __forceinline__ void gemm_tile8(const u16* __restrict__ Ap, const u16* __restrict__ Bp, int K,
;                                            f32x4 (&acc)[2][2][4][2], char* shm, const int tid, const float* hsr = nullptr) {
;   const int wid = tid >> 6, lane = tid & 63, wr = wid >> 2, wc = wid & 3, fr = lane & 15, fq = lane >> 4;
;   int r0, c0, r1, c1;
;   stage_rc(tid * 16, r0, c0);
;   stage_rc(tid * 16 + 8192, r1, c1);
;   const unsigned off0 = (unsigned)(r0 * K + c0) * 2u, off1 = (unsigned)(r1 * K + c1) * 2u;
;   const int wvoff = __builtin_amdgcn_readfirstlane(tid >> 6) * 1024;
;   const u16* A1 = Ap + (size_t)128 * K;
;   const u16* B1p = Bp + (size_t)128 * K;
; #pragma unroll
;   for (int a = 0; a < 2; ++a)
; #pragma unroll
;     for (int b = 0; b < 2; ++b)
; #pragma unroll
;       for (int m = 0; m < 4; ++m)
; #pragma unroll
;         for (int n = 0; n < 2; ++n) acc[a][b][m][n] = f32x4{0.f, 0.f, 0.f, 0.f};
;   const int abase = lds_byte(wr * 64 + fr, fq * 8), bbase = lds_byte(wc * 32 + fr, fq * 8);
;   bf16x8 At[4][2], B0[2][2], B1[2][2];
;   const unsigned lds0 = (unsigned)(size_t)(__attribute__((address_space(3))) char*)shm + (unsigned)wvoff;
;     ...
;   const int nt = K / BK;
;   WAIT_V(0);
;   if (wr == 1) BAR;
;   BAR;
;   BAR;
;   for (int t = 0; t < nt - 2; t += 2) {
;     if constexpr (HS) {
;       if (t > 0 && (t & 7) == 0) {
;         const float* rt = hsr + ((t >> 3) - 1) * 256 + wr * 64 + fq * 4;
; #pragma unroll
;         for (int ai = 0; ai < 2; ++ai)
; #pragma unroll
;           for (int m = 0; m < 4; ++m) {
;             const f32x4 q4 = *(const f32x4*)(rt + ai * 128 + m * 16);
; #pragma unroll
;             for (int bj = 0; bj < 2; ++bj)
; #pragma unroll
;               for (int n = 0; n < 2; ++n) acc[ai][bj][m][n] *= q4;
;             SCHED;
;           }
;       }
;     }
;     LDB8(B0, 0, 0); SCHED; LDA8(0, 0); STG_A(1, 1, t + 1);
;     WAIT_L(8); BAR; WAIT_L(0); MMA8(0, 0, B0); BAR; SCHED;
;     LDB8(B1, 0, 1); STG_B(0, 0, t + 2);
;     BAR; WAIT_L(0); MMA8(0, 1, B1); BAR;
.LBB0_98:
	s_or_b64 exec, exec, s[2:3]
	v_mov_b32_e32 v4, s14
	v_bfe_i32 v4, v4, 0, 8
	v_ashrrev_i32_e32 v5, 31, v4
	v_lshlrev_b64 v[4:5], 19, v[4:5]
	v_bfe_i32 v6, v0, 27, 1
	v_lshl_add_u64 v[130:131], s[0:1], 0, v[4:5]
	v_lshlrev_b32_e32 v4, 4, v0
	v_lshrrev_b32_e32 v6, 22, v6
	v_add_u32_e32 v6, v4, v6
	v_and_b32_e32 v6, 0xfffffc00, v6
	v_ashrrev_i32_e32 v5, 31, v0
	v_sub_u32_e32 v6, v4, v6
	v_lshrrev_b32_e32 v5, 26, v5
	v_lshrrev_b32_e32 v7, 4, v6
	v_add_u32_e32 v5, v0, v5
	v_bitop3_b32 v7, v7, v6, 32 bitop3:0x6c
	v_ashrrev_i32_e32 v6, 31, v6
	v_ashrrev_i32_e32 v5, 6, v5
	v_lshrrev_b32_e32 v6, 26, v6
	v_lshlrev_b32_e32 v8, 3, v5
	v_add_u32_e32 v6, v7, v6
	v_and_b32_e32 v8, 0x1ffff0, v8
	v_ashrrev_i32_e32 v6, 6, v6
	v_add_u32_e32 v8, v6, v8
	v_mul_i32_i24_e32 v6, 64, v6
	v_add_u32_e32 v4, 0x2000, v4
	v_sub_u32_e32 v6, v7, v6
	v_ashrrev_i32_e32 v7, 31, v4
	v_lshrrev_b32_e32 v7, 22, v7
	v_add_u32_e32 v7, v4, v7
	v_ashrrev_i32_e32 v7, 10, v7
	v_mul_i32_i24_e32 v9, 0x400, v7
	v_sub_u32_e32 v4, v4, v9
	v_lshrrev_b32_e32 v9, 4, v4
	v_bitop3_b32 v4, v9, v4, 32 bitop3:0x6c
	v_ashrrev_i32_e32 v10, 31, v4
	v_lshrrev_b32_e32 v10, 26, v10
	v_add_u32_e32 v10, v4, v10
	v_lshlrev_b32_e32 v9, 3, v7
	v_lshrrev_b32_e32 v11, 6, v10
	v_and_b32_e32 v10, 0xc0, v10
	s_ashr_i32 s5, s4, 31
	v_and_b32_e32 v9, 0x1ffff0, v9
	v_lshlrev_b32_e32 v7, 5, v7
	v_sub_u32_e32 v4, v4, v10
	s_lshl_b64 s[10:11], s[4:5], 11
	v_readlane_b32 s2, v253, 63
	v_lshlrev_b32_e32 v5, 5, v5
	v_add_u32_e32 v9, v11, v9
	v_and_b32_e32 v7, 32, v7
	v_ashrrev_i16_sdwa v4, v178, sext(v4) dst_sel:DWORD dst_unused:UNUSED_PAD src0_sel:DWORD src1_sel:BYTE_0
	v_readlane_b32 s3, v254, 0
	s_add_u32 s9, s2, s10
	v_and_b32_e32 v5, 32, v5
	v_ashrrev_i16_sdwa v6, v178, sext(v6) dst_sel:DWORD dst_unused:UNUSED_PAD src0_sel:DWORD src1_sel:BYTE_0
	v_bfe_i32 v4, v4, 0, 16
	v_lshl_or_b32 v7, v9, 10, v7
	s_addc_u32 s12, s3, s11
	v_bfe_i32 v6, v6, 0, 16
	v_lshl_or_b32 v5, v8, 10, v5
	v_and_b32_e32 v8, 15, v0
	v_add_lshl_u32 v135, v7, v4, 1
	s_lshl_b32 s13, s13, 10
	v_lshlrev_b32_e32 v7, 2, v0
	v_add_lshl_u32 v136, v5, v6, 1
	s_mov_b64 s[2:3], 0x40000
	v_and_b32_e32 v4, 48, v0
	v_lshlrev_b32_e32 v5, 6, v8
	v_and_b32_e32 v7, 32, v7
	s_add_i32 s14, s13, 0
	v_lshl_add_u64 v[132:133], v[130:131], 0, s[2:3]
	v_or_b32_e32 v6, v5, v4
	v_bitop3_b32 v4, v5, v7, v4 bitop3:0x36
	v_lshlrev_b32_e32 v2, 12, v2
	s_movk_i32 s2, 0x3000
	s_add_u32 s15, s9, 0x40100
	v_lshlrev_b32_e32 v3, 13, v3
	v_and_or_b32 v137, v2, s2, v4
	s_addc_u32 s16, s12, 0
	v_readlane_b32 s2, v254, 32
	v_bitop3_b32 v3, v6, v3, v7 bitop3:0xde
	s_add_u32 s17, s2, s10
	v_readlane_b32 s2, v254, 33
	v_mov_b32_e32 v2, 0
	s_addc_u32 s18, s2, s11
	s_mov_b32 s19, -2
	s_mov_b64 s[2:3], 0
	v_add_u32_e32 v134, 0, v3
	s_waitcnt lgkmcnt(0)
	v_readfirstlane_b32 s24, v130
	v_readfirstlane_b32 s25, v131
	v_readfirstlane_b32 s26, v132
	v_readfirstlane_b32 s27, v133
	s_barrier
	s_barrier
	v_add_u32_e32 v158, 0x10000, v137
	ds_read_b128 v[138:141], v158
	ds_read_b128 v[142:145], v158 offset:1024
	ds_read_b128 v[154:157], v158 offset:2048
	ds_read_b128 v[158:161], v158 offset:3072
	ds_read_b128 v[162:165], v134
	ds_read_b128 v[166:169], v134 offset:1024
	ds_read_b128 v[170:173], v134 offset:2048
	ds_read_b128 v[174:177], v134 offset:3072
	ds_read_b128 v[180:183], v134 offset:4096
	ds_read_b128 v[184:187], v134 offset:5120
	ds_read_b128 v[188:191], v134 offset:6144
	ds_read_b128 v[192:195], v134 offset:7168
	v_add_u32_e32 v208, 0x14000, v137
	ds_read_b128 v[196:199], v208
	ds_read_b128 v[200:203], v208 offset:1024
	ds_read_b128 v[204:207], v208 offset:2048
	ds_read_b128 v[208:211], v208 offset:3072
	s_add_u32 s22, s17, s2
	s_addc_u32 s23, s18, s3
	s_add_u32 s22, s22, 0x80
	s_addc_u32 s23, s23, 0
	s_add_i32 s36, s14, 0xc000
	s_mov_b32 m0, s36
	s_nop 0
	global_load_lds_dwordx4 v136, s[22:23]
	s_add_i32 s36, s14, 0xe000
	s_mov_b32 m0, s36
	s_nop 0
	global_load_lds_dwordx4 v135, s[22:23]
	s_waitcnt vmcnt(8) lgkmcnt(0)
	s_barrier
	s_setprio 1
	v_mfma_f32_16x16x32_bf16 v[126:129], v[162:165], v[138:141], 0
	v_mfma_f32_16x16x32_bf16 v[122:125], v[162:165], v[154:157], 0
	v_mfma_f32_16x16x32_bf16 v[114:117], v[170:173], v[154:157], 0
	v_mfma_f32_16x16x32_bf16 v[118:121], v[170:173], v[138:141], 0
	v_mfma_f32_16x16x32_bf16 v[110:113], v[180:183], v[138:141], 0
	v_mfma_f32_16x16x32_bf16 v[106:109], v[180:183], v[154:157], 0
	v_mfma_f32_16x16x32_bf16 v[98:101], v[188:191], v[154:157], 0
	v_mfma_f32_16x16x32_bf16 v[102:105], v[188:191], v[138:141], 0
	v_mfma_f32_16x16x32_bf16 v[126:129], v[166:169], v[142:145], v[126:129]
	v_mfma_f32_16x16x32_bf16 v[122:125], v[166:169], v[158:161], v[122:125]
	v_mfma_f32_16x16x32_bf16 v[114:117], v[174:177], v[158:161], v[114:117]
	v_mfma_f32_16x16x32_bf16 v[118:121], v[174:177], v[142:145], v[118:121]
	v_mfma_f32_16x16x32_bf16 v[110:113], v[184:187], v[142:145], v[110:113]
	v_mfma_f32_16x16x32_bf16 v[106:109], v[184:187], v[158:161], v[106:109]
	v_mfma_f32_16x16x32_bf16 v[98:101], v[192:195], v[158:161], v[98:101]
	v_mfma_f32_16x16x32_bf16 v[102:105], v[192:195], v[142:145], v[102:105]
	v_mfma_f32_16x16x32_bf16 v[94:97], v[162:165], v[196:199], 0
	v_mfma_f32_16x16x32_bf16 v[90:93], v[162:165], v[204:207], 0
	v_mfma_f32_16x16x32_bf16 v[82:85], v[170:173], v[204:207], 0
	v_mfma_f32_16x16x32_bf16 v[86:89], v[170:173], v[196:199], 0
	v_mfma_f32_16x16x32_bf16 v[78:81], v[180:183], v[196:199], 0
	v_mfma_f32_16x16x32_bf16 v[74:77], v[180:183], v[204:207], 0
	v_mfma_f32_16x16x32_bf16 v[66:69], v[188:191], v[204:207], 0
	v_mfma_f32_16x16x32_bf16 v[70:73], v[188:191], v[196:199], 0
	v_mfma_f32_16x16x32_bf16 v[94:97], v[166:169], v[200:203], v[94:97]
	v_mfma_f32_16x16x32_bf16 v[90:93], v[166:169], v[208:211], v[90:93]
	v_mfma_f32_16x16x32_bf16 v[82:85], v[174:177], v[208:211], v[82:85]
	v_mfma_f32_16x16x32_bf16 v[86:89], v[174:177], v[200:203], v[86:89]
	v_mfma_f32_16x16x32_bf16 v[78:81], v[184:187], v[200:203], v[78:81]
	v_mfma_f32_16x16x32_bf16 v[74:77], v[184:187], v[208:211], v[74:77]
	v_mfma_f32_16x16x32_bf16 v[66:69], v[192:195], v[208:211], v[66:69]
	v_mfma_f32_16x16x32_bf16 v[70:73], v[192:195], v[200:203], v[70:73]
	s_setprio 0
	s_barrier
; #define WAIT_V(n) asm volatile("s_waitcnt vmcnt(" #n ")" ::: "memory")
; #define WAIT_L(n) asm volatile("s_waitcnt lgkmcnt(" #n ")" ::: "memory")
; #define BAR __builtin_amdgcn_s_barrier()
; #define SCHED __builtin_amdgcn_sched_barrier(0)
; #define STG_A(b, h, kt) stage_half_s(lds0 + ((b) * 2 + (h)) * HT_B, ((h) ? A1 : Ap) + (kt) * BK, off0, off1)
; #define STG_B(b, h, kt) stage_half_s(lds0 + (4 + (b) * 2 + (h)) * HT_B, ((h) ? B1p : Bp) + (kt) * BK, off0, off1)
; #define STG_A(b, h, kt) stage_half_s(lds0 + ((b) * 2 + (h)) * HT_B, ((h) ? A1 : Ap) + (kt) * BK, off0, off1)
; #define STG_B(b, h, kt) stage_half_s(lds0 + (4 + (b) * 2 + (h)) * HT_B, ((h) ? B1p : Bp) + (kt) * BK, off0, off1)
; #define LDA8(b, h) _Pragma("unroll") for (int m = 0; m < 4; ++m) _Pragma("unroll") for (int k = 0; k < 2; ++k) \
;     At[m][k] = *(const bf16x8*)(SA_(shm, b, h) + abase + (m * 2 + k) * 1024)
; #define LDB8(dst, b, h) _Pragma("unroll") for (int n = 0; n < 2; ++n) _Pragma("unroll") for (int k = 0; k < 2; ++k) \
;     dst[n][k] = *(const bf16x8*)(SB_(shm, b, h) + bbase + (n * 2 + k) * 1024)
; #define MMA8(ai, bj, Bx) do { __builtin_amdgcn_s_setprio(1); \
;     _Pragma("unroll") for (int m = 0; m < 4; ++m) _Pragma("unroll") for (int n = 0; n < 2; ++n) _Pragma("unroll") for (int k = 0; k < 2; ++k) \
;       acc[ai][bj][m][n] = __builtin_amdgcn_mfma_f32_16x16x32_bf16(At[m][k], Bx[n][k], acc[ai][bj][m][n], 0, 0, 0); \
;     __builtin_amdgcn_s_setprio(0); } while (0)
; template <bool HS>
; __device__ __forceinline__ void gemm_tile8(const u16* __restrict__ Ap, const u16* __restrict__ Bp, int K,
;                                            f32x4 (&acc)[2][2][4][2], char* shm, const int tid, const float* hsr = nullptr) {
;     ...
;     LDA8(0, 1); STG_A(0, 0, t + 2);
;     BAR; WAIT_L(0); MMA8(1, 0, B0); BAR; SCHED;
;     STG_B(0, 1, t + 2);
;     WAIT_V(6); BAR; MMA8(1, 1, B1); BAR;
;     LDB8(B0, 1, 0); SCHED; LDA8(1, 0); STG_A(0, 1, t + 2);
;     WAIT_L(8); BAR; WAIT_L(0); MMA8(0, 0, B0); BAR; SCHED;
;     LDB8(B1, 1, 1); STG_B(1, 0, t + 3);
;     BAR; WAIT_L(0); MMA8(0, 1, B1); BAR;
	ds_read_b128 v[162:165], v134 offset:16384
	ds_read_b128 v[166:169], v134 offset:17408
	ds_read_b128 v[170:173], v134 offset:18432
	ds_read_b128 v[174:177], v134 offset:19456
	ds_read_b128 v[180:183], v134 offset:20480
	ds_read_b128 v[184:187], v134 offset:21504
	ds_read_b128 v[188:191], v134 offset:22528
	ds_read_b128 v[192:195], v134 offset:23552
	s_add_u32 s22, s24, s2
	s_addc_u32 s23, s25, s3
	s_add_u32 s22, s22, 0x100
	s_addc_u32 s23, s23, 0
	s_add_i32 s36, s14, 0x10000
	s_mov_b32 m0, s36
	s_nop 0
	global_load_lds_dwordx4 v136, s[22:23]
	s_add_i32 s36, s14, 0x12000
	s_mov_b32 m0, s36
	s_nop 0
	global_load_lds_dwordx4 v135, s[22:23]
	s_add_u32 s22, s9, s2
	s_addc_u32 s23, s12, s3
	s_add_u32 s22, s22, 0x100
	s_addc_u32 s23, s23, 0
	s_mov_b32 m0, s14
	s_nop 0
	global_load_lds_dwordx4 v136, s[22:23]
	s_add_i32 s36, s14, 0x2000
	s_mov_b32 m0, s36
	s_nop 0
	global_load_lds_dwordx4 v135, s[22:23]
	s_add_u32 s22, s26, s2
	s_addc_u32 s23, s27, s3
	s_add_u32 s22, s22, 0x100
	s_addc_u32 s23, s23, 0
	s_add_i32 s36, s14, 0x14000
	s_mov_b32 m0, s36
	s_nop 0
	global_load_lds_dwordx4 v136, s[22:23]
	s_add_i32 s36, s14, 0x16000
	s_mov_b32 m0, s36
	s_nop 0
	global_load_lds_dwordx4 v135, s[22:23]
	s_waitcnt vmcnt(8) lgkmcnt(0)
	s_barrier
	s_setprio 1
	v_mfma_f32_16x16x32_bf16 v[62:65], v[162:165], v[138:141], 0
	v_mfma_f32_16x16x32_bf16 v[58:61], v[162:165], v[154:157], 0
	v_mfma_f32_16x16x32_bf16 v[50:53], v[170:173], v[154:157], 0
	v_mfma_f32_16x16x32_bf16 v[54:57], v[170:173], v[138:141], 0
	v_mfma_f32_16x16x32_bf16 v[46:49], v[180:183], v[138:141], 0
	v_mfma_f32_16x16x32_bf16 v[42:45], v[180:183], v[154:157], 0
	v_mfma_f32_16x16x32_bf16 v[34:37], v[188:191], v[154:157], 0
	v_mfma_f32_16x16x32_bf16 v[38:41], v[188:191], v[138:141], 0
	v_mfma_f32_16x16x32_bf16 v[62:65], v[166:169], v[142:145], v[62:65]
	v_mfma_f32_16x16x32_bf16 v[58:61], v[166:169], v[158:161], v[58:61]
	v_mfma_f32_16x16x32_bf16 v[50:53], v[174:177], v[158:161], v[50:53]
	v_mfma_f32_16x16x32_bf16 v[54:57], v[174:177], v[142:145], v[54:57]
	v_mfma_f32_16x16x32_bf16 v[46:49], v[184:187], v[142:145], v[46:49]
	v_mfma_f32_16x16x32_bf16 v[42:45], v[184:187], v[158:161], v[42:45]
	v_mfma_f32_16x16x32_bf16 v[34:37], v[192:195], v[158:161], v[34:37]
	v_mfma_f32_16x16x32_bf16 v[38:41], v[192:195], v[142:145], v[38:41]
	v_mfma_f32_16x16x32_bf16 v[30:33], v[162:165], v[196:199], 0
	v_mfma_f32_16x16x32_bf16 v[26:29], v[162:165], v[204:207], 0
	v_mfma_f32_16x16x32_bf16 v[18:21], v[170:173], v[204:207], 0
	v_mfma_f32_16x16x32_bf16 v[22:25], v[170:173], v[196:199], 0
	v_mfma_f32_16x16x32_bf16 v[14:17], v[180:183], v[196:199], 0
	v_mfma_f32_16x16x32_bf16 v[10:13], v[180:183], v[204:207], 0
	v_mfma_f32_16x16x32_bf16 v[2:5], v[188:191], v[204:207], 0
	v_mfma_f32_16x16x32_bf16 v[6:9], v[188:191], v[196:199], 0
	v_mfma_f32_16x16x32_bf16 v[30:33], v[166:169], v[200:203], v[30:33]
	v_mfma_f32_16x16x32_bf16 v[26:29], v[166:169], v[208:211], v[26:29]
	v_mfma_f32_16x16x32_bf16 v[18:21], v[174:177], v[208:211], v[18:21]
	v_mfma_f32_16x16x32_bf16 v[22:25], v[174:177], v[200:203], v[22:25]
	v_mfma_f32_16x16x32_bf16 v[14:17], v[184:187], v[200:203], v[14:17]
	v_mfma_f32_16x16x32_bf16 v[10:13], v[184:187], v[208:211], v[10:13]
	v_mfma_f32_16x16x32_bf16 v[2:5], v[192:195], v[208:211], v[2:5]
	v_mfma_f32_16x16x32_bf16 v[6:9], v[192:195], v[200:203], v[6:9]
	s_setprio 0
	s_barrier
	v_add_u32_e32 v158, 0x18000, v137
	ds_read_b128 v[138:141], v158
	ds_read_b128 v[142:145], v158 offset:1024
	ds_read_b128 v[154:157], v158 offset:2048
	ds_read_b128 v[158:161], v158 offset:3072
	ds_read_b128 v[162:165], v134 offset:32768
	ds_read_b128 v[166:169], v134 offset:33792
	ds_read_b128 v[170:173], v134 offset:34816
	ds_read_b128 v[174:177], v134 offset:35840
	ds_read_b128 v[180:183], v134 offset:36864
	ds_read_b128 v[184:187], v134 offset:37888
	ds_read_b128 v[188:191], v134 offset:38912
	ds_read_b128 v[192:195], v134 offset:39936
	v_add_u32_e32 v208, 0x1c000, v137
	ds_read_b128 v[196:199], v208
	ds_read_b128 v[200:203], v208 offset:1024
	ds_read_b128 v[204:207], v208 offset:2048
	ds_read_b128 v[208:211], v208 offset:3072
	s_add_u32 s22, s17, s2
	s_addc_u32 s23, s18, s3
	s_add_u32 s22, s22, 0x100
	s_addc_u32 s23, s23, 0
	s_add_i32 s36, s14, 0x4000
	s_mov_b32 m0, s36
	s_nop 0
	global_load_lds_dwordx4 v136, s[22:23]
	s_add_i32 s36, s14, 0x6000
	s_mov_b32 m0, s36
	s_nop 0
	global_load_lds_dwordx4 v135, s[22:23]
	s_waitcnt vmcnt(8) lgkmcnt(0)
	s_barrier
	s_setprio 1
	v_mfma_f32_16x16x32_bf16 v[126:129], v[162:165], v[138:141], v[126:129]
	v_mfma_f32_16x16x32_bf16 v[122:125], v[162:165], v[154:157], v[122:125]
	v_mfma_f32_16x16x32_bf16 v[114:117], v[170:173], v[154:157], v[114:117]
	v_mfma_f32_16x16x32_bf16 v[118:121], v[170:173], v[138:141], v[118:121]
	v_mfma_f32_16x16x32_bf16 v[110:113], v[180:183], v[138:141], v[110:113]
	v_mfma_f32_16x16x32_bf16 v[106:109], v[180:183], v[154:157], v[106:109]
	v_mfma_f32_16x16x32_bf16 v[98:101], v[188:191], v[154:157], v[98:101]
	v_mfma_f32_16x16x32_bf16 v[102:105], v[188:191], v[138:141], v[102:105]
	v_mfma_f32_16x16x32_bf16 v[126:129], v[166:169], v[142:145], v[126:129]
	v_mfma_f32_16x16x32_bf16 v[122:125], v[166:169], v[158:161], v[122:125]
	v_mfma_f32_16x16x32_bf16 v[114:117], v[174:177], v[158:161], v[114:117]
	v_mfma_f32_16x16x32_bf16 v[118:121], v[174:177], v[142:145], v[118:121]
	v_mfma_f32_16x16x32_bf16 v[110:113], v[184:187], v[142:145], v[110:113]
	v_mfma_f32_16x16x32_bf16 v[106:109], v[184:187], v[158:161], v[106:109]
	v_mfma_f32_16x16x32_bf16 v[98:101], v[192:195], v[158:161], v[98:101]
	v_mfma_f32_16x16x32_bf16 v[102:105], v[192:195], v[142:145], v[102:105]
	v_mfma_f32_16x16x32_bf16 v[94:97], v[162:165], v[196:199], v[94:97]
	v_mfma_f32_16x16x32_bf16 v[90:93], v[162:165], v[204:207], v[90:93]
	v_mfma_f32_16x16x32_bf16 v[82:85], v[170:173], v[204:207], v[82:85]
	v_mfma_f32_16x16x32_bf16 v[86:89], v[170:173], v[196:199], v[86:89]
	v_mfma_f32_16x16x32_bf16 v[78:81], v[180:183], v[196:199], v[78:81]
	v_mfma_f32_16x16x32_bf16 v[74:77], v[180:183], v[204:207], v[74:77]
	v_mfma_f32_16x16x32_bf16 v[66:69], v[188:191], v[204:207], v[66:69]
	v_mfma_f32_16x16x32_bf16 v[70:73], v[188:191], v[196:199], v[70:73]
	v_mfma_f32_16x16x32_bf16 v[94:97], v[166:169], v[200:203], v[94:97]
	v_mfma_f32_16x16x32_bf16 v[90:93], v[166:169], v[208:211], v[90:93]
	v_mfma_f32_16x16x32_bf16 v[82:85], v[174:177], v[208:211], v[82:85]
	v_mfma_f32_16x16x32_bf16 v[86:89], v[174:177], v[200:203], v[86:89]
	v_mfma_f32_16x16x32_bf16 v[78:81], v[184:187], v[200:203], v[78:81]
	v_mfma_f32_16x16x32_bf16 v[74:77], v[184:187], v[208:211], v[74:77]
	v_mfma_f32_16x16x32_bf16 v[66:69], v[192:195], v[208:211], v[66:69]
	v_mfma_f32_16x16x32_bf16 v[70:73], v[192:195], v[200:203], v[70:73]
	s_setprio 0
	s_barrier
; #define WAIT_V(n) asm volatile("s_waitcnt vmcnt(" #n ")" ::: "memory")
; #define WAIT_L(n) asm volatile("s_waitcnt lgkmcnt(" #n ")" ::: "memory")
; #define BAR __builtin_amdgcn_s_barrier()
; #define SCHED __builtin_amdgcn_sched_barrier(0)
; #define STG_A(b, h, kt) stage_half_s(lds0 + ((b) * 2 + (h)) * HT_B, ((h) ? A1 : Ap) + (kt) * BK, off0, off1)
; #define STG_B(b, h, kt) stage_half_s(lds0 + (4 + (b) * 2 + (h)) * HT_B, ((h) ? B1p : Bp) + (kt) * BK, off0, off1)
; #define STG_A(b, h, kt) stage_half_s(lds0 + ((b) * 2 + (h)) * HT_B, ((h) ? A1 : Ap) + (kt) * BK, off0, off1)
; #define STG_B(b, h, kt) stage_half_s(lds0 + (4 + (b) * 2 + (h)) * HT_B, ((h) ? B1p : Bp) + (kt) * BK, off0, off1)
; #define LDA8(b, h) _Pragma("unroll") for (int m = 0; m < 4; ++m) _Pragma("unroll") for (int k = 0; k < 2; ++k) \
;     At[m][k] = *(const bf16x8*)(SA_(shm, b, h) + abase + (m * 2 + k) * 1024)
; #define LDB8(dst, b, h) _Pragma("unroll") for (int n = 0; n < 2; ++n) _Pragma("unroll") for (int k = 0; k < 2; ++k) \
;     dst[n][k] = *(const bf16x8*)(SB_(shm, b, h) + bbase + (n * 2 + k) * 1024)
; #define MMA8(ai, bj, Bx) do { __builtin_amdgcn_s_setprio(1); \
;     _Pragma("unroll") for (int m = 0; m < 4; ++m) _Pragma("unroll") for (int n = 0; n < 2; ++n) _Pragma("unroll") for (int k = 0; k < 2; ++k) \
;       acc[ai][bj][m][n] = __builtin_amdgcn_mfma_f32_16x16x32_bf16(At[m][k], Bx[n][k], acc[ai][bj][m][n], 0, 0, 0); \
;     __builtin_amdgcn_s_setprio(0); } while (0)
; template <bool HS>
; __device__ __forceinline__ void gemm_tile8(const u16* __restrict__ Ap, const u16* __restrict__ Bp, int K,
;                                            f32x4 (&acc)[2][2][4][2], char* shm, const int tid, const float* hsr = nullptr) {
;     ...
;     LDB8(B0, 0, 0); SCHED; LDA8(0, 0); STG_A(1, 1, t + 1);
;     WAIT_L(8); BAR; WAIT_L(0); MMA8(0, 0, B0); BAR; SCHED;
;     LDB8(B1, 0, 1); STG_B(0, 0, t + 2);
;     ...
;     LDA8(1, 1); STG_A(1, 0, t + 3);
;     BAR; WAIT_L(0); MMA8(1, 0, B0); BAR; SCHED;
;     STG_B(1, 1, t + 3);
;     WAIT_V(6); BAR; MMA8(1, 1, B1); BAR;
;   }
	ds_read_b128 v[162:165], v134 offset:49152
	ds_read_b128 v[166:169], v134 offset:50176
	ds_read_b128 v[170:173], v134 offset:51200
	ds_read_b128 v[174:177], v134 offset:52224
	ds_read_b128 v[180:183], v134 offset:53248
	ds_read_b128 v[184:187], v134 offset:54272
	ds_read_b128 v[188:191], v134 offset:55296
	ds_read_b128 v[192:195], v134 offset:56320
	s_add_u32 s22, s24, s2
	s_addc_u32 s23, s25, s3
	s_add_u32 s22, s22, 0x180
	s_addc_u32 s23, s23, 0
	s_add_i32 s36, s14, 0x18000
	s_mov_b32 m0, s36
	s_nop 0
	global_load_lds_dwordx4 v136, s[22:23]
	s_add_i32 s36, s14, 0x1a000
	s_mov_b32 m0, s36
	s_nop 0
	global_load_lds_dwordx4 v135, s[22:23]
	s_add_u32 s22, s9, s2
	s_addc_u32 s23, s12, s3
	s_add_u32 s22, s22, 0x180
	s_addc_u32 s23, s23, 0
	s_add_i32 s36, s14, 0x8000
	s_mov_b32 m0, s36
	s_nop 0
	global_load_lds_dwordx4 v136, s[22:23]
	s_add_i32 s36, s14, 0xa000
	s_mov_b32 m0, s36
	s_nop 0
	global_load_lds_dwordx4 v135, s[22:23]
	s_add_u32 s22, s26, s2
	s_addc_u32 s23, s27, s3
	s_add_u32 s22, s22, 0x180
	s_addc_u32 s23, s23, 0
	s_add_i32 s36, s14, 0x1c000
	s_mov_b32 m0, s36
	s_nop 0
	global_load_lds_dwordx4 v136, s[22:23]
	s_add_i32 s36, s14, 0x1e000
	s_mov_b32 m0, s36
	s_nop 0
	global_load_lds_dwordx4 v135, s[22:23]
	s_waitcnt vmcnt(8) lgkmcnt(0)
	s_barrier
	s_setprio 1
	v_mfma_f32_16x16x32_bf16 v[62:65], v[162:165], v[138:141], v[62:65]
	v_mfma_f32_16x16x32_bf16 v[58:61], v[162:165], v[154:157], v[58:61]
	v_mfma_f32_16x16x32_bf16 v[50:53], v[170:173], v[154:157], v[50:53]
	v_mfma_f32_16x16x32_bf16 v[54:57], v[170:173], v[138:141], v[54:57]
	v_mfma_f32_16x16x32_bf16 v[46:49], v[180:183], v[138:141], v[46:49]
	v_mfma_f32_16x16x32_bf16 v[42:45], v[180:183], v[154:157], v[42:45]
	v_mfma_f32_16x16x32_bf16 v[34:37], v[188:191], v[154:157], v[34:37]
	v_mfma_f32_16x16x32_bf16 v[38:41], v[188:191], v[138:141], v[38:41]
	v_mfma_f32_16x16x32_bf16 v[62:65], v[166:169], v[142:145], v[62:65]
	v_mfma_f32_16x16x32_bf16 v[58:61], v[166:169], v[158:161], v[58:61]
	v_mfma_f32_16x16x32_bf16 v[50:53], v[174:177], v[158:161], v[50:53]
	v_mfma_f32_16x16x32_bf16 v[54:57], v[174:177], v[142:145], v[54:57]
	v_mfma_f32_16x16x32_bf16 v[46:49], v[184:187], v[142:145], v[46:49]
	v_mfma_f32_16x16x32_bf16 v[42:45], v[184:187], v[158:161], v[42:45]
	v_mfma_f32_16x16x32_bf16 v[34:37], v[192:195], v[158:161], v[34:37]
	v_mfma_f32_16x16x32_bf16 v[38:41], v[192:195], v[142:145], v[38:41]
	v_mfma_f32_16x16x32_bf16 v[30:33], v[162:165], v[196:199], v[30:33]
	v_mfma_f32_16x16x32_bf16 v[26:29], v[162:165], v[204:207], v[26:29]
	v_mfma_f32_16x16x32_bf16 v[18:21], v[170:173], v[204:207], v[18:21]
	v_mfma_f32_16x16x32_bf16 v[22:25], v[170:173], v[196:199], v[22:25]
	v_mfma_f32_16x16x32_bf16 v[14:17], v[180:183], v[196:199], v[14:17]
	v_mfma_f32_16x16x32_bf16 v[10:13], v[180:183], v[204:207], v[10:13]
	v_mfma_f32_16x16x32_bf16 v[2:5], v[188:191], v[204:207], v[2:5]
	v_mfma_f32_16x16x32_bf16 v[6:9], v[188:191], v[196:199], v[6:9]
	v_mfma_f32_16x16x32_bf16 v[30:33], v[166:169], v[200:203], v[30:33]
	v_mfma_f32_16x16x32_bf16 v[26:29], v[166:169], v[208:211], v[26:29]
	v_mfma_f32_16x16x32_bf16 v[18:21], v[174:177], v[208:211], v[18:21]
	v_mfma_f32_16x16x32_bf16 v[22:25], v[174:177], v[200:203], v[22:25]
	v_mfma_f32_16x16x32_bf16 v[14:17], v[184:187], v[200:203], v[14:17]
	v_mfma_f32_16x16x32_bf16 v[10:13], v[184:187], v[208:211], v[10:13]
	v_mfma_f32_16x16x32_bf16 v[2:5], v[192:195], v[208:211], v[2:5]
	v_mfma_f32_16x16x32_bf16 v[6:9], v[192:195], v[200:203], v[6:9]
	s_setprio 0
	s_barrier
	s_add_i32 s19, s19, 2
	s_add_u32 s2, s2, 0x100
	s_addc_u32 s3, s3, 0
	s_cmp_lt_u32 s19, 12
	s_cbranch_scc0 .Lk_conv_out_exit
.Lk_conv_out:
	v_add_u32_e32 v158, 0x10000, v137
	ds_read_b128 v[138:141], v158
	ds_read_b128 v[142:145], v158 offset:1024
	ds_read_b128 v[154:157], v158 offset:2048
	ds_read_b128 v[158:161], v158 offset:3072
	ds_read_b128 v[162:165], v134
	ds_read_b128 v[166:169], v134 offset:1024
	ds_read_b128 v[170:173], v134 offset:2048
	ds_read_b128 v[174:177], v134 offset:3072
	ds_read_b128 v[180:183], v134 offset:4096
	ds_read_b128 v[184:187], v134 offset:5120
	ds_read_b128 v[188:191], v134 offset:6144
	ds_read_b128 v[192:195], v134 offset:7168
	v_add_u32_e32 v208, 0x14000, v137
	ds_read_b128 v[196:199], v208
	ds_read_b128 v[200:203], v208 offset:1024
	ds_read_b128 v[204:207], v208 offset:2048
	ds_read_b128 v[208:211], v208 offset:3072
	s_add_u32 s22, s17, s2
	s_addc_u32 s23, s18, s3
	s_add_u32 s22, s22, 0x80
	s_addc_u32 s23, s23, 0
	s_add_i32 s36, s14, 0xc000
	s_mov_b32 m0, s36
	s_nop 0
	global_load_lds_dwordx4 v136, s[22:23]
	s_add_i32 s36, s14, 0xe000
	s_mov_b32 m0, s36
	s_nop 0
	global_load_lds_dwordx4 v135, s[22:23]
	s_waitcnt vmcnt(8) lgkmcnt(0)
	s_barrier
; #define WAIT_V(n) asm volatile("s_waitcnt vmcnt(" #n ")" ::: "memory")
; #define WAIT_L(n) asm volatile("s_waitcnt lgkmcnt(" #n ")" ::: "memory")
; #define BAR __builtin_amdgcn_s_barrier()
; #define SCHED __builtin_amdgcn_sched_barrier(0)
; #define STG_A(b, h, kt) stage_half_s(lds0 + ((b) * 2 + (h)) * HT_B, ((h) ? A1 : Ap) + (kt) * BK, off0, off1)
; #define STG_B(b, h, kt) stage_half_s(lds0 + (4 + (b) * 2 + (h)) * HT_B, ((h) ? B1p : Bp) + (kt) * BK, off0, off1)
; #define STG_A(b, h, kt) stage_half_s(lds0 + ((b) * 2 + (h)) * HT_B, ((h) ? A1 : Ap) + (kt) * BK, off0, off1)
; #define STG_B(b, h, kt) stage_half_s(lds0 + (4 + (b) * 2 + (h)) * HT_B, ((h) ? B1p : Bp) + (kt) * BK, off0, off1)
; #define LDA8(b, h) _Pragma("unroll") for (int m = 0; m < 4; ++m) _Pragma("unroll") for (int k = 0; k < 2; ++k) \
;     At[m][k] = *(const bf16x8*)(SA_(shm, b, h) + abase + (m * 2 + k) * 1024)
; #define LDB8(dst, b, h) _Pragma("unroll") for (int n = 0; n < 2; ++n) _Pragma("unroll") for (int k = 0; k < 2; ++k) \
;     dst[n][k] = *(const bf16x8*)(SB_(shm, b, h) + bbase + (n * 2 + k) * 1024)
; #define MMA8(ai, bj, Bx) do { __builtin_amdgcn_s_setprio(1); \
;     _Pragma("unroll") for (int m = 0; m < 4; ++m) _Pragma("unroll") for (int n = 0; n < 2; ++n) _Pragma("unroll") for (int k = 0; k < 2; ++k) \
;       acc[ai][bj][m][n] = __builtin_amdgcn_mfma_f32_16x16x32_bf16(At[m][k], Bx[n][k], acc[ai][bj][m][n], 0, 0, 0); \
;     __builtin_amdgcn_s_setprio(0); } while (0)
; template <bool HS>
; __device__ __forceinline__ void gemm_tile8(const u16* __restrict__ Ap, const u16* __restrict__ Bp, int K,
;                                            f32x4 (&acc)[2][2][4][2], char* shm, const int tid, const float* hsr = nullptr) {
;     ...
;     WAIT_L(8); BAR; WAIT_L(0); MMA8(0, 0, B0); BAR; SCHED;
;     LDB8(B1, 0, 1); STG_B(0, 0, t + 2);
;     BAR; WAIT_L(0); MMA8(0, 1, B1); BAR;
;     LDA8(0, 1); STG_A(0, 0, t + 2);
;     BAR; WAIT_L(0); MMA8(1, 0, B0); BAR; SCHED;
;     STG_B(0, 1, t + 2);
;     WAIT_V(6); BAR; MMA8(1, 1, B1); BAR;
;     LDB8(B0, 1, 0); SCHED; LDA8(1, 0); STG_A(0, 1, t + 2);
;     WAIT_L(8); BAR; WAIT_L(0); MMA8(0, 0, B0); BAR; SCHED;
;     LDB8(B1, 1, 1); STG_B(1, 0, t + 3);
;     BAR; WAIT_L(0); MMA8(0, 1, B1); BAR;
	s_setprio 1
	v_mfma_f32_16x16x32_bf16 v[126:129], v[162:165], v[138:141], v[126:129]
	v_mfma_f32_16x16x32_bf16 v[122:125], v[162:165], v[154:157], v[122:125]
	v_mfma_f32_16x16x32_bf16 v[114:117], v[170:173], v[154:157], v[114:117]
	v_mfma_f32_16x16x32_bf16 v[118:121], v[170:173], v[138:141], v[118:121]
	v_mfma_f32_16x16x32_bf16 v[110:113], v[180:183], v[138:141], v[110:113]
	v_mfma_f32_16x16x32_bf16 v[106:109], v[180:183], v[154:157], v[106:109]
	v_mfma_f32_16x16x32_bf16 v[98:101], v[188:191], v[154:157], v[98:101]
	v_mfma_f32_16x16x32_bf16 v[102:105], v[188:191], v[138:141], v[102:105]
	v_mfma_f32_16x16x32_bf16 v[126:129], v[166:169], v[142:145], v[126:129]
	v_mfma_f32_16x16x32_bf16 v[122:125], v[166:169], v[158:161], v[122:125]
	v_mfma_f32_16x16x32_bf16 v[114:117], v[174:177], v[158:161], v[114:117]
	v_mfma_f32_16x16x32_bf16 v[118:121], v[174:177], v[142:145], v[118:121]
	v_mfma_f32_16x16x32_bf16 v[110:113], v[184:187], v[142:145], v[110:113]
	v_mfma_f32_16x16x32_bf16 v[106:109], v[184:187], v[158:161], v[106:109]
	v_mfma_f32_16x16x32_bf16 v[98:101], v[192:195], v[158:161], v[98:101]
	v_mfma_f32_16x16x32_bf16 v[102:105], v[192:195], v[142:145], v[102:105]
	v_mfma_f32_16x16x32_bf16 v[94:97], v[162:165], v[196:199], v[94:97]
	v_mfma_f32_16x16x32_bf16 v[90:93], v[162:165], v[204:207], v[90:93]
	v_mfma_f32_16x16x32_bf16 v[82:85], v[170:173], v[204:207], v[82:85]
	v_mfma_f32_16x16x32_bf16 v[86:89], v[170:173], v[196:199], v[86:89]
	v_mfma_f32_16x16x32_bf16 v[78:81], v[180:183], v[196:199], v[78:81]
	v_mfma_f32_16x16x32_bf16 v[74:77], v[180:183], v[204:207], v[74:77]
	v_mfma_f32_16x16x32_bf16 v[66:69], v[188:191], v[204:207], v[66:69]
	v_mfma_f32_16x16x32_bf16 v[70:73], v[188:191], v[196:199], v[70:73]
	v_mfma_f32_16x16x32_bf16 v[94:97], v[166:169], v[200:203], v[94:97]
	v_mfma_f32_16x16x32_bf16 v[90:93], v[166:169], v[208:211], v[90:93]
	v_mfma_f32_16x16x32_bf16 v[82:85], v[174:177], v[208:211], v[82:85]
	v_mfma_f32_16x16x32_bf16 v[86:89], v[174:177], v[200:203], v[86:89]
	v_mfma_f32_16x16x32_bf16 v[78:81], v[184:187], v[200:203], v[78:81]
	v_mfma_f32_16x16x32_bf16 v[74:77], v[184:187], v[208:211], v[74:77]
	v_mfma_f32_16x16x32_bf16 v[66:69], v[192:195], v[208:211], v[66:69]
	v_mfma_f32_16x16x32_bf16 v[70:73], v[192:195], v[200:203], v[70:73]
	s_setprio 0
	s_barrier
	ds_read_b128 v[162:165], v134 offset:16384
	ds_read_b128 v[166:169], v134 offset:17408
	ds_read_b128 v[170:173], v134 offset:18432
	ds_read_b128 v[174:177], v134 offset:19456
	ds_read_b128 v[180:183], v134 offset:20480
	ds_read_b128 v[184:187], v134 offset:21504
	ds_read_b128 v[188:191], v134 offset:22528
	ds_read_b128 v[192:195], v134 offset:23552
	s_add_u32 s22, s24, s2
	s_addc_u32 s23, s25, s3
	s_add_u32 s22, s22, 0x100
	s_addc_u32 s23, s23, 0
	s_add_i32 s36, s14, 0x10000
	s_mov_b32 m0, s36
	s_nop 0
	global_load_lds_dwordx4 v136, s[22:23]
	s_add_i32 s36, s14, 0x12000
	s_mov_b32 m0, s36
	s_nop 0
	global_load_lds_dwordx4 v135, s[22:23]
	s_add_u32 s22, s9, s2
	s_addc_u32 s23, s12, s3
	s_add_u32 s22, s22, 0x100
	s_addc_u32 s23, s23, 0
	s_mov_b32 m0, s14
	s_nop 0
	global_load_lds_dwordx4 v136, s[22:23]
	s_add_i32 s36, s14, 0x2000
	s_mov_b32 m0, s36
	s_nop 0
	global_load_lds_dwordx4 v135, s[22:23]
	s_add_u32 s22, s26, s2
	s_addc_u32 s23, s27, s3
	s_add_u32 s22, s22, 0x100
	s_addc_u32 s23, s23, 0
	s_add_i32 s36, s14, 0x14000
	s_mov_b32 m0, s36
	s_nop 0
	global_load_lds_dwordx4 v136, s[22:23]
	s_add_i32 s36, s14, 0x16000
	s_mov_b32 m0, s36
	s_nop 0
	global_load_lds_dwordx4 v135, s[22:23]
	s_waitcnt vmcnt(8) lgkmcnt(0)
	s_barrier
	s_setprio 1
	v_mfma_f32_16x16x32_bf16 v[62:65], v[162:165], v[138:141], v[62:65]
	v_mfma_f32_16x16x32_bf16 v[58:61], v[162:165], v[154:157], v[58:61]
	v_mfma_f32_16x16x32_bf16 v[50:53], v[170:173], v[154:157], v[50:53]
	v_mfma_f32_16x16x32_bf16 v[54:57], v[170:173], v[138:141], v[54:57]
	v_mfma_f32_16x16x32_bf16 v[46:49], v[180:183], v[138:141], v[46:49]
	v_mfma_f32_16x16x32_bf16 v[42:45], v[180:183], v[154:157], v[42:45]
	v_mfma_f32_16x16x32_bf16 v[34:37], v[188:191], v[154:157], v[34:37]
	v_mfma_f32_16x16x32_bf16 v[38:41], v[188:191], v[138:141], v[38:41]
	v_mfma_f32_16x16x32_bf16 v[62:65], v[166:169], v[142:145], v[62:65]
	v_mfma_f32_16x16x32_bf16 v[58:61], v[166:169], v[158:161], v[58:61]
	v_mfma_f32_16x16x32_bf16 v[50:53], v[174:177], v[158:161], v[50:53]
	v_mfma_f32_16x16x32_bf16 v[54:57], v[174:177], v[142:145], v[54:57]
	v_mfma_f32_16x16x32_bf16 v[46:49], v[184:187], v[142:145], v[46:49]
	v_mfma_f32_16x16x32_bf16 v[42:45], v[184:187], v[158:161], v[42:45]
	v_mfma_f32_16x16x32_bf16 v[34:37], v[192:195], v[158:161], v[34:37]
	v_mfma_f32_16x16x32_bf16 v[38:41], v[192:195], v[142:145], v[38:41]
	v_mfma_f32_16x16x32_bf16 v[30:33], v[162:165], v[196:199], v[30:33]
	v_mfma_f32_16x16x32_bf16 v[26:29], v[162:165], v[204:207], v[26:29]
	v_mfma_f32_16x16x32_bf16 v[18:21], v[170:173], v[204:207], v[18:21]
	v_mfma_f32_16x16x32_bf16 v[22:25], v[170:173], v[196:199], v[22:25]
	v_mfma_f32_16x16x32_bf16 v[14:17], v[180:183], v[196:199], v[14:17]
	v_mfma_f32_16x16x32_bf16 v[10:13], v[180:183], v[204:207], v[10:13]
	v_mfma_f32_16x16x32_bf16 v[2:5], v[188:191], v[204:207], v[2:5]
	v_mfma_f32_16x16x32_bf16 v[6:9], v[188:191], v[196:199], v[6:9]
	v_mfma_f32_16x16x32_bf16 v[30:33], v[166:169], v[200:203], v[30:33]
	v_mfma_f32_16x16x32_bf16 v[26:29], v[166:169], v[208:211], v[26:29]
	v_mfma_f32_16x16x32_bf16 v[18:21], v[174:177], v[208:211], v[18:21]
	v_mfma_f32_16x16x32_bf16 v[22:25], v[174:177], v[200:203], v[22:25]
	v_mfma_f32_16x16x32_bf16 v[14:17], v[184:187], v[200:203], v[14:17]
	v_mfma_f32_16x16x32_bf16 v[10:13], v[184:187], v[208:211], v[10:13]
	v_mfma_f32_16x16x32_bf16 v[2:5], v[192:195], v[208:211], v[2:5]
	v_mfma_f32_16x16x32_bf16 v[6:9], v[192:195], v[200:203], v[6:9]
	s_setprio 0
	s_barrier
; #define WAIT_V(n) asm volatile("s_waitcnt vmcnt(" #n ")" ::: "memory")
; #define WAIT_L(n) asm volatile("s_waitcnt lgkmcnt(" #n ")" ::: "memory")
; #define BAR __builtin_amdgcn_s_barrier()
; #define SCHED __builtin_amdgcn_sched_barrier(0)
; #define STG_A(b, h, kt) stage_half_s(lds0 + ((b) * 2 + (h)) * HT_B, ((h) ? A1 : Ap) + (kt) * BK, off0, off1)
; #define STG_B(b, h, kt) stage_half_s(lds0 + (4 + (b) * 2 + (h)) * HT_B, ((h) ? B1p : Bp) + (kt) * BK, off0, off1)
; #define STG_A(b, h, kt) stage_half_s(lds0 + ((b) * 2 + (h)) * HT_B, ((h) ? A1 : Ap) + (kt) * BK, off0, off1)
; #define STG_B(b, h, kt) stage_half_s(lds0 + (4 + (b) * 2 + (h)) * HT_B, ((h) ? B1p : Bp) + (kt) * BK, off0, off1)
; #define LDA8(b, h) _Pragma("unroll") for (int m = 0; m < 4; ++m) _Pragma("unroll") for (int k = 0; k < 2; ++k) \
;     At[m][k] = *(const bf16x8*)(SA_(shm, b, h) + abase + (m * 2 + k) * 1024)
; #define LDB8(dst, b, h) _Pragma("unroll") for (int n = 0; n < 2; ++n) _Pragma("unroll") for (int k = 0; k < 2; ++k) \
;     dst[n][k] = *(const bf16x8*)(SB_(shm, b, h) + bbase + (n * 2 + k) * 1024)
; #define MMA8(ai, bj, Bx) do { __builtin_amdgcn_s_setprio(1); \
;     _Pragma("unroll") for (int m = 0; m < 4; ++m) _Pragma("unroll") for (int n = 0; n < 2; ++n) _Pragma("unroll") for (int k = 0; k < 2; ++k) \
;       acc[ai][bj][m][n] = __builtin_amdgcn_mfma_f32_16x16x32_bf16(At[m][k], Bx[n][k], acc[ai][bj][m][n], 0, 0, 0); \
;     __builtin_amdgcn_s_setprio(0); } while (0)
; template <bool HS>
; __device__ __forceinline__ void gemm_tile8(const u16* __restrict__ Ap, const u16* __restrict__ Bp, int K,
;                                            f32x4 (&acc)[2][2][4][2], char* shm, const int tid, const float* hsr = nullptr) {
;     ...
;     LDB8(B0, 1, 0); SCHED; LDA8(1, 0); STG_A(0, 1, t + 2);
;     WAIT_L(8); BAR; WAIT_L(0); MMA8(0, 0, B0); BAR; SCHED;
;     LDB8(B1, 1, 1); STG_B(1, 0, t + 3);
;     BAR; WAIT_L(0); MMA8(0, 1, B1); BAR;
;     LDA8(1, 1); STG_A(1, 0, t + 3);
;     BAR; WAIT_L(0); MMA8(1, 0, B0); BAR; SCHED;
;     STG_B(1, 1, t + 3);
;     WAIT_V(6); BAR; MMA8(1, 1, B1); BAR;
;   }
	v_add_u32_e32 v158, 0x18000, v137
	ds_read_b128 v[138:141], v158
	ds_read_b128 v[142:145], v158 offset:1024
	ds_read_b128 v[154:157], v158 offset:2048
	ds_read_b128 v[158:161], v158 offset:3072
	ds_read_b128 v[162:165], v134 offset:32768
	ds_read_b128 v[166:169], v134 offset:33792
	ds_read_b128 v[170:173], v134 offset:34816
	ds_read_b128 v[174:177], v134 offset:35840
	ds_read_b128 v[180:183], v134 offset:36864
	ds_read_b128 v[184:187], v134 offset:37888
	ds_read_b128 v[188:191], v134 offset:38912
	ds_read_b128 v[192:195], v134 offset:39936
	v_add_u32_e32 v208, 0x1c000, v137
	ds_read_b128 v[196:199], v208
	ds_read_b128 v[200:203], v208 offset:1024
	ds_read_b128 v[204:207], v208 offset:2048
	ds_read_b128 v[208:211], v208 offset:3072
	s_add_u32 s22, s17, s2
	s_addc_u32 s23, s18, s3
	s_add_u32 s22, s22, 0x100
	s_addc_u32 s23, s23, 0
	s_add_i32 s36, s14, 0x4000
	s_mov_b32 m0, s36
	s_nop 0
	global_load_lds_dwordx4 v136, s[22:23]
	s_add_i32 s36, s14, 0x6000
	s_mov_b32 m0, s36
	s_nop 0
	global_load_lds_dwordx4 v135, s[22:23]
	s_waitcnt vmcnt(8) lgkmcnt(0)
	s_barrier
	s_setprio 1
	v_mfma_f32_16x16x32_bf16 v[126:129], v[162:165], v[138:141], v[126:129]
	v_mfma_f32_16x16x32_bf16 v[122:125], v[162:165], v[154:157], v[122:125]
	v_mfma_f32_16x16x32_bf16 v[114:117], v[170:173], v[154:157], v[114:117]
	v_mfma_f32_16x16x32_bf16 v[118:121], v[170:173], v[138:141], v[118:121]
	v_mfma_f32_16x16x32_bf16 v[110:113], v[180:183], v[138:141], v[110:113]
	v_mfma_f32_16x16x32_bf16 v[106:109], v[180:183], v[154:157], v[106:109]
	v_mfma_f32_16x16x32_bf16 v[98:101], v[188:191], v[154:157], v[98:101]
	v_mfma_f32_16x16x32_bf16 v[102:105], v[188:191], v[138:141], v[102:105]
	v_mfma_f32_16x16x32_bf16 v[126:129], v[166:169], v[142:145], v[126:129]
	v_mfma_f32_16x16x32_bf16 v[122:125], v[166:169], v[158:161], v[122:125]
	v_mfma_f32_16x16x32_bf16 v[114:117], v[174:177], v[158:161], v[114:117]
	v_mfma_f32_16x16x32_bf16 v[118:121], v[174:177], v[142:145], v[118:121]
	v_mfma_f32_16x16x32_bf16 v[110:113], v[184:187], v[142:145], v[110:113]
	v_mfma_f32_16x16x32_bf16 v[106:109], v[184:187], v[158:161], v[106:109]
	v_mfma_f32_16x16x32_bf16 v[98:101], v[192:195], v[158:161], v[98:101]
	v_mfma_f32_16x16x32_bf16 v[102:105], v[192:195], v[142:145], v[102:105]
	v_mfma_f32_16x16x32_bf16 v[94:97], v[162:165], v[196:199], v[94:97]
	v_mfma_f32_16x16x32_bf16 v[90:93], v[162:165], v[204:207], v[90:93]
	v_mfma_f32_16x16x32_bf16 v[82:85], v[170:173], v[204:207], v[82:85]
	v_mfma_f32_16x16x32_bf16 v[86:89], v[170:173], v[196:199], v[86:89]
	v_mfma_f32_16x16x32_bf16 v[78:81], v[180:183], v[196:199], v[78:81]
	v_mfma_f32_16x16x32_bf16 v[74:77], v[180:183], v[204:207], v[74:77]
	v_mfma_f32_16x16x32_bf16 v[66:69], v[188:191], v[204:207], v[66:69]
	v_mfma_f32_16x16x32_bf16 v[70:73], v[188:191], v[196:199], v[70:73]
	v_mfma_f32_16x16x32_bf16 v[94:97], v[166:169], v[200:203], v[94:97]
	v_mfma_f32_16x16x32_bf16 v[90:93], v[166:169], v[208:211], v[90:93]
	v_mfma_f32_16x16x32_bf16 v[82:85], v[174:177], v[208:211], v[82:85]
	v_mfma_f32_16x16x32_bf16 v[86:89], v[174:177], v[200:203], v[86:89]
	v_mfma_f32_16x16x32_bf16 v[78:81], v[184:187], v[200:203], v[78:81]
	v_mfma_f32_16x16x32_bf16 v[74:77], v[184:187], v[208:211], v[74:77]
	v_mfma_f32_16x16x32_bf16 v[66:69], v[192:195], v[208:211], v[66:69]
	v_mfma_f32_16x16x32_bf16 v[70:73], v[192:195], v[200:203], v[70:73]
	s_setprio 0
	s_barrier
	ds_read_b128 v[162:165], v134 offset:49152
	ds_read_b128 v[166:169], v134 offset:50176
	ds_read_b128 v[170:173], v134 offset:51200
	ds_read_b128 v[174:177], v134 offset:52224
	ds_read_b128 v[180:183], v134 offset:53248
	ds_read_b128 v[184:187], v134 offset:54272
	ds_read_b128 v[188:191], v134 offset:55296
	ds_read_b128 v[192:195], v134 offset:56320
	s_add_u32 s22, s24, s2
	s_addc_u32 s23, s25, s3
	s_add_u32 s22, s22, 0x180
	s_addc_u32 s23, s23, 0
	s_add_i32 s36, s14, 0x18000
	s_mov_b32 m0, s36
	s_nop 0
	global_load_lds_dwordx4 v136, s[22:23]
	s_add_i32 s36, s14, 0x1a000
	s_mov_b32 m0, s36
	s_nop 0
	global_load_lds_dwordx4 v135, s[22:23]
	s_add_u32 s22, s9, s2
	s_addc_u32 s23, s12, s3
	s_add_u32 s22, s22, 0x180
	s_addc_u32 s23, s23, 0
	s_add_i32 s36, s14, 0x8000
	s_mov_b32 m0, s36
	s_nop 0
	global_load_lds_dwordx4 v136, s[22:23]
	s_add_i32 s36, s14, 0xa000
	s_mov_b32 m0, s36
	s_nop 0
	global_load_lds_dwordx4 v135, s[22:23]
	s_add_u32 s22, s26, s2
	s_addc_u32 s23, s27, s3
	s_add_u32 s22, s22, 0x180
	s_addc_u32 s23, s23, 0
	s_add_i32 s36, s14, 0x1c000
	s_mov_b32 m0, s36
	s_nop 0
	global_load_lds_dwordx4 v136, s[22:23]
	s_add_i32 s36, s14, 0x1e000
	s_mov_b32 m0, s36
	s_nop 0
	global_load_lds_dwordx4 v135, s[22:23]
	s_waitcnt vmcnt(8) lgkmcnt(0)
	s_barrier
	s_setprio 1
	v_mfma_f32_16x16x32_bf16 v[62:65], v[162:165], v[138:141], v[62:65]
	v_mfma_f32_16x16x32_bf16 v[58:61], v[162:165], v[154:157], v[58:61]
	v_mfma_f32_16x16x32_bf16 v[50:53], v[170:173], v[154:157], v[50:53]
	v_mfma_f32_16x16x32_bf16 v[54:57], v[170:173], v[138:141], v[54:57]
	v_mfma_f32_16x16x32_bf16 v[46:49], v[180:183], v[138:141], v[46:49]
	v_mfma_f32_16x16x32_bf16 v[42:45], v[180:183], v[154:157], v[42:45]
	v_mfma_f32_16x16x32_bf16 v[34:37], v[188:191], v[154:157], v[34:37]
	v_mfma_f32_16x16x32_bf16 v[38:41], v[188:191], v[138:141], v[38:41]
	v_mfma_f32_16x16x32_bf16 v[62:65], v[166:169], v[142:145], v[62:65]
	v_mfma_f32_16x16x32_bf16 v[58:61], v[166:169], v[158:161], v[58:61]
	v_mfma_f32_16x16x32_bf16 v[50:53], v[174:177], v[158:161], v[50:53]
	v_mfma_f32_16x16x32_bf16 v[54:57], v[174:177], v[142:145], v[54:57]
	v_mfma_f32_16x16x32_bf16 v[46:49], v[184:187], v[142:145], v[46:49]
	v_mfma_f32_16x16x32_bf16 v[42:45], v[184:187], v[158:161], v[42:45]
	v_mfma_f32_16x16x32_bf16 v[34:37], v[192:195], v[158:161], v[34:37]
	v_mfma_f32_16x16x32_bf16 v[38:41], v[192:195], v[142:145], v[38:41]
	v_mfma_f32_16x16x32_bf16 v[30:33], v[162:165], v[196:199], v[30:33]
	v_mfma_f32_16x16x32_bf16 v[26:29], v[162:165], v[204:207], v[26:29]
	v_mfma_f32_16x16x32_bf16 v[18:21], v[170:173], v[204:207], v[18:21]
	v_mfma_f32_16x16x32_bf16 v[22:25], v[170:173], v[196:199], v[22:25]
	v_mfma_f32_16x16x32_bf16 v[14:17], v[180:183], v[196:199], v[14:17]
	v_mfma_f32_16x16x32_bf16 v[10:13], v[180:183], v[204:207], v[10:13]
	v_mfma_f32_16x16x32_bf16 v[2:5], v[188:191], v[204:207], v[2:5]
	v_mfma_f32_16x16x32_bf16 v[6:9], v[188:191], v[196:199], v[6:9]
	v_mfma_f32_16x16x32_bf16 v[30:33], v[166:169], v[200:203], v[30:33]
	v_mfma_f32_16x16x32_bf16 v[26:29], v[166:169], v[208:211], v[26:29]
	v_mfma_f32_16x16x32_bf16 v[18:21], v[174:177], v[208:211], v[18:21]
	v_mfma_f32_16x16x32_bf16 v[22:25], v[174:177], v[200:203], v[22:25]
	v_mfma_f32_16x16x32_bf16 v[14:17], v[184:187], v[200:203], v[14:17]
	v_mfma_f32_16x16x32_bf16 v[10:13], v[184:187], v[208:211], v[10:13]
	v_mfma_f32_16x16x32_bf16 v[2:5], v[192:195], v[208:211], v[2:5]
	v_mfma_f32_16x16x32_bf16 v[6:9], v[192:195], v[200:203], v[6:9]
	s_setprio 0
	s_barrier
	s_add_i32 s19, s19, 2
	s_add_u32 s2, s2, 0x100
	s_addc_u32 s3, s3, 0
	s_cmp_lt_u32 s19, 12
	s_cbranch_scc1 .Lk_conv_out

; #define WAIT_V(n) asm volatile("s_waitcnt vmcnt(" #n ")" ::: "memory")
; #define WAIT_L(n) asm volatile("s_waitcnt lgkmcnt(" #n ")" ::: "memory")
; #define BAR __builtin_amdgcn_s_barrier()
; #define SCHED __builtin_amdgcn_sched_barrier(0)
; template <bool HS>
; __device__ __forceinline__ void gemm_tile8(const u16* __restrict__ Ap, const u16* __restrict__ Bp, int K,
;                                            f32x4 (&acc)[2][2][4][2], char* shm, const int tid, const float* hsr = nullptr) {
;   const int wid = tid >> 6, lane = tid & 63, wr = wid >> 2, wc = wid & 3, fr = lane & 15, fq = lane >> 4;
;   int r0, c0, r1, c1;
;   stage_rc(tid * 16, r0, c0);
;   stage_rc(tid * 16 + 8192, r1, c1);
;   const unsigned off0 = (unsigned)(r0 * K + c0) * 2u, off1 = (unsigned)(r1 * K + c1) * 2u;
;   const int wvoff = __builtin_amdgcn_readfirstlane(tid >> 6) * 1024;
;   const u16* A1 = Ap + (size_t)128 * K;
;   const u16* B1p = Bp + (size_t)128 * K;
; #pragma unroll
;   for (int a = 0; a < 2; ++a)
; #pragma unroll
;     for (int b = 0; b < 2; ++b)
; #pragma unroll
;       for (int m = 0; m < 4; ++m)
; #pragma unroll
;         for (int n = 0; n < 2; ++n) acc[a][b][m][n] = f32x4{0.f, 0.f, 0.f, 0.f};
;   const int abase = lds_byte(wr * 64 + fr, fq * 8), bbase = lds_byte(wc * 32 + fr, fq * 8);
;   bf16x8 At[4][2], B0[2][2], B1[2][2];
;   const unsigned lds0 = (unsigned)(size_t)(__attribute__((address_space(3))) char*)shm + (unsigned)wvoff;
;     ...
;   const int nt = K / BK;
;   WAIT_V(0);
;   if (wr == 1) BAR;
;   BAR;
;   BAR;
;   for (int t = 0; t < nt - 2; t += 2) {
;     if constexpr (HS) {
;       if (t > 0 && (t & 7) == 0) {
;         const float* rt = hsr + ((t >> 3) - 1) * 256 + wr * 64 + fq * 4;
; #pragma unroll
;         for (int ai = 0; ai < 2; ++ai)
; #pragma unroll
;           for (int m = 0; m < 4; ++m) {
;             const f32x4 q4 = *(const f32x4*)(rt + ai * 128 + m * 16);
; #pragma unroll
;             for (int bj = 0; bj < 2; ++bj)
; #pragma unroll
;               for (int n = 0; n < 2; ++n) acc[ai][bj][m][n] *= q4;
;             SCHED;
;           }
;       }
;     }
;     LDB8(B0, 0, 0); SCHED; LDA8(0, 0); STG_A(1, 1, t + 1);
;     WAIT_L(8); BAR; WAIT_L(0); MMA8(0, 0, B0); BAR; SCHED;
;     LDB8(B1, 0, 1); STG_B(0, 0, t + 2);
;     BAR; WAIT_L(0); MMA8(0, 1, B1); BAR;
.LBB0_317:
	s_or_b64 exec, exec, s[6:7]
	v_mov_b32_e32 v4, s11
	v_bfe_i32 v4, v4, 0, 8
	v_ashrrev_i32_e32 v5, 31, v4
	v_lshlrev_b64 v[4:5], 19, v[4:5]
	v_bfe_i32 v6, v0, 27, 1
	v_lshl_add_u64 v[130:131], s[0:1], 0, v[4:5]
	v_lshlrev_b32_e32 v4, 4, v0
	v_lshrrev_b32_e32 v6, 22, v6
	v_add_u32_e32 v6, v4, v6
	v_and_b32_e32 v6, 0xfffffc00, v6
	v_ashrrev_i32_e32 v5, 31, v0
	v_sub_u32_e32 v6, v4, v6
	v_lshrrev_b32_e32 v5, 26, v5
	v_lshrrev_b32_e32 v7, 4, v6
	v_add_u32_e32 v5, v0, v5
	v_bitop3_b32 v7, v7, v6, 32 bitop3:0x6c
	v_ashrrev_i32_e32 v6, 31, v6
	v_ashrrev_i32_e32 v5, 6, v5
	v_lshrrev_b32_e32 v6, 26, v6
	v_lshlrev_b32_e32 v8, 3, v5
	v_add_u32_e32 v6, v7, v6
	v_and_b32_e32 v8, 0x1ffff0, v8
	v_ashrrev_i32_e32 v6, 6, v6
	v_add_u32_e32 v8, v6, v8
	v_mul_i32_i24_e32 v6, 64, v6
	v_add_u32_e32 v4, 0x2000, v4
	v_sub_u32_e32 v6, v7, v6
	v_ashrrev_i32_e32 v7, 31, v4
	v_lshrrev_b32_e32 v7, 22, v7
	v_add_u32_e32 v7, v4, v7
	v_ashrrev_i32_e32 v7, 10, v7
	v_mul_i32_i24_e32 v9, 0x400, v7
	v_sub_u32_e32 v4, v4, v9
	v_lshrrev_b32_e32 v9, 4, v4
	v_bitop3_b32 v4, v9, v4, 32 bitop3:0x6c
	v_ashrrev_i32_e32 v10, 31, v4
	v_lshrrev_b32_e32 v10, 26, v10
	v_add_u32_e32 v10, v4, v10
	v_lshlrev_b32_e32 v9, 3, v7
	v_lshrrev_b32_e32 v11, 6, v10
	v_and_b32_e32 v10, 0xc0, v10
	s_ashr_i32 s5, s4, 31
	v_and_b32_e32 v9, 0x1ffff0, v9
	v_lshlrev_b32_e32 v7, 5, v7
	v_sub_u32_e32 v4, v4, v10
	s_lshl_b64 s[6:7], s[4:5], 11
	v_lshlrev_b32_e32 v5, 5, v5
	v_add_u32_e32 v9, v11, v9
	v_and_b32_e32 v7, 32, v7
	v_ashrrev_i16_sdwa v4, v178, sext(v4) dst_sel:DWORD dst_unused:UNUSED_PAD src0_sel:DWORD src1_sel:BYTE_0
	s_add_u32 s8, s88, s6
	v_and_b32_e32 v5, 32, v5
	v_ashrrev_i16_sdwa v6, v178, sext(v6) dst_sel:DWORD dst_unused:UNUSED_PAD src0_sel:DWORD src1_sel:BYTE_0
	v_bfe_i32 v4, v4, 0, 16
	v_lshl_or_b32 v7, v9, 10, v7
	s_addc_u32 s9, s89, s7
	v_bfe_i32 v6, v6, 0, 16
	v_lshl_or_b32 v5, v8, 10, v5
	v_and_b32_e32 v8, 15, v0
	v_add_lshl_u32 v139, v7, v4, 1
	s_lshl_b32 s10, s10, 10
	v_lshlrev_b32_e32 v7, 2, v0
	v_add_lshl_u32 v140, v5, v6, 1
	s_mov_b64 s[4:5], 0x40000
	v_and_b32_e32 v4, 48, v0
	v_lshlrev_b32_e32 v5, 6, v8
	v_and_b32_e32 v7, 32, v7
	s_add_i32 s11, s10, 0
	v_lshl_add_u64 v[132:133], v[130:131], 0, s[4:5]
	v_or_b32_e32 v6, v5, v4
	v_bitop3_b32 v4, v5, v7, v4 bitop3:0x36
	v_lshlrev_b32_e32 v2, 12, v2
	s_movk_i32 s4, 0x3000
	s_add_u32 s13, s8, 0x40100
	v_lshlrev_b32_e32 v3, 13, v3
	v_and_or_b32 v141, v2, s4, v4
	s_addc_u32 s14, s9, 0
	v_readlane_b32 s4, v254, 34
	v_bitop3_b32 v3, v6, v3, v7 bitop3:0xde
	s_add_u32 s15, s4, s6
	v_readlane_b32 s4, v254, 35
	v_mov_b32_e32 v2, 0
	s_addc_u32 s16, s4, s7
	s_mov_b32 s17, -2
	s_mov_b64 s[4:5], 0
	v_add_u32_e32 v138, 0, v3
	s_waitcnt lgkmcnt(0)
	v_readfirstlane_b32 s24, v130
	v_readfirstlane_b32 s25, v131
	v_readfirstlane_b32 s22, v132
	v_readfirstlane_b32 s23, v133
	s_barrier
	s_barrier
	v_add_u32_e32 v154, 0x10000, v141
	ds_read_b128 v[142:145], v154
	ds_read_b128 v[146:149], v154 offset:1024
	ds_read_b128 v[150:153], v154 offset:2048
	ds_read_b128 v[154:157], v154 offset:3072
	ds_read_b128 v[158:161], v138
	ds_read_b128 v[162:165], v138 offset:1024
	ds_read_b128 v[166:169], v138 offset:2048
	ds_read_b128 v[170:173], v138 offset:3072
	ds_read_b128 v[174:177], v138 offset:4096
	ds_read_b128 v[180:183], v138 offset:5120
	ds_read_b128 v[184:187], v138 offset:6144
	ds_read_b128 v[188:191], v138 offset:7168
	v_add_u32_e32 v204, 0x14000, v141
	ds_read_b128 v[192:195], v204
	ds_read_b128 v[196:199], v204 offset:1024
	ds_read_b128 v[200:203], v204 offset:2048
	ds_read_b128 v[204:207], v204 offset:3072
	s_add_u32 s20, s15, s4
	s_addc_u32 s21, s16, s5
	s_add_u32 s20, s20, 0x80
	s_addc_u32 s21, s21, 0
	s_add_i32 s18, s11, 0xc000
	s_mov_b32 m0, s18
	s_nop 0
	global_load_lds_dwordx4 v140, s[20:21]
	s_add_i32 s18, s11, 0xe000
	s_mov_b32 m0, s18
	s_nop 0
	global_load_lds_dwordx4 v139, s[20:21]
	s_waitcnt vmcnt(8) lgkmcnt(0)
	s_barrier
	s_setprio 1
	v_mfma_f32_16x16x32_bf16 v[126:129], v[158:161], v[142:145], 0
	v_mfma_f32_16x16x32_bf16 v[122:125], v[158:161], v[150:153], 0
	v_mfma_f32_16x16x32_bf16 v[114:117], v[166:169], v[150:153], 0
	v_mfma_f32_16x16x32_bf16 v[118:121], v[166:169], v[142:145], 0
	v_mfma_f32_16x16x32_bf16 v[110:113], v[174:177], v[142:145], 0
	v_mfma_f32_16x16x32_bf16 v[106:109], v[174:177], v[150:153], 0
	v_mfma_f32_16x16x32_bf16 v[98:101], v[184:187], v[150:153], 0
	v_mfma_f32_16x16x32_bf16 v[102:105], v[184:187], v[142:145], 0
	v_mfma_f32_16x16x32_bf16 v[126:129], v[162:165], v[146:149], v[126:129]
	v_mfma_f32_16x16x32_bf16 v[122:125], v[162:165], v[154:157], v[122:125]
	v_mfma_f32_16x16x32_bf16 v[114:117], v[170:173], v[154:157], v[114:117]
	v_mfma_f32_16x16x32_bf16 v[118:121], v[170:173], v[146:149], v[118:121]
	v_mfma_f32_16x16x32_bf16 v[110:113], v[180:183], v[146:149], v[110:113]
	v_mfma_f32_16x16x32_bf16 v[106:109], v[180:183], v[154:157], v[106:109]
	v_mfma_f32_16x16x32_bf16 v[98:101], v[188:191], v[154:157], v[98:101]
	v_mfma_f32_16x16x32_bf16 v[102:105], v[188:191], v[146:149], v[102:105]
	v_mfma_f32_16x16x32_bf16 v[94:97], v[158:161], v[192:195], 0
	v_mfma_f32_16x16x32_bf16 v[90:93], v[158:161], v[200:203], 0
	v_mfma_f32_16x16x32_bf16 v[82:85], v[166:169], v[200:203], 0
	v_mfma_f32_16x16x32_bf16 v[86:89], v[166:169], v[192:195], 0
	v_mfma_f32_16x16x32_bf16 v[78:81], v[174:177], v[192:195], 0
	v_mfma_f32_16x16x32_bf16 v[74:77], v[174:177], v[200:203], 0
	v_mfma_f32_16x16x32_bf16 v[66:69], v[184:187], v[200:203], 0
	v_mfma_f32_16x16x32_bf16 v[70:73], v[184:187], v[192:195], 0
	v_mfma_f32_16x16x32_bf16 v[94:97], v[162:165], v[196:199], v[94:97]
	v_mfma_f32_16x16x32_bf16 v[90:93], v[162:165], v[204:207], v[90:93]
	v_mfma_f32_16x16x32_bf16 v[82:85], v[170:173], v[204:207], v[82:85]
	v_mfma_f32_16x16x32_bf16 v[86:89], v[170:173], v[196:199], v[86:89]
	v_mfma_f32_16x16x32_bf16 v[78:81], v[180:183], v[196:199], v[78:81]
	v_mfma_f32_16x16x32_bf16 v[74:77], v[180:183], v[204:207], v[74:77]
	v_mfma_f32_16x16x32_bf16 v[66:69], v[188:191], v[204:207], v[66:69]
	v_mfma_f32_16x16x32_bf16 v[70:73], v[188:191], v[196:199], v[70:73]
	s_setprio 0
	s_barrier
; #define WAIT_V(n) asm volatile("s_waitcnt vmcnt(" #n ")" ::: "memory")
; #define WAIT_L(n) asm volatile("s_waitcnt lgkmcnt(" #n ")" ::: "memory")
; #define BAR __builtin_amdgcn_s_barrier()
; #define SCHED __builtin_amdgcn_sched_barrier(0)
; #define STG_A(b, h, kt) stage_half_s(lds0 + ((b) * 2 + (h)) * HT_B, ((h) ? A1 : Ap) + (kt) * BK, off0, off1)
; #define STG_B(b, h, kt) stage_half_s(lds0 + (4 + (b) * 2 + (h)) * HT_B, ((h) ? B1p : Bp) + (kt) * BK, off0, off1)
; #define STG_A(b, h, kt) stage_half_s(lds0 + ((b) * 2 + (h)) * HT_B, ((h) ? A1 : Ap) + (kt) * BK, off0, off1)
; #define STG_B(b, h, kt) stage_half_s(lds0 + (4 + (b) * 2 + (h)) * HT_B, ((h) ? B1p : Bp) + (kt) * BK, off0, off1)
; #define LDA8(b, h) _Pragma("unroll") for (int m = 0; m < 4; ++m) _Pragma("unroll") for (int k = 0; k < 2; ++k) \
;     At[m][k] = *(const bf16x8*)(SA_(shm, b, h) + abase + (m * 2 + k) * 1024)
; #define LDB8(dst, b, h) _Pragma("unroll") for (int n = 0; n < 2; ++n) _Pragma("unroll") for (int k = 0; k < 2; ++k) \
;     dst[n][k] = *(const bf16x8*)(SB_(shm, b, h) + bbase + (n * 2 + k) * 1024)
; #define MMA8(ai, bj, Bx) do { __builtin_amdgcn_s_setprio(1); \
;     _Pragma("unroll") for (int m = 0; m < 4; ++m) _Pragma("unroll") for (int n = 0; n < 2; ++n) _Pragma("unroll") for (int k = 0; k < 2; ++k) \
;       acc[ai][bj][m][n] = __builtin_amdgcn_mfma_f32_16x16x32_bf16(At[m][k], Bx[n][k], acc[ai][bj][m][n], 0, 0, 0); \
;     __builtin_amdgcn_s_setprio(0); } while (0)
; template <bool HS>
; __device__ __forceinline__ void gemm_tile8(const u16* __restrict__ Ap, const u16* __restrict__ Bp, int K,
;                                            f32x4 (&acc)[2][2][4][2], char* shm, const int tid, const float* hsr = nullptr) {
;     ...
;     LDA8(0, 1); STG_A(0, 0, t + 2);
;     BAR; WAIT_L(0); MMA8(1, 0, B0); BAR; SCHED;
;     STG_B(0, 1, t + 2);
;     WAIT_V(6); BAR; MMA8(1, 1, B1); BAR;
;     LDB8(B0, 1, 0); SCHED; LDA8(1, 0); STG_A(0, 1, t + 2);
;     WAIT_L(8); BAR; WAIT_L(0); MMA8(0, 0, B0); BAR; SCHED;
;     LDB8(B1, 1, 1); STG_B(1, 0, t + 3);
;     BAR; WAIT_L(0); MMA8(0, 1, B1); BAR;
	ds_read_b128 v[158:161], v138 offset:16384
	ds_read_b128 v[162:165], v138 offset:17408
	ds_read_b128 v[166:169], v138 offset:18432
	ds_read_b128 v[170:173], v138 offset:19456
	ds_read_b128 v[174:177], v138 offset:20480
	ds_read_b128 v[180:183], v138 offset:21504
	ds_read_b128 v[184:187], v138 offset:22528
	ds_read_b128 v[188:191], v138 offset:23552
	s_add_u32 s20, s24, s4
	s_addc_u32 s21, s25, s5
	s_add_u32 s20, s20, 0x100
	s_addc_u32 s21, s21, 0
	s_add_i32 s18, s11, 0x10000
	s_mov_b32 m0, s18
	s_nop 0
	global_load_lds_dwordx4 v140, s[20:21]
	s_add_i32 s18, s11, 0x12000
	s_mov_b32 m0, s18
	s_nop 0
	global_load_lds_dwordx4 v139, s[20:21]
	s_add_u32 s20, s8, s4
	s_addc_u32 s21, s9, s5
	s_add_u32 s20, s20, 0x100
	s_addc_u32 s21, s21, 0
	s_mov_b32 m0, s11
	s_nop 0
	global_load_lds_dwordx4 v140, s[20:21]
	s_add_i32 s18, s11, 0x2000
	s_mov_b32 m0, s18
	s_nop 0
	global_load_lds_dwordx4 v139, s[20:21]
	s_add_u32 s20, s22, s4
	s_addc_u32 s21, s23, s5
	s_add_u32 s20, s20, 0x100
	s_addc_u32 s21, s21, 0
	s_add_i32 s18, s11, 0x14000
	s_mov_b32 m0, s18
	s_nop 0
	global_load_lds_dwordx4 v140, s[20:21]
	s_add_i32 s18, s11, 0x16000
	s_mov_b32 m0, s18
	s_nop 0
	global_load_lds_dwordx4 v139, s[20:21]
	s_waitcnt vmcnt(8) lgkmcnt(0)
	s_barrier
	s_setprio 1
	v_mfma_f32_16x16x32_bf16 v[62:65], v[158:161], v[142:145], 0
	v_mfma_f32_16x16x32_bf16 v[58:61], v[158:161], v[150:153], 0
	v_mfma_f32_16x16x32_bf16 v[50:53], v[166:169], v[150:153], 0
	v_mfma_f32_16x16x32_bf16 v[54:57], v[166:169], v[142:145], 0
	v_mfma_f32_16x16x32_bf16 v[46:49], v[174:177], v[142:145], 0
	v_mfma_f32_16x16x32_bf16 v[42:45], v[174:177], v[150:153], 0
	v_mfma_f32_16x16x32_bf16 v[34:37], v[184:187], v[150:153], 0
	v_mfma_f32_16x16x32_bf16 v[38:41], v[184:187], v[142:145], 0
	v_mfma_f32_16x16x32_bf16 v[62:65], v[162:165], v[146:149], v[62:65]
	v_mfma_f32_16x16x32_bf16 v[58:61], v[162:165], v[154:157], v[58:61]
	v_mfma_f32_16x16x32_bf16 v[50:53], v[170:173], v[154:157], v[50:53]
	v_mfma_f32_16x16x32_bf16 v[54:57], v[170:173], v[146:149], v[54:57]
	v_mfma_f32_16x16x32_bf16 v[46:49], v[180:183], v[146:149], v[46:49]
	v_mfma_f32_16x16x32_bf16 v[42:45], v[180:183], v[154:157], v[42:45]
	v_mfma_f32_16x16x32_bf16 v[34:37], v[188:191], v[154:157], v[34:37]
	v_mfma_f32_16x16x32_bf16 v[38:41], v[188:191], v[146:149], v[38:41]
	v_mfma_f32_16x16x32_bf16 v[30:33], v[158:161], v[192:195], 0
	v_mfma_f32_16x16x32_bf16 v[26:29], v[158:161], v[200:203], 0
	v_mfma_f32_16x16x32_bf16 v[18:21], v[166:169], v[200:203], 0
	v_mfma_f32_16x16x32_bf16 v[22:25], v[166:169], v[192:195], 0
	v_mfma_f32_16x16x32_bf16 v[14:17], v[174:177], v[192:195], 0
	v_mfma_f32_16x16x32_bf16 v[10:13], v[174:177], v[200:203], 0
	v_mfma_f32_16x16x32_bf16 v[2:5], v[184:187], v[200:203], 0
	v_mfma_f32_16x16x32_bf16 v[6:9], v[184:187], v[192:195], 0
	v_mfma_f32_16x16x32_bf16 v[30:33], v[162:165], v[196:199], v[30:33]
	v_mfma_f32_16x16x32_bf16 v[26:29], v[162:165], v[204:207], v[26:29]
	v_mfma_f32_16x16x32_bf16 v[18:21], v[170:173], v[204:207], v[18:21]
	v_mfma_f32_16x16x32_bf16 v[22:25], v[170:173], v[196:199], v[22:25]
	v_mfma_f32_16x16x32_bf16 v[14:17], v[180:183], v[196:199], v[14:17]
	v_mfma_f32_16x16x32_bf16 v[10:13], v[180:183], v[204:207], v[10:13]
	v_mfma_f32_16x16x32_bf16 v[2:5], v[188:191], v[204:207], v[2:5]
	v_mfma_f32_16x16x32_bf16 v[6:9], v[188:191], v[196:199], v[6:9]
	s_setprio 0
	s_barrier
	v_add_u32_e32 v154, 0x18000, v141
	ds_read_b128 v[142:145], v154
	ds_read_b128 v[146:149], v154 offset:1024
	ds_read_b128 v[150:153], v154 offset:2048
	ds_read_b128 v[154:157], v154 offset:3072
	ds_read_b128 v[158:161], v138 offset:32768
	ds_read_b128 v[162:165], v138 offset:33792
	ds_read_b128 v[166:169], v138 offset:34816
	ds_read_b128 v[170:173], v138 offset:35840
	ds_read_b128 v[174:177], v138 offset:36864
	ds_read_b128 v[180:183], v138 offset:37888
	ds_read_b128 v[184:187], v138 offset:38912
	ds_read_b128 v[188:191], v138 offset:39936
	v_add_u32_e32 v204, 0x1c000, v141
	ds_read_b128 v[192:195], v204
	ds_read_b128 v[196:199], v204 offset:1024
	ds_read_b128 v[200:203], v204 offset:2048
	ds_read_b128 v[204:207], v204 offset:3072
	s_add_u32 s20, s15, s4
	s_addc_u32 s21, s16, s5
	s_add_u32 s20, s20, 0x100
	s_addc_u32 s21, s21, 0
	s_add_i32 s18, s11, 0x4000
	s_mov_b32 m0, s18
	s_nop 0
	global_load_lds_dwordx4 v140, s[20:21]
	s_add_i32 s18, s11, 0x6000
	s_mov_b32 m0, s18
	s_nop 0
	global_load_lds_dwordx4 v139, s[20:21]
	s_waitcnt vmcnt(8) lgkmcnt(0)
	s_barrier
	s_setprio 1
	v_mfma_f32_16x16x32_bf16 v[126:129], v[158:161], v[142:145], v[126:129]
	v_mfma_f32_16x16x32_bf16 v[122:125], v[158:161], v[150:153], v[122:125]
	v_mfma_f32_16x16x32_bf16 v[114:117], v[166:169], v[150:153], v[114:117]
	v_mfma_f32_16x16x32_bf16 v[118:121], v[166:169], v[142:145], v[118:121]
	v_mfma_f32_16x16x32_bf16 v[110:113], v[174:177], v[142:145], v[110:113]
	v_mfma_f32_16x16x32_bf16 v[106:109], v[174:177], v[150:153], v[106:109]
	v_mfma_f32_16x16x32_bf16 v[98:101], v[184:187], v[150:153], v[98:101]
	v_mfma_f32_16x16x32_bf16 v[102:105], v[184:187], v[142:145], v[102:105]
	v_mfma_f32_16x16x32_bf16 v[126:129], v[162:165], v[146:149], v[126:129]
	v_mfma_f32_16x16x32_bf16 v[122:125], v[162:165], v[154:157], v[122:125]
	v_mfma_f32_16x16x32_bf16 v[114:117], v[170:173], v[154:157], v[114:117]
	v_mfma_f32_16x16x32_bf16 v[118:121], v[170:173], v[146:149], v[118:121]
	v_mfma_f32_16x16x32_bf16 v[110:113], v[180:183], v[146:149], v[110:113]
	v_mfma_f32_16x16x32_bf16 v[106:109], v[180:183], v[154:157], v[106:109]
	v_mfma_f32_16x16x32_bf16 v[98:101], v[188:191], v[154:157], v[98:101]
	v_mfma_f32_16x16x32_bf16 v[102:105], v[188:191], v[146:149], v[102:105]
	v_mfma_f32_16x16x32_bf16 v[94:97], v[158:161], v[192:195], v[94:97]
	v_mfma_f32_16x16x32_bf16 v[90:93], v[158:161], v[200:203], v[90:93]
	v_mfma_f32_16x16x32_bf16 v[82:85], v[166:169], v[200:203], v[82:85]
	v_mfma_f32_16x16x32_bf16 v[86:89], v[166:169], v[192:195], v[86:89]
	v_mfma_f32_16x16x32_bf16 v[78:81], v[174:177], v[192:195], v[78:81]
	v_mfma_f32_16x16x32_bf16 v[74:77], v[174:177], v[200:203], v[74:77]
	v_mfma_f32_16x16x32_bf16 v[66:69], v[184:187], v[200:203], v[66:69]
	v_mfma_f32_16x16x32_bf16 v[70:73], v[184:187], v[192:195], v[70:73]
	v_mfma_f32_16x16x32_bf16 v[94:97], v[162:165], v[196:199], v[94:97]
	v_mfma_f32_16x16x32_bf16 v[90:93], v[162:165], v[204:207], v[90:93]
	v_mfma_f32_16x16x32_bf16 v[82:85], v[170:173], v[204:207], v[82:85]
	v_mfma_f32_16x16x32_bf16 v[86:89], v[170:173], v[196:199], v[86:89]
	v_mfma_f32_16x16x32_bf16 v[78:81], v[180:183], v[196:199], v[78:81]
	v_mfma_f32_16x16x32_bf16 v[74:77], v[180:183], v[204:207], v[74:77]
	v_mfma_f32_16x16x32_bf16 v[66:69], v[188:191], v[204:207], v[66:69]
	v_mfma_f32_16x16x32_bf16 v[70:73], v[188:191], v[196:199], v[70:73]
	s_setprio 0
	s_barrier
; #define WAIT_V(n) asm volatile("s_waitcnt vmcnt(" #n ")" ::: "memory")
; #define WAIT_L(n) asm volatile("s_waitcnt lgkmcnt(" #n ")" ::: "memory")
; #define BAR __builtin_amdgcn_s_barrier()
; #define SCHED __builtin_amdgcn_sched_barrier(0)
; #define STG_A(b, h, kt) stage_half_s(lds0 + ((b) * 2 + (h)) * HT_B, ((h) ? A1 : Ap) + (kt) * BK, off0, off1)
; #define STG_B(b, h, kt) stage_half_s(lds0 + (4 + (b) * 2 + (h)) * HT_B, ((h) ? B1p : Bp) + (kt) * BK, off0, off1)
; #define STG_A(b, h, kt) stage_half_s(lds0 + ((b) * 2 + (h)) * HT_B, ((h) ? A1 : Ap) + (kt) * BK, off0, off1)
; #define STG_B(b, h, kt) stage_half_s(lds0 + (4 + (b) * 2 + (h)) * HT_B, ((h) ? B1p : Bp) + (kt) * BK, off0, off1)
; #define LDA8(b, h) _Pragma("unroll") for (int m = 0; m < 4; ++m) _Pragma("unroll") for (int k = 0; k < 2; ++k) \
;     At[m][k] = *(const bf16x8*)(SA_(shm, b, h) + abase + (m * 2 + k) * 1024)
; #define LDB8(dst, b, h) _Pragma("unroll") for (int n = 0; n < 2; ++n) _Pragma("unroll") for (int k = 0; k < 2; ++k) \
;     dst[n][k] = *(const bf16x8*)(SB_(shm, b, h) + bbase + (n * 2 + k) * 1024)
; #define MMA8(ai, bj, Bx) do { __builtin_amdgcn_s_setprio(1); \
;     _Pragma("unroll") for (int m = 0; m < 4; ++m) _Pragma("unroll") for (int n = 0; n < 2; ++n) _Pragma("unroll") for (int k = 0; k < 2; ++k) \
;       acc[ai][bj][m][n] = __builtin_amdgcn_mfma_f32_16x16x32_bf16(At[m][k], Bx[n][k], acc[ai][bj][m][n], 0, 0, 0); \
;     __builtin_amdgcn_s_setprio(0); } while (0)
; template <bool HS>
; __device__ __forceinline__ void gemm_tile8(const u16* __restrict__ Ap, const u16* __restrict__ Bp, int K,
;                                            f32x4 (&acc)[2][2][4][2], char* shm, const int tid, const float* hsr = nullptr) {
;     ...
;     LDB8(B0, 0, 0); SCHED; LDA8(0, 0); STG_A(1, 1, t + 1);
;     WAIT_L(8); BAR; WAIT_L(0); MMA8(0, 0, B0); BAR; SCHED;
;     LDB8(B1, 0, 1); STG_B(0, 0, t + 2);
;     ...
;     LDA8(1, 1); STG_A(1, 0, t + 3);
;     BAR; WAIT_L(0); MMA8(1, 0, B0); BAR; SCHED;
;     STG_B(1, 1, t + 3);
;     WAIT_V(6); BAR; MMA8(1, 1, B1); BAR;
;   }
	ds_read_b128 v[158:161], v138 offset:49152
	ds_read_b128 v[162:165], v138 offset:50176
	ds_read_b128 v[166:169], v138 offset:51200
	ds_read_b128 v[170:173], v138 offset:52224
	ds_read_b128 v[174:177], v138 offset:53248
	ds_read_b128 v[180:183], v138 offset:54272
	ds_read_b128 v[184:187], v138 offset:55296
	ds_read_b128 v[188:191], v138 offset:56320
	s_add_u32 s20, s24, s4
	s_addc_u32 s21, s25, s5
	s_add_u32 s20, s20, 0x180
	s_addc_u32 s21, s21, 0
	s_add_i32 s18, s11, 0x18000
	s_mov_b32 m0, s18
	s_nop 0
	global_load_lds_dwordx4 v140, s[20:21]
	s_add_i32 s18, s11, 0x1a000
	s_mov_b32 m0, s18
	s_nop 0
	global_load_lds_dwordx4 v139, s[20:21]
	s_add_u32 s20, s8, s4
	s_addc_u32 s21, s9, s5
	s_add_u32 s20, s20, 0x180
	s_addc_u32 s21, s21, 0
	s_add_i32 s18, s11, 0x8000
	s_mov_b32 m0, s18
	s_nop 0
	global_load_lds_dwordx4 v140, s[20:21]
	s_add_i32 s18, s11, 0xa000
	s_mov_b32 m0, s18
	s_nop 0
	global_load_lds_dwordx4 v139, s[20:21]
	s_add_u32 s20, s22, s4
	s_addc_u32 s21, s23, s5
	s_add_u32 s20, s20, 0x180
	s_addc_u32 s21, s21, 0
	s_add_i32 s18, s11, 0x1c000
	s_mov_b32 m0, s18
	s_nop 0
	global_load_lds_dwordx4 v140, s[20:21]
	s_add_i32 s18, s11, 0x1e000
	s_mov_b32 m0, s18
	s_nop 0
	global_load_lds_dwordx4 v139, s[20:21]
	s_waitcnt vmcnt(8) lgkmcnt(0)
	s_barrier
	s_setprio 1
	v_mfma_f32_16x16x32_bf16 v[62:65], v[158:161], v[142:145], v[62:65]
	v_mfma_f32_16x16x32_bf16 v[58:61], v[158:161], v[150:153], v[58:61]
	v_mfma_f32_16x16x32_bf16 v[50:53], v[166:169], v[150:153], v[50:53]
	v_mfma_f32_16x16x32_bf16 v[54:57], v[166:169], v[142:145], v[54:57]
	v_mfma_f32_16x16x32_bf16 v[46:49], v[174:177], v[142:145], v[46:49]
	v_mfma_f32_16x16x32_bf16 v[42:45], v[174:177], v[150:153], v[42:45]
	v_mfma_f32_16x16x32_bf16 v[34:37], v[184:187], v[150:153], v[34:37]
	v_mfma_f32_16x16x32_bf16 v[38:41], v[184:187], v[142:145], v[38:41]
	v_mfma_f32_16x16x32_bf16 v[62:65], v[162:165], v[146:149], v[62:65]
	v_mfma_f32_16x16x32_bf16 v[58:61], v[162:165], v[154:157], v[58:61]
	v_mfma_f32_16x16x32_bf16 v[50:53], v[170:173], v[154:157], v[50:53]
	v_mfma_f32_16x16x32_bf16 v[54:57], v[170:173], v[146:149], v[54:57]
	v_mfma_f32_16x16x32_bf16 v[46:49], v[180:183], v[146:149], v[46:49]
	v_mfma_f32_16x16x32_bf16 v[42:45], v[180:183], v[154:157], v[42:45]
	v_mfma_f32_16x16x32_bf16 v[34:37], v[188:191], v[154:157], v[34:37]
	v_mfma_f32_16x16x32_bf16 v[38:41], v[188:191], v[146:149], v[38:41]
	v_mfma_f32_16x16x32_bf16 v[30:33], v[158:161], v[192:195], v[30:33]
	v_mfma_f32_16x16x32_bf16 v[26:29], v[158:161], v[200:203], v[26:29]
	v_mfma_f32_16x16x32_bf16 v[18:21], v[166:169], v[200:203], v[18:21]
	v_mfma_f32_16x16x32_bf16 v[22:25], v[166:169], v[192:195], v[22:25]
	v_mfma_f32_16x16x32_bf16 v[14:17], v[174:177], v[192:195], v[14:17]
	v_mfma_f32_16x16x32_bf16 v[10:13], v[174:177], v[200:203], v[10:13]
	v_mfma_f32_16x16x32_bf16 v[2:5], v[184:187], v[200:203], v[2:5]
	v_mfma_f32_16x16x32_bf16 v[6:9], v[184:187], v[192:195], v[6:9]
	v_mfma_f32_16x16x32_bf16 v[30:33], v[162:165], v[196:199], v[30:33]
	v_mfma_f32_16x16x32_bf16 v[26:29], v[162:165], v[204:207], v[26:29]
	v_mfma_f32_16x16x32_bf16 v[18:21], v[170:173], v[204:207], v[18:21]
	v_mfma_f32_16x16x32_bf16 v[22:25], v[170:173], v[196:199], v[22:25]
	v_mfma_f32_16x16x32_bf16 v[14:17], v[180:183], v[196:199], v[14:17]
	v_mfma_f32_16x16x32_bf16 v[10:13], v[180:183], v[204:207], v[10:13]
	v_mfma_f32_16x16x32_bf16 v[2:5], v[188:191], v[204:207], v[2:5]
	v_mfma_f32_16x16x32_bf16 v[6:9], v[188:191], v[196:199], v[6:9]
	s_setprio 0
	s_barrier
	s_add_i32 s17, s17, 2
	s_add_u32 s4, s4, 0x100
	s_addc_u32 s5, s5, 0
	s_cmp_lt_u32 s17, 12
	s_cbranch_scc0 .Lk_conv_in_exit
.Lk_conv_in:
	v_add_u32_e32 v154, 0x10000, v141
	ds_read_b128 v[142:145], v154
	ds_read_b128 v[146:149], v154 offset:1024
	ds_read_b128 v[150:153], v154 offset:2048
	ds_read_b128 v[154:157], v154 offset:3072
	ds_read_b128 v[158:161], v138
	ds_read_b128 v[162:165], v138 offset:1024
	ds_read_b128 v[166:169], v138 offset:2048
	ds_read_b128 v[170:173], v138 offset:3072
	ds_read_b128 v[174:177], v138 offset:4096
	ds_read_b128 v[180:183], v138 offset:5120
	ds_read_b128 v[184:187], v138 offset:6144
	ds_read_b128 v[188:191], v138 offset:7168
	v_add_u32_e32 v204, 0x14000, v141
	ds_read_b128 v[192:195], v204
	ds_read_b128 v[196:199], v204 offset:1024
	ds_read_b128 v[200:203], v204 offset:2048
	ds_read_b128 v[204:207], v204 offset:3072
	s_add_u32 s20, s15, s4
	s_addc_u32 s21, s16, s5
	s_add_u32 s20, s20, 0x80
	s_addc_u32 s21, s21, 0
	s_add_i32 s18, s11, 0xc000
	s_mov_b32 m0, s18
	s_nop 0
	global_load_lds_dwordx4 v140, s[20:21]
	s_add_i32 s18, s11, 0xe000
	s_mov_b32 m0, s18
	s_nop 0
	global_load_lds_dwordx4 v139, s[20:21]
	s_waitcnt vmcnt(8) lgkmcnt(0)
	s_barrier
; #define WAIT_V(n) asm volatile("s_waitcnt vmcnt(" #n ")" ::: "memory")
; #define WAIT_L(n) asm volatile("s_waitcnt lgkmcnt(" #n ")" ::: "memory")
; #define BAR __builtin_amdgcn_s_barrier()
; #define SCHED __builtin_amdgcn_sched_barrier(0)
; #define STG_A(b, h, kt) stage_half_s(lds0 + ((b) * 2 + (h)) * HT_B, ((h) ? A1 : Ap) + (kt) * BK, off0, off1)
; #define STG_B(b, h, kt) stage_half_s(lds0 + (4 + (b) * 2 + (h)) * HT_B, ((h) ? B1p : Bp) + (kt) * BK, off0, off1)
; #define STG_A(b, h, kt) stage_half_s(lds0 + ((b) * 2 + (h)) * HT_B, ((h) ? A1 : Ap) + (kt) * BK, off0, off1)
; #define STG_B(b, h, kt) stage_half_s(lds0 + (4 + (b) * 2 + (h)) * HT_B, ((h) ? B1p : Bp) + (kt) * BK, off0, off1)
; #define LDA8(b, h) _Pragma("unroll") for (int m = 0; m < 4; ++m) _Pragma("unroll") for (int k = 0; k < 2; ++k) \
;     At[m][k] = *(const bf16x8*)(SA_(shm, b, h) + abase + (m * 2 + k) * 1024)
; #define LDB8(dst, b, h) _Pragma("unroll") for (int n = 0; n < 2; ++n) _Pragma("unroll") for (int k = 0; k < 2; ++k) \
;     dst[n][k] = *(const bf16x8*)(SB_(shm, b, h) + bbase + (n * 2 + k) * 1024)
; #define MMA8(ai, bj, Bx) do { __builtin_amdgcn_s_setprio(1); \
;     _Pragma("unroll") for (int m = 0; m < 4; ++m) _Pragma("unroll") for (int n = 0; n < 2; ++n) _Pragma("unroll") for (int k = 0; k < 2; ++k) \
;       acc[ai][bj][m][n] = __builtin_amdgcn_mfma_f32_16x16x32_bf16(At[m][k], Bx[n][k], acc[ai][bj][m][n], 0, 0, 0); \
;     __builtin_amdgcn_s_setprio(0); } while (0)
; template <bool HS>
; __device__ __forceinline__ void gemm_tile8(const u16* __restrict__ Ap, const u16* __restrict__ Bp, int K,
;                                            f32x4 (&acc)[2][2][4][2], char* shm, const int tid, const float* hsr = nullptr) {
;     ...
;     WAIT_L(8); BAR; WAIT_L(0); MMA8(0, 0, B0); BAR; SCHED;
;     LDB8(B1, 0, 1); STG_B(0, 0, t + 2);
;     BAR; WAIT_L(0); MMA8(0, 1, B1); BAR;
;     LDA8(0, 1); STG_A(0, 0, t + 2);
;     BAR; WAIT_L(0); MMA8(1, 0, B0); BAR; SCHED;
;     STG_B(0, 1, t + 2);
;     WAIT_V(6); BAR; MMA8(1, 1, B1); BAR;
;     LDB8(B0, 1, 0); SCHED; LDA8(1, 0); STG_A(0, 1, t + 2);
;     WAIT_L(8); BAR; WAIT_L(0); MMA8(0, 0, B0); BAR; SCHED;
;     LDB8(B1, 1, 1); STG_B(1, 0, t + 3);
;     BAR; WAIT_L(0); MMA8(0, 1, B1); BAR;
	s_setprio 1
	v_mfma_f32_16x16x32_bf16 v[126:129], v[158:161], v[142:145], v[126:129]
	v_mfma_f32_16x16x32_bf16 v[122:125], v[158:161], v[150:153], v[122:125]
	v_mfma_f32_16x16x32_bf16 v[114:117], v[166:169], v[150:153], v[114:117]
	v_mfma_f32_16x16x32_bf16 v[118:121], v[166:169], v[142:145], v[118:121]
	v_mfma_f32_16x16x32_bf16 v[110:113], v[174:177], v[142:145], v[110:113]
	v_mfma_f32_16x16x32_bf16 v[106:109], v[174:177], v[150:153], v[106:109]
	v_mfma_f32_16x16x32_bf16 v[98:101], v[184:187], v[150:153], v[98:101]
	v_mfma_f32_16x16x32_bf16 v[102:105], v[184:187], v[142:145], v[102:105]
	v_mfma_f32_16x16x32_bf16 v[126:129], v[162:165], v[146:149], v[126:129]
	v_mfma_f32_16x16x32_bf16 v[122:125], v[162:165], v[154:157], v[122:125]
	v_mfma_f32_16x16x32_bf16 v[114:117], v[170:173], v[154:157], v[114:117]
	v_mfma_f32_16x16x32_bf16 v[118:121], v[170:173], v[146:149], v[118:121]
	v_mfma_f32_16x16x32_bf16 v[110:113], v[180:183], v[146:149], v[110:113]
	v_mfma_f32_16x16x32_bf16 v[106:109], v[180:183], v[154:157], v[106:109]
	v_mfma_f32_16x16x32_bf16 v[98:101], v[188:191], v[154:157], v[98:101]
	v_mfma_f32_16x16x32_bf16 v[102:105], v[188:191], v[146:149], v[102:105]
	v_mfma_f32_16x16x32_bf16 v[94:97], v[158:161], v[192:195], v[94:97]
	v_mfma_f32_16x16x32_bf16 v[90:93], v[158:161], v[200:203], v[90:93]
	v_mfma_f32_16x16x32_bf16 v[82:85], v[166:169], v[200:203], v[82:85]
	v_mfma_f32_16x16x32_bf16 v[86:89], v[166:169], v[192:195], v[86:89]
	v_mfma_f32_16x16x32_bf16 v[78:81], v[174:177], v[192:195], v[78:81]
	v_mfma_f32_16x16x32_bf16 v[74:77], v[174:177], v[200:203], v[74:77]
	v_mfma_f32_16x16x32_bf16 v[66:69], v[184:187], v[200:203], v[66:69]
	v_mfma_f32_16x16x32_bf16 v[70:73], v[184:187], v[192:195], v[70:73]
	v_mfma_f32_16x16x32_bf16 v[94:97], v[162:165], v[196:199], v[94:97]
	v_mfma_f32_16x16x32_bf16 v[90:93], v[162:165], v[204:207], v[90:93]
	v_mfma_f32_16x16x32_bf16 v[82:85], v[170:173], v[204:207], v[82:85]
	v_mfma_f32_16x16x32_bf16 v[86:89], v[170:173], v[196:199], v[86:89]
	v_mfma_f32_16x16x32_bf16 v[78:81], v[180:183], v[196:199], v[78:81]
	v_mfma_f32_16x16x32_bf16 v[74:77], v[180:183], v[204:207], v[74:77]
	v_mfma_f32_16x16x32_bf16 v[66:69], v[188:191], v[204:207], v[66:69]
	v_mfma_f32_16x16x32_bf16 v[70:73], v[188:191], v[196:199], v[70:73]
	s_setprio 0
	s_barrier
	ds_read_b128 v[158:161], v138 offset:16384
	ds_read_b128 v[162:165], v138 offset:17408
	ds_read_b128 v[166:169], v138 offset:18432
	ds_read_b128 v[170:173], v138 offset:19456
	ds_read_b128 v[174:177], v138 offset:20480
	ds_read_b128 v[180:183], v138 offset:21504
	ds_read_b128 v[184:187], v138 offset:22528
	ds_read_b128 v[188:191], v138 offset:23552
	s_add_u32 s20, s24, s4
	s_addc_u32 s21, s25, s5
	s_add_u32 s20, s20, 0x100
	s_addc_u32 s21, s21, 0
	s_add_i32 s18, s11, 0x10000
	s_mov_b32 m0, s18
	s_nop 0
	global_load_lds_dwordx4 v140, s[20:21]
	s_add_i32 s18, s11, 0x12000
	s_mov_b32 m0, s18
	s_nop 0
	global_load_lds_dwordx4 v139, s[20:21]
	s_add_u32 s20, s8, s4
	s_addc_u32 s21, s9, s5
	s_add_u32 s20, s20, 0x100
	s_addc_u32 s21, s21, 0
	s_mov_b32 m0, s11
	s_nop 0
	global_load_lds_dwordx4 v140, s[20:21]
	s_add_i32 s18, s11, 0x2000
	s_mov_b32 m0, s18
	s_nop 0
	global_load_lds_dwordx4 v139, s[20:21]
	s_add_u32 s20, s22, s4
	s_addc_u32 s21, s23, s5
	s_add_u32 s20, s20, 0x100
	s_addc_u32 s21, s21, 0
	s_add_i32 s18, s11, 0x14000
	s_mov_b32 m0, s18
	s_nop 0
	global_load_lds_dwordx4 v140, s[20:21]
	s_add_i32 s18, s11, 0x16000
	s_mov_b32 m0, s18
	s_nop 0
	global_load_lds_dwordx4 v139, s[20:21]
	s_waitcnt vmcnt(8) lgkmcnt(0)
	s_barrier
	s_setprio 1
	v_mfma_f32_16x16x32_bf16 v[62:65], v[158:161], v[142:145], v[62:65]
	v_mfma_f32_16x16x32_bf16 v[58:61], v[158:161], v[150:153], v[58:61]
	v_mfma_f32_16x16x32_bf16 v[50:53], v[166:169], v[150:153], v[50:53]
	v_mfma_f32_16x16x32_bf16 v[54:57], v[166:169], v[142:145], v[54:57]
	v_mfma_f32_16x16x32_bf16 v[46:49], v[174:177], v[142:145], v[46:49]
	v_mfma_f32_16x16x32_bf16 v[42:45], v[174:177], v[150:153], v[42:45]
	v_mfma_f32_16x16x32_bf16 v[34:37], v[184:187], v[150:153], v[34:37]
	v_mfma_f32_16x16x32_bf16 v[38:41], v[184:187], v[142:145], v[38:41]
	v_mfma_f32_16x16x32_bf16 v[62:65], v[162:165], v[146:149], v[62:65]
	v_mfma_f32_16x16x32_bf16 v[58:61], v[162:165], v[154:157], v[58:61]
	v_mfma_f32_16x16x32_bf16 v[50:53], v[170:173], v[154:157], v[50:53]
	v_mfma_f32_16x16x32_bf16 v[54:57], v[170:173], v[146:149], v[54:57]
	v_mfma_f32_16x16x32_bf16 v[46:49], v[180:183], v[146:149], v[46:49]
	v_mfma_f32_16x16x32_bf16 v[42:45], v[180:183], v[154:157], v[42:45]
	v_mfma_f32_16x16x32_bf16 v[34:37], v[188:191], v[154:157], v[34:37]
	v_mfma_f32_16x16x32_bf16 v[38:41], v[188:191], v[146:149], v[38:41]
	v_mfma_f32_16x16x32_bf16 v[30:33], v[158:161], v[192:195], v[30:33]
	v_mfma_f32_16x16x32_bf16 v[26:29], v[158:161], v[200:203], v[26:29]
	v_mfma_f32_16x16x32_bf16 v[18:21], v[166:169], v[200:203], v[18:21]
	v_mfma_f32_16x16x32_bf16 v[22:25], v[166:169], v[192:195], v[22:25]
	v_mfma_f32_16x16x32_bf16 v[14:17], v[174:177], v[192:195], v[14:17]
	v_mfma_f32_16x16x32_bf16 v[10:13], v[174:177], v[200:203], v[10:13]
	v_mfma_f32_16x16x32_bf16 v[2:5], v[184:187], v[200:203], v[2:5]
	v_mfma_f32_16x16x32_bf16 v[6:9], v[184:187], v[192:195], v[6:9]
	v_mfma_f32_16x16x32_bf16 v[30:33], v[162:165], v[196:199], v[30:33]
	v_mfma_f32_16x16x32_bf16 v[26:29], v[162:165], v[204:207], v[26:29]
	v_mfma_f32_16x16x32_bf16 v[18:21], v[170:173], v[204:207], v[18:21]
	v_mfma_f32_16x16x32_bf16 v[22:25], v[170:173], v[196:199], v[22:25]
	v_mfma_f32_16x16x32_bf16 v[14:17], v[180:183], v[196:199], v[14:17]
	v_mfma_f32_16x16x32_bf16 v[10:13], v[180:183], v[204:207], v[10:13]
	v_mfma_f32_16x16x32_bf16 v[2:5], v[188:191], v[204:207], v[2:5]
	v_mfma_f32_16x16x32_bf16 v[6:9], v[188:191], v[196:199], v[6:9]
	s_setprio 0
	s_barrier
; #define WAIT_V(n) asm volatile("s_waitcnt vmcnt(" #n ")" ::: "memory")
; #define WAIT_L(n) asm volatile("s_waitcnt lgkmcnt(" #n ")" ::: "memory")
; #define BAR __builtin_amdgcn_s_barrier()
; #define SCHED __builtin_amdgcn_sched_barrier(0)
; #define STG_A(b, h, kt) stage_half_s(lds0 + ((b) * 2 + (h)) * HT_B, ((h) ? A1 : Ap) + (kt) * BK, off0, off1)
; #define STG_B(b, h, kt) stage_half_s(lds0 + (4 + (b) * 2 + (h)) * HT_B, ((h) ? B1p : Bp) + (kt) * BK, off0, off1)
; #define STG_A(b, h, kt) stage_half_s(lds0 + ((b) * 2 + (h)) * HT_B, ((h) ? A1 : Ap) + (kt) * BK, off0, off1)
; #define STG_B(b, h, kt) stage_half_s(lds0 + (4 + (b) * 2 + (h)) * HT_B, ((h) ? B1p : Bp) + (kt) * BK, off0, off1)
; #define LDA8(b, h) _Pragma("unroll") for (int m = 0; m < 4; ++m) _Pragma("unroll") for (int k = 0; k < 2; ++k) \
;     At[m][k] = *(const bf16x8*)(SA_(shm, b, h) + abase + (m * 2 + k) * 1024)
; #define LDB8(dst, b, h) _Pragma("unroll") for (int n = 0; n < 2; ++n) _Pragma("unroll") for (int k = 0; k < 2; ++k) \
;     dst[n][k] = *(const bf16x8*)(SB_(shm, b, h) + bbase + (n * 2 + k) * 1024)
; #define MMA8(ai, bj, Bx) do { __builtin_amdgcn_s_setprio(1); \
;     _Pragma("unroll") for (int m = 0; m < 4; ++m) _Pragma("unroll") for (int n = 0; n < 2; ++n) _Pragma("unroll") for (int k = 0; k < 2; ++k) \
;       acc[ai][bj][m][n] = __builtin_amdgcn_mfma_f32_16x16x32_bf16(At[m][k], Bx[n][k], acc[ai][bj][m][n], 0, 0, 0); \
;     __builtin_amdgcn_s_setprio(0); } while (0)
; template <bool HS>
; __device__ __forceinline__ void gemm_tile8(const u16* __restrict__ Ap, const u16* __restrict__ Bp, int K,
;                                            f32x4 (&acc)[2][2][4][2], char* shm, const int tid, const float* hsr = nullptr) {
;     ...
;     LDB8(B0, 1, 0); SCHED; LDA8(1, 0); STG_A(0, 1, t + 2);
;     WAIT_L(8); BAR; WAIT_L(0); MMA8(0, 0, B0); BAR; SCHED;
;     LDB8(B1, 1, 1); STG_B(1, 0, t + 3);
;     BAR; WAIT_L(0); MMA8(0, 1, B1); BAR;
;     LDA8(1, 1); STG_A(1, 0, t + 3);
;     BAR; WAIT_L(0); MMA8(1, 0, B0); BAR; SCHED;
;     STG_B(1, 1, t + 3);
;     WAIT_V(6); BAR; MMA8(1, 1, B1); BAR;
;   }
	v_add_u32_e32 v154, 0x18000, v141
	ds_read_b128 v[142:145], v154
	ds_read_b128 v[146:149], v154 offset:1024
	ds_read_b128 v[150:153], v154 offset:2048
	ds_read_b128 v[154:157], v154 offset:3072
	ds_read_b128 v[158:161], v138 offset:32768
	ds_read_b128 v[162:165], v138 offset:33792
	ds_read_b128 v[166:169], v138 offset:34816
	ds_read_b128 v[170:173], v138 offset:35840
	ds_read_b128 v[174:177], v138 offset:36864
	ds_read_b128 v[180:183], v138 offset:37888
	ds_read_b128 v[184:187], v138 offset:38912
	ds_read_b128 v[188:191], v138 offset:39936
	v_add_u32_e32 v204, 0x1c000, v141
	ds_read_b128 v[192:195], v204
	ds_read_b128 v[196:199], v204 offset:1024
	ds_read_b128 v[200:203], v204 offset:2048
	ds_read_b128 v[204:207], v204 offset:3072
	s_add_u32 s20, s15, s4
	s_addc_u32 s21, s16, s5
	s_add_u32 s20, s20, 0x100
	s_addc_u32 s21, s21, 0
	s_add_i32 s18, s11, 0x4000
	s_mov_b32 m0, s18
	s_nop 0
	global_load_lds_dwordx4 v140, s[20:21]
	s_add_i32 s18, s11, 0x6000
	s_mov_b32 m0, s18
	s_nop 0
	global_load_lds_dwordx4 v139, s[20:21]
	s_waitcnt vmcnt(8) lgkmcnt(0)
	s_barrier
	s_setprio 1
	v_mfma_f32_16x16x32_bf16 v[126:129], v[158:161], v[142:145], v[126:129]
	v_mfma_f32_16x16x32_bf16 v[122:125], v[158:161], v[150:153], v[122:125]
	v_mfma_f32_16x16x32_bf16 v[114:117], v[166:169], v[150:153], v[114:117]
	v_mfma_f32_16x16x32_bf16 v[118:121], v[166:169], v[142:145], v[118:121]
	v_mfma_f32_16x16x32_bf16 v[110:113], v[174:177], v[142:145], v[110:113]
	v_mfma_f32_16x16x32_bf16 v[106:109], v[174:177], v[150:153], v[106:109]
	v_mfma_f32_16x16x32_bf16 v[98:101], v[184:187], v[150:153], v[98:101]
	v_mfma_f32_16x16x32_bf16 v[102:105], v[184:187], v[142:145], v[102:105]
	v_mfma_f32_16x16x32_bf16 v[126:129], v[162:165], v[146:149], v[126:129]
	v_mfma_f32_16x16x32_bf16 v[122:125], v[162:165], v[154:157], v[122:125]
	v_mfma_f32_16x16x32_bf16 v[114:117], v[170:173], v[154:157], v[114:117]
	v_mfma_f32_16x16x32_bf16 v[118:121], v[170:173], v[146:149], v[118:121]
	v_mfma_f32_16x16x32_bf16 v[110:113], v[180:183], v[146:149], v[110:113]
	v_mfma_f32_16x16x32_bf16 v[106:109], v[180:183], v[154:157], v[106:109]
	v_mfma_f32_16x16x32_bf16 v[98:101], v[188:191], v[154:157], v[98:101]
	v_mfma_f32_16x16x32_bf16 v[102:105], v[188:191], v[146:149], v[102:105]
	v_mfma_f32_16x16x32_bf16 v[94:97], v[158:161], v[192:195], v[94:97]
	v_mfma_f32_16x16x32_bf16 v[90:93], v[158:161], v[200:203], v[90:93]
	v_mfma_f32_16x16x32_bf16 v[82:85], v[166:169], v[200:203], v[82:85]
	v_mfma_f32_16x16x32_bf16 v[86:89], v[166:169], v[192:195], v[86:89]
	v_mfma_f32_16x16x32_bf16 v[78:81], v[174:177], v[192:195], v[78:81]
	v_mfma_f32_16x16x32_bf16 v[74:77], v[174:177], v[200:203], v[74:77]
	v_mfma_f32_16x16x32_bf16 v[66:69], v[184:187], v[200:203], v[66:69]
	v_mfma_f32_16x16x32_bf16 v[70:73], v[184:187], v[192:195], v[70:73]
	v_mfma_f32_16x16x32_bf16 v[94:97], v[162:165], v[196:199], v[94:97]
	v_mfma_f32_16x16x32_bf16 v[90:93], v[162:165], v[204:207], v[90:93]
	v_mfma_f32_16x16x32_bf16 v[82:85], v[170:173], v[204:207], v[82:85]
	v_mfma_f32_16x16x32_bf16 v[86:89], v[170:173], v[196:199], v[86:89]
	v_mfma_f32_16x16x32_bf16 v[78:81], v[180:183], v[196:199], v[78:81]
	v_mfma_f32_16x16x32_bf16 v[74:77], v[180:183], v[204:207], v[74:77]
	v_mfma_f32_16x16x32_bf16 v[66:69], v[188:191], v[204:207], v[66:69]
	v_mfma_f32_16x16x32_bf16 v[70:73], v[188:191], v[196:199], v[70:73]
	s_setprio 0
	s_barrier
	ds_read_b128 v[158:161], v138 offset:49152
	ds_read_b128 v[162:165], v138 offset:50176
	ds_read_b128 v[166:169], v138 offset:51200
	ds_read_b128 v[170:173], v138 offset:52224
	ds_read_b128 v[174:177], v138 offset:53248
	ds_read_b128 v[180:183], v138 offset:54272
	ds_read_b128 v[184:187], v138 offset:55296
	ds_read_b128 v[188:191], v138 offset:56320
	s_add_u32 s20, s24, s4
	s_addc_u32 s21, s25, s5
	s_add_u32 s20, s20, 0x180
	s_addc_u32 s21, s21, 0
	s_add_i32 s18, s11, 0x18000
	s_mov_b32 m0, s18
	s_nop 0
	global_load_lds_dwordx4 v140, s[20:21]
	s_add_i32 s18, s11, 0x1a000
	s_mov_b32 m0, s18
	s_nop 0
	global_load_lds_dwordx4 v139, s[20:21]
	s_add_u32 s20, s8, s4
	s_addc_u32 s21, s9, s5
	s_add_u32 s20, s20, 0x180
	s_addc_u32 s21, s21, 0
	s_add_i32 s18, s11, 0x8000
	s_mov_b32 m0, s18
	s_nop 0
	global_load_lds_dwordx4 v140, s[20:21]
	s_add_i32 s18, s11, 0xa000
	s_mov_b32 m0, s18
	s_nop 0
	global_load_lds_dwordx4 v139, s[20:21]
	s_add_u32 s20, s22, s4
	s_addc_u32 s21, s23, s5
	s_add_u32 s20, s20, 0x180
	s_addc_u32 s21, s21, 0
	s_add_i32 s18, s11, 0x1c000
	s_mov_b32 m0, s18
	s_nop 0
	global_load_lds_dwordx4 v140, s[20:21]
	s_add_i32 s18, s11, 0x1e000
	s_mov_b32 m0, s18
	s_nop 0
	global_load_lds_dwordx4 v139, s[20:21]
	s_waitcnt vmcnt(8) lgkmcnt(0)
	s_barrier
	s_setprio 1
	v_mfma_f32_16x16x32_bf16 v[62:65], v[158:161], v[142:145], v[62:65]
	v_mfma_f32_16x16x32_bf16 v[58:61], v[158:161], v[150:153], v[58:61]
	v_mfma_f32_16x16x32_bf16 v[50:53], v[166:169], v[150:153], v[50:53]
	v_mfma_f32_16x16x32_bf16 v[54:57], v[166:169], v[142:145], v[54:57]
	v_mfma_f32_16x16x32_bf16 v[46:49], v[174:177], v[142:145], v[46:49]
	v_mfma_f32_16x16x32_bf16 v[42:45], v[174:177], v[150:153], v[42:45]
	v_mfma_f32_16x16x32_bf16 v[34:37], v[184:187], v[150:153], v[34:37]
	v_mfma_f32_16x16x32_bf16 v[38:41], v[184:187], v[142:145], v[38:41]
	v_mfma_f32_16x16x32_bf16 v[62:65], v[162:165], v[146:149], v[62:65]
	v_mfma_f32_16x16x32_bf16 v[58:61], v[162:165], v[154:157], v[58:61]
	v_mfma_f32_16x16x32_bf16 v[50:53], v[170:173], v[154:157], v[50:53]
	v_mfma_f32_16x16x32_bf16 v[54:57], v[170:173], v[146:149], v[54:57]
	v_mfma_f32_16x16x32_bf16 v[46:49], v[180:183], v[146:149], v[46:49]
	v_mfma_f32_16x16x32_bf16 v[42:45], v[180:183], v[154:157], v[42:45]
	v_mfma_f32_16x16x32_bf16 v[34:37], v[188:191], v[154:157], v[34:37]
	v_mfma_f32_16x16x32_bf16 v[38:41], v[188:191], v[146:149], v[38:41]
	v_mfma_f32_16x16x32_bf16 v[30:33], v[158:161], v[192:195], v[30:33]
	v_mfma_f32_16x16x32_bf16 v[26:29], v[158:161], v[200:203], v[26:29]
	v_mfma_f32_16x16x32_bf16 v[18:21], v[166:169], v[200:203], v[18:21]
	v_mfma_f32_16x16x32_bf16 v[22:25], v[166:169], v[192:195], v[22:25]
	v_mfma_f32_16x16x32_bf16 v[14:17], v[174:177], v[192:195], v[14:17]
	v_mfma_f32_16x16x32_bf16 v[10:13], v[174:177], v[200:203], v[10:13]
	v_mfma_f32_16x16x32_bf16 v[2:5], v[184:187], v[200:203], v[2:5]
	v_mfma_f32_16x16x32_bf16 v[6:9], v[184:187], v[192:195], v[6:9]
	v_mfma_f32_16x16x32_bf16 v[30:33], v[162:165], v[196:199], v[30:33]
	v_mfma_f32_16x16x32_bf16 v[26:29], v[162:165], v[204:207], v[26:29]
	v_mfma_f32_16x16x32_bf16 v[18:21], v[170:173], v[204:207], v[18:21]
	v_mfma_f32_16x16x32_bf16 v[22:25], v[170:173], v[196:199], v[22:25]
	v_mfma_f32_16x16x32_bf16 v[14:17], v[180:183], v[196:199], v[14:17]
	v_mfma_f32_16x16x32_bf16 v[10:13], v[180:183], v[204:207], v[10:13]
	v_mfma_f32_16x16x32_bf16 v[2:5], v[188:191], v[204:207], v[2:5]
	v_mfma_f32_16x16x32_bf16 v[6:9], v[188:191], v[196:199], v[6:9]
	s_setprio 0
	s_barrier
	s_add_i32 s17, s17, 2
	s_add_u32 s4, s4, 0x100
	s_addc_u32 s5, s5, 0
	s_cmp_lt_u32 s17, 12
	s_cbranch_scc1 .Lk_conv_in

; #define WAIT_V(n) asm volatile("s_waitcnt vmcnt(" #n ")" ::: "memory")
; #define WAIT_L(n) asm volatile("s_waitcnt lgkmcnt(" #n ")" ::: "memory")
; #define BAR __builtin_amdgcn_s_barrier()
; #define SCHED __builtin_amdgcn_sched_barrier(0)
; template <bool HS>
; __device__ __forceinline__ void gemm_tile8(const u16* __restrict__ Ap, const u16* __restrict__ Bp, int K,
;                                            f32x4 (&acc)[2][2][4][2], char* shm, const int tid, const float* hsr = nullptr) {
;   const int wid = tid >> 6, lane = tid & 63, wr = wid >> 2, wc = wid & 3, fr = lane & 15, fq = lane >> 4;
;   int r0, c0, r1, c1;
;   stage_rc(tid * 16, r0, c0);
;   stage_rc(tid * 16 + 8192, r1, c1);
;   const unsigned off0 = (unsigned)(r0 * K + c0) * 2u, off1 = (unsigned)(r1 * K + c1) * 2u;
;   const int wvoff = __builtin_amdgcn_readfirstlane(tid >> 6) * 1024;
;   const u16* A1 = Ap + (size_t)128 * K;
;   const u16* B1p = Bp + (size_t)128 * K;
; #pragma unroll
;   for (int a = 0; a < 2; ++a)
; #pragma unroll
;     for (int b = 0; b < 2; ++b)
; #pragma unroll
;       for (int m = 0; m < 4; ++m)
; #pragma unroll
;         for (int n = 0; n < 2; ++n) acc[a][b][m][n] = f32x4{0.f, 0.f, 0.f, 0.f};
;   const int abase = lds_byte(wr * 64 + fr, fq * 8), bbase = lds_byte(wc * 32 + fr, fq * 8);
;   bf16x8 At[4][2], B0[2][2], B1[2][2];
;   const unsigned lds0 = (unsigned)(size_t)(__attribute__((address_space(3))) char*)shm + (unsigned)wvoff;
;     ...
;   const int nt = K / BK;
;   WAIT_V(0);
;   if (wr == 1) BAR;
;   BAR;
;   BAR;
;   for (int t = 0; t < nt - 2; t += 2) {
;     if constexpr (HS) {
;       if (t > 0 && (t & 7) == 0) {
;         const float* rt = hsr + ((t >> 3) - 1) * 256 + wr * 64 + fq * 4;
; #pragma unroll
;         for (int ai = 0; ai < 2; ++ai)
; #pragma unroll
;           for (int m = 0; m < 4; ++m) {
;             const f32x4 q4 = *(const f32x4*)(rt + ai * 128 + m * 16);
; #pragma unroll
;             for (int bj = 0; bj < 2; ++bj)
; #pragma unroll
;               for (int n = 0; n < 2; ++n) acc[ai][bj][m][n] *= q4;
;             SCHED;
;           }
;       }
;     }
;     LDB8(B0, 0, 0); SCHED; LDA8(0, 0); STG_A(1, 1, t + 1);
;     WAIT_L(8); BAR; WAIT_L(0); MMA8(0, 0, B0); BAR; SCHED;
;     LDB8(B1, 0, 1); STG_B(0, 0, t + 2);
;     BAR; WAIT_L(0); MMA8(0, 1, B1); BAR;
.LBB0_582:
	s_or_b64 exec, exec, s[8:9]
	v_bfe_i32 v6, v0, 27, 1
	v_lshlrev_b32_e32 v4, 4, v0
	v_lshrrev_b32_e32 v6, 22, v6
	v_add_u32_e32 v6, v4, v6
	v_and_b32_e32 v6, 0xfffffc00, v6
	v_ashrrev_i32_e32 v5, 31, v0
	v_sub_u32_e32 v6, v4, v6
	v_lshrrev_b32_e32 v5, 26, v5
	v_lshrrev_b32_e32 v7, 4, v6
	v_add_u32_e32 v5, v0, v5
	v_bitop3_b32 v7, v7, v6, 32 bitop3:0x6c
	v_ashrrev_i32_e32 v6, 31, v6
	v_ashrrev_i32_e32 v5, 6, v5
	v_lshrrev_b32_e32 v6, 26, v6
	v_lshlrev_b32_e32 v8, 3, v5
	v_add_u32_e32 v6, v7, v6
	v_and_b32_e32 v8, 0x1ffff0, v8
	v_ashrrev_i32_e32 v6, 6, v6
	v_add_u32_e32 v8, v6, v8
	v_mul_i32_i24_e32 v6, 64, v6
	v_add_u32_e32 v4, 0x2000, v4
	v_sub_u32_e32 v6, v7, v6
	v_ashrrev_i32_e32 v7, 31, v4
	v_lshrrev_b32_e32 v7, 22, v7
	v_add_u32_e32 v7, v4, v7
	v_ashrrev_i32_e32 v7, 10, v7
	v_mul_i32_i24_e32 v9, 0x400, v7
	v_sub_u32_e32 v4, v4, v9
	v_lshrrev_b32_e32 v9, 4, v4
	v_bitop3_b32 v4, v9, v4, 32 bitop3:0x6c
	s_ashr_i32 s7, s6, 31
	v_ashrrev_i32_e32 v10, 31, v4
	s_lshl_b64 s[6:7], s[6:7], 11
	v_readlane_b32 s20, v254, 47
	v_lshrrev_b32_e32 v10, 26, v10
	v_readlane_b32 s21, v254, 48
	s_add_u32 s8, s20, s6
	v_add_u32_e32 v10, v4, v10
	s_addc_u32 s9, s21, s7
	s_ashr_i32 s3, s2, 31
	v_lshlrev_b32_e32 v9, 3, v7
	v_lshrrev_b32_e32 v11, 6, v10
	v_and_b32_e32 v10, 0xc0, v10
	s_lshl_b64 s[6:7], s[2:3], 19
	v_readlane_b32 s3, v255, 7
	v_and_b32_e32 v9, 0x1ffff0, v9
	v_lshlrev_b32_e32 v7, 5, v7
	v_sub_u32_e32 v4, v4, v10
	s_add_u32 s3, s3, s6
	v_readlane_b32 s6, v255, 8
	v_lshlrev_b32_e32 v5, 5, v5
	v_add_u32_e32 v9, v11, v9
	v_and_b32_e32 v7, 32, v7
	v_ashrrev_i16_sdwa v4, v178, sext(v4) dst_sel:DWORD dst_unused:UNUSED_PAD src0_sel:DWORD src1_sel:BYTE_0
	s_addc_u32 s10, s6, s7
	v_and_b32_e32 v5, 32, v5
	v_ashrrev_i16_sdwa v6, v178, sext(v6) dst_sel:DWORD dst_unused:UNUSED_PAD src0_sel:DWORD src1_sel:BYTE_0
	v_bfe_i32 v4, v4, 0, 16
	v_lshl_or_b32 v7, v9, 10, v7
	s_lshl_b32 s11, s11, 10
	v_bfe_i32 v6, v6, 0, 16
	v_lshl_or_b32 v5, v8, 10, v5
	v_and_b32_e32 v8, 15, v0
	v_add_lshl_u32 v131, v7, v4, 1
	s_add_u32 s13, s3, 0x40000
	v_lshlrev_b32_e32 v7, 2, v0
	v_add_lshl_u32 v132, v5, v6, 1
	s_addc_u32 s14, s10, 0
	v_and_b32_e32 v4, 48, v0
	v_lshlrev_b32_e32 v5, 6, v8
	v_and_b32_e32 v7, 32, v7
	s_add_i32 s15, s11, 0
	v_or_b32_e32 v6, v5, v4
	v_bitop3_b32 v4, v5, v7, v4 bitop3:0x36
	v_lshlrev_b32_e32 v2, 12, v2
	s_movk_i32 s6, 0x3000
	s_add_u32 s16, s8, 0x40100
	v_and_or_b32 v133, v2, s6, v4
	s_addc_u32 s17, s9, 0
	s_add_i32 s6, s18, s19
	s_ashr_i32 s7, s6, 31
	v_lshlrev_b32_e32 v3, 13, v3
	s_lshl_b64 s[6:7], s[6:7], 11
	v_readlane_b32 s18, v254, 34
	v_bitop3_b32 v3, v6, v3, v7 bitop3:0xde
	s_add_u32 s18, s18, s6
	v_readlane_b32 s6, v254, 35
	v_mov_b32_e32 v2, 0
	s_addc_u32 s19, s6, s7
	s_mov_b32 s20, -2
	s_mov_b64 s[6:7], 0
	v_add_u32_e32 v130, 0, v3
	s_waitcnt lgkmcnt(0)
	v_readlane_b32 s22, v254, 49
	v_readlane_b32 s23, v254, 50
	s_barrier
	s_barrier
	v_add_u32_e32 v154, 0x10000, v133
	ds_read_b128 v[142:145], v154
	ds_read_b128 v[146:149], v154 offset:1024
	ds_read_b128 v[150:153], v154 offset:2048
	ds_read_b128 v[154:157], v154 offset:3072
	ds_read_b128 v[158:161], v130
	ds_read_b128 v[164:167], v130 offset:1024
	ds_read_b128 v[168:171], v130 offset:2048
	ds_read_b128 v[172:175], v130 offset:3072
	ds_read_b128 v[180:183], v130 offset:4096
	ds_read_b128 v[184:187], v130 offset:5120
	ds_read_b128 v[188:191], v130 offset:6144
	ds_read_b128 v[192:195], v130 offset:7168
	v_add_u32_e32 v208, 0x14000, v133
	ds_read_b128 v[196:199], v208
	ds_read_b128 v[200:203], v208 offset:1024
	ds_read_b128 v[204:207], v208 offset:2048
	ds_read_b128 v[208:211], v208 offset:3072
	s_add_u32 s24, s18, s6
	s_addc_u32 s25, s19, s7
	s_add_u32 s24, s24, 0x80
	s_addc_u32 s25, s25, 0
	s_add_i32 s23, s15, 0xc000
	s_mov_b32 m0, s23
	s_nop 0
	global_load_lds_dwordx4 v132, s[24:25]
	s_add_i32 s23, s15, 0xe000
	s_mov_b32 m0, s23
	s_nop 0
	global_load_lds_dwordx4 v131, s[24:25]
	s_waitcnt vmcnt(8) lgkmcnt(0)
	s_barrier
	s_setprio 1
	v_mfma_f32_16x16x32_bf16 v[126:129], v[158:161], v[142:145], 0
	v_mfma_f32_16x16x32_bf16 v[122:125], v[158:161], v[150:153], 0
	v_mfma_f32_16x16x32_bf16 v[114:117], v[168:171], v[150:153], 0
	v_mfma_f32_16x16x32_bf16 v[118:121], v[168:171], v[142:145], 0
	v_mfma_f32_16x16x32_bf16 v[110:113], v[180:183], v[142:145], 0
	v_mfma_f32_16x16x32_bf16 v[106:109], v[180:183], v[150:153], 0
	v_mfma_f32_16x16x32_bf16 v[98:101], v[188:191], v[150:153], 0
	v_mfma_f32_16x16x32_bf16 v[102:105], v[188:191], v[142:145], 0
	v_mfma_f32_16x16x32_bf16 v[126:129], v[164:167], v[146:149], v[126:129]
	v_mfma_f32_16x16x32_bf16 v[122:125], v[164:167], v[154:157], v[122:125]
	v_mfma_f32_16x16x32_bf16 v[114:117], v[172:175], v[154:157], v[114:117]
	v_mfma_f32_16x16x32_bf16 v[118:121], v[172:175], v[146:149], v[118:121]
	v_mfma_f32_16x16x32_bf16 v[110:113], v[184:187], v[146:149], v[110:113]
	v_mfma_f32_16x16x32_bf16 v[106:109], v[184:187], v[154:157], v[106:109]
	v_mfma_f32_16x16x32_bf16 v[98:101], v[192:195], v[154:157], v[98:101]
	v_mfma_f32_16x16x32_bf16 v[102:105], v[192:195], v[146:149], v[102:105]
	v_mfma_f32_16x16x32_bf16 v[94:97], v[158:161], v[196:199], 0
	v_mfma_f32_16x16x32_bf16 v[90:93], v[158:161], v[204:207], 0
	v_mfma_f32_16x16x32_bf16 v[82:85], v[168:171], v[204:207], 0
	v_mfma_f32_16x16x32_bf16 v[86:89], v[168:171], v[196:199], 0
	v_mfma_f32_16x16x32_bf16 v[78:81], v[180:183], v[196:199], 0
	v_mfma_f32_16x16x32_bf16 v[74:77], v[180:183], v[204:207], 0
	v_mfma_f32_16x16x32_bf16 v[66:69], v[188:191], v[204:207], 0
	v_mfma_f32_16x16x32_bf16 v[70:73], v[188:191], v[196:199], 0
	v_mfma_f32_16x16x32_bf16 v[94:97], v[164:167], v[200:203], v[94:97]
	v_mfma_f32_16x16x32_bf16 v[90:93], v[164:167], v[208:211], v[90:93]
	v_mfma_f32_16x16x32_bf16 v[82:85], v[172:175], v[208:211], v[82:85]
	v_mfma_f32_16x16x32_bf16 v[86:89], v[172:175], v[200:203], v[86:89]
	v_mfma_f32_16x16x32_bf16 v[78:81], v[184:187], v[200:203], v[78:81]
	v_mfma_f32_16x16x32_bf16 v[74:77], v[184:187], v[208:211], v[74:77]
	v_mfma_f32_16x16x32_bf16 v[66:69], v[192:195], v[208:211], v[66:69]
	v_mfma_f32_16x16x32_bf16 v[70:73], v[192:195], v[200:203], v[70:73]
	s_setprio 0
	s_barrier
; #define WAIT_V(n) asm volatile("s_waitcnt vmcnt(" #n ")" ::: "memory")
; #define WAIT_L(n) asm volatile("s_waitcnt lgkmcnt(" #n ")" ::: "memory")
; #define BAR __builtin_amdgcn_s_barrier()
; #define SCHED __builtin_amdgcn_sched_barrier(0)
; #define STG_A(b, h, kt) stage_half_s(lds0 + ((b) * 2 + (h)) * HT_B, ((h) ? A1 : Ap) + (kt) * BK, off0, off1)
; #define STG_B(b, h, kt) stage_half_s(lds0 + (4 + (b) * 2 + (h)) * HT_B, ((h) ? B1p : Bp) + (kt) * BK, off0, off1)
; #define STG_A(b, h, kt) stage_half_s(lds0 + ((b) * 2 + (h)) * HT_B, ((h) ? A1 : Ap) + (kt) * BK, off0, off1)
; #define STG_B(b, h, kt) stage_half_s(lds0 + (4 + (b) * 2 + (h)) * HT_B, ((h) ? B1p : Bp) + (kt) * BK, off0, off1)
; #define LDA8(b, h) _Pragma("unroll") for (int m = 0; m < 4; ++m) _Pragma("unroll") for (int k = 0; k < 2; ++k) \
;     At[m][k] = *(const bf16x8*)(SA_(shm, b, h) + abase + (m * 2 + k) * 1024)
; #define LDB8(dst, b, h) _Pragma("unroll") for (int n = 0; n < 2; ++n) _Pragma("unroll") for (int k = 0; k < 2; ++k) \
;     dst[n][k] = *(const bf16x8*)(SB_(shm, b, h) + bbase + (n * 2 + k) * 1024)
; #define MMA8(ai, bj, Bx) do { __builtin_amdgcn_s_setprio(1); \
;     _Pragma("unroll") for (int m = 0; m < 4; ++m) _Pragma("unroll") for (int n = 0; n < 2; ++n) _Pragma("unroll") for (int k = 0; k < 2; ++k) \
;       acc[ai][bj][m][n] = __builtin_amdgcn_mfma_f32_16x16x32_bf16(At[m][k], Bx[n][k], acc[ai][bj][m][n], 0, 0, 0); \
;     __builtin_amdgcn_s_setprio(0); } while (0)
; template <bool HS>
; __device__ __forceinline__ void gemm_tile8(const u16* __restrict__ Ap, const u16* __restrict__ Bp, int K,
;                                            f32x4 (&acc)[2][2][4][2], char* shm, const int tid, const float* hsr = nullptr) {
;     ...
;     LDA8(0, 1); STG_A(0, 0, t + 2);
;     BAR; WAIT_L(0); MMA8(1, 0, B0); BAR; SCHED;
;     STG_B(0, 1, t + 2);
;     WAIT_V(6); BAR; MMA8(1, 1, B1); BAR;
;     LDB8(B0, 1, 0); SCHED; LDA8(1, 0); STG_A(0, 1, t + 2);
;     WAIT_L(8); BAR; WAIT_L(0); MMA8(0, 0, B0); BAR; SCHED;
;     LDB8(B1, 1, 1); STG_B(1, 0, t + 3);
;     BAR; WAIT_L(0); MMA8(0, 1, B1); BAR;
	ds_read_b128 v[158:161], v130 offset:16384
	ds_read_b128 v[164:167], v130 offset:17408
	ds_read_b128 v[168:171], v130 offset:18432
	ds_read_b128 v[172:175], v130 offset:19456
	ds_read_b128 v[180:183], v130 offset:20480
	ds_read_b128 v[184:187], v130 offset:21504
	ds_read_b128 v[188:191], v130 offset:22528
	ds_read_b128 v[192:195], v130 offset:23552
	s_add_u32 s24, s3, s6
	s_addc_u32 s25, s10, s7
	s_add_u32 s24, s24, 0x100
	s_addc_u32 s25, s25, 0
	s_add_i32 s23, s15, 0x10000
	s_mov_b32 m0, s23
	s_nop 0
	global_load_lds_dwordx4 v132, s[24:25]
	s_add_i32 s23, s15, 0x12000
	s_mov_b32 m0, s23
	s_nop 0
	global_load_lds_dwordx4 v131, s[24:25]
	s_add_u32 s24, s8, s6
	s_addc_u32 s25, s9, s7
	s_add_u32 s24, s24, 0x100
	s_addc_u32 s25, s25, 0
	s_mov_b32 m0, s15
	s_nop 0
	global_load_lds_dwordx4 v132, s[24:25]
	s_add_i32 s23, s15, 0x2000
	s_mov_b32 m0, s23
	s_nop 0
	global_load_lds_dwordx4 v131, s[24:25]
	s_add_u32 s24, s13, s6
	s_addc_u32 s25, s14, s7
	s_add_u32 s24, s24, 0x100
	s_addc_u32 s25, s25, 0
	s_add_i32 s23, s15, 0x14000
	s_mov_b32 m0, s23
	s_nop 0
	global_load_lds_dwordx4 v132, s[24:25]
	s_add_i32 s23, s15, 0x16000
	s_mov_b32 m0, s23
	s_nop 0
	global_load_lds_dwordx4 v131, s[24:25]
	s_waitcnt vmcnt(8) lgkmcnt(0)
	s_barrier
	s_setprio 1
	v_mfma_f32_16x16x32_bf16 v[62:65], v[158:161], v[142:145], 0
	v_mfma_f32_16x16x32_bf16 v[58:61], v[158:161], v[150:153], 0
	v_mfma_f32_16x16x32_bf16 v[50:53], v[168:171], v[150:153], 0
	v_mfma_f32_16x16x32_bf16 v[54:57], v[168:171], v[142:145], 0
	v_mfma_f32_16x16x32_bf16 v[46:49], v[180:183], v[142:145], 0
	v_mfma_f32_16x16x32_bf16 v[42:45], v[180:183], v[150:153], 0
	v_mfma_f32_16x16x32_bf16 v[34:37], v[188:191], v[150:153], 0
	v_mfma_f32_16x16x32_bf16 v[38:41], v[188:191], v[142:145], 0
	v_mfma_f32_16x16x32_bf16 v[62:65], v[164:167], v[146:149], v[62:65]
	v_mfma_f32_16x16x32_bf16 v[58:61], v[164:167], v[154:157], v[58:61]
	v_mfma_f32_16x16x32_bf16 v[50:53], v[172:175], v[154:157], v[50:53]
	v_mfma_f32_16x16x32_bf16 v[54:57], v[172:175], v[146:149], v[54:57]
	v_mfma_f32_16x16x32_bf16 v[46:49], v[184:187], v[146:149], v[46:49]
	v_mfma_f32_16x16x32_bf16 v[42:45], v[184:187], v[154:157], v[42:45]
	v_mfma_f32_16x16x32_bf16 v[34:37], v[192:195], v[154:157], v[34:37]
	v_mfma_f32_16x16x32_bf16 v[38:41], v[192:195], v[146:149], v[38:41]
	v_mfma_f32_16x16x32_bf16 v[30:33], v[158:161], v[196:199], 0
	v_mfma_f32_16x16x32_bf16 v[26:29], v[158:161], v[204:207], 0
	v_mfma_f32_16x16x32_bf16 v[18:21], v[168:171], v[204:207], 0
	v_mfma_f32_16x16x32_bf16 v[22:25], v[168:171], v[196:199], 0
	v_mfma_f32_16x16x32_bf16 v[14:17], v[180:183], v[196:199], 0
	v_mfma_f32_16x16x32_bf16 v[10:13], v[180:183], v[204:207], 0
	v_mfma_f32_16x16x32_bf16 v[2:5], v[188:191], v[204:207], 0
	v_mfma_f32_16x16x32_bf16 v[6:9], v[188:191], v[196:199], 0
	v_mfma_f32_16x16x32_bf16 v[30:33], v[164:167], v[200:203], v[30:33]
	v_mfma_f32_16x16x32_bf16 v[26:29], v[164:167], v[208:211], v[26:29]
	v_mfma_f32_16x16x32_bf16 v[18:21], v[172:175], v[208:211], v[18:21]
	v_mfma_f32_16x16x32_bf16 v[22:25], v[172:175], v[200:203], v[22:25]
	v_mfma_f32_16x16x32_bf16 v[14:17], v[184:187], v[200:203], v[14:17]
	v_mfma_f32_16x16x32_bf16 v[10:13], v[184:187], v[208:211], v[10:13]
	v_mfma_f32_16x16x32_bf16 v[2:5], v[192:195], v[208:211], v[2:5]
	v_mfma_f32_16x16x32_bf16 v[6:9], v[192:195], v[200:203], v[6:9]
	s_setprio 0
	s_barrier
	v_add_u32_e32 v154, 0x18000, v133
	ds_read_b128 v[142:145], v154
	ds_read_b128 v[146:149], v154 offset:1024
	ds_read_b128 v[150:153], v154 offset:2048
	ds_read_b128 v[154:157], v154 offset:3072
	ds_read_b128 v[158:161], v130 offset:32768
	ds_read_b128 v[164:167], v130 offset:33792
	ds_read_b128 v[168:171], v130 offset:34816
	ds_read_b128 v[172:175], v130 offset:35840
	ds_read_b128 v[180:183], v130 offset:36864
	ds_read_b128 v[184:187], v130 offset:37888
	ds_read_b128 v[188:191], v130 offset:38912
	ds_read_b128 v[192:195], v130 offset:39936
	v_add_u32_e32 v208, 0x1c000, v133
	ds_read_b128 v[196:199], v208
	ds_read_b128 v[200:203], v208 offset:1024
	ds_read_b128 v[204:207], v208 offset:2048
	ds_read_b128 v[208:211], v208 offset:3072
	s_add_u32 s24, s18, s6
	s_addc_u32 s25, s19, s7
	s_add_u32 s24, s24, 0x100
	s_addc_u32 s25, s25, 0
	s_add_i32 s23, s15, 0x4000
	s_mov_b32 m0, s23
	s_nop 0
	global_load_lds_dwordx4 v132, s[24:25]
	s_add_i32 s23, s15, 0x6000
	s_mov_b32 m0, s23
	s_nop 0
	global_load_lds_dwordx4 v131, s[24:25]
	s_waitcnt vmcnt(8) lgkmcnt(0)
	s_barrier
	s_setprio 1
	v_mfma_f32_16x16x32_bf16 v[126:129], v[158:161], v[142:145], v[126:129]
	v_mfma_f32_16x16x32_bf16 v[122:125], v[158:161], v[150:153], v[122:125]
	v_mfma_f32_16x16x32_bf16 v[114:117], v[168:171], v[150:153], v[114:117]
	v_mfma_f32_16x16x32_bf16 v[118:121], v[168:171], v[142:145], v[118:121]
	v_mfma_f32_16x16x32_bf16 v[110:113], v[180:183], v[142:145], v[110:113]
	v_mfma_f32_16x16x32_bf16 v[106:109], v[180:183], v[150:153], v[106:109]
	v_mfma_f32_16x16x32_bf16 v[98:101], v[188:191], v[150:153], v[98:101]
	v_mfma_f32_16x16x32_bf16 v[102:105], v[188:191], v[142:145], v[102:105]
	v_mfma_f32_16x16x32_bf16 v[126:129], v[164:167], v[146:149], v[126:129]
	v_mfma_f32_16x16x32_bf16 v[122:125], v[164:167], v[154:157], v[122:125]
	v_mfma_f32_16x16x32_bf16 v[114:117], v[172:175], v[154:157], v[114:117]
	v_mfma_f32_16x16x32_bf16 v[118:121], v[172:175], v[146:149], v[118:121]
	v_mfma_f32_16x16x32_bf16 v[110:113], v[184:187], v[146:149], v[110:113]
	v_mfma_f32_16x16x32_bf16 v[106:109], v[184:187], v[154:157], v[106:109]
	v_mfma_f32_16x16x32_bf16 v[98:101], v[192:195], v[154:157], v[98:101]
	v_mfma_f32_16x16x32_bf16 v[102:105], v[192:195], v[146:149], v[102:105]
	v_mfma_f32_16x16x32_bf16 v[94:97], v[158:161], v[196:199], v[94:97]
	v_mfma_f32_16x16x32_bf16 v[90:93], v[158:161], v[204:207], v[90:93]
	v_mfma_f32_16x16x32_bf16 v[82:85], v[168:171], v[204:207], v[82:85]
	v_mfma_f32_16x16x32_bf16 v[86:89], v[168:171], v[196:199], v[86:89]
	v_mfma_f32_16x16x32_bf16 v[78:81], v[180:183], v[196:199], v[78:81]
	v_mfma_f32_16x16x32_bf16 v[74:77], v[180:183], v[204:207], v[74:77]
	v_mfma_f32_16x16x32_bf16 v[66:69], v[188:191], v[204:207], v[66:69]
	v_mfma_f32_16x16x32_bf16 v[70:73], v[188:191], v[196:199], v[70:73]
	v_mfma_f32_16x16x32_bf16 v[94:97], v[164:167], v[200:203], v[94:97]
	v_mfma_f32_16x16x32_bf16 v[90:93], v[164:167], v[208:211], v[90:93]
	v_mfma_f32_16x16x32_bf16 v[82:85], v[172:175], v[208:211], v[82:85]
	v_mfma_f32_16x16x32_bf16 v[86:89], v[172:175], v[200:203], v[86:89]
	v_mfma_f32_16x16x32_bf16 v[78:81], v[184:187], v[200:203], v[78:81]
	v_mfma_f32_16x16x32_bf16 v[74:77], v[184:187], v[208:211], v[74:77]
	v_mfma_f32_16x16x32_bf16 v[66:69], v[192:195], v[208:211], v[66:69]
	v_mfma_f32_16x16x32_bf16 v[70:73], v[192:195], v[200:203], v[70:73]
	s_setprio 0
	s_barrier
; #define WAIT_V(n) asm volatile("s_waitcnt vmcnt(" #n ")" ::: "memory")
; #define WAIT_L(n) asm volatile("s_waitcnt lgkmcnt(" #n ")" ::: "memory")
; #define BAR __builtin_amdgcn_s_barrier()
; #define SCHED __builtin_amdgcn_sched_barrier(0)
; #define STG_A(b, h, kt) stage_half_s(lds0 + ((b) * 2 + (h)) * HT_B, ((h) ? A1 : Ap) + (kt) * BK, off0, off1)
; #define STG_B(b, h, kt) stage_half_s(lds0 + (4 + (b) * 2 + (h)) * HT_B, ((h) ? B1p : Bp) + (kt) * BK, off0, off1)
; #define STG_A(b, h, kt) stage_half_s(lds0 + ((b) * 2 + (h)) * HT_B, ((h) ? A1 : Ap) + (kt) * BK, off0, off1)
; #define STG_B(b, h, kt) stage_half_s(lds0 + (4 + (b) * 2 + (h)) * HT_B, ((h) ? B1p : Bp) + (kt) * BK, off0, off1)
; #define LDA8(b, h) _Pragma("unroll") for (int m = 0; m < 4; ++m) _Pragma("unroll") for (int k = 0; k < 2; ++k) \
;     At[m][k] = *(const bf16x8*)(SA_(shm, b, h) + abase + (m * 2 + k) * 1024)
; #define LDB8(dst, b, h) _Pragma("unroll") for (int n = 0; n < 2; ++n) _Pragma("unroll") for (int k = 0; k < 2; ++k) \
;     dst[n][k] = *(const bf16x8*)(SB_(shm, b, h) + bbase + (n * 2 + k) * 1024)
; #define MMA8(ai, bj, Bx) do { __builtin_amdgcn_s_setprio(1); \
;     _Pragma("unroll") for (int m = 0; m < 4; ++m) _Pragma("unroll") for (int n = 0; n < 2; ++n) _Pragma("unroll") for (int k = 0; k < 2; ++k) \
;       acc[ai][bj][m][n] = __builtin_amdgcn_mfma_f32_16x16x32_bf16(At[m][k], Bx[n][k], acc[ai][bj][m][n], 0, 0, 0); \
;     __builtin_amdgcn_s_setprio(0); } while (0)
; template <bool HS>
; __device__ __forceinline__ void gemm_tile8(const u16* __restrict__ Ap, const u16* __restrict__ Bp, int K,
;                                            f32x4 (&acc)[2][2][4][2], char* shm, const int tid, const float* hsr = nullptr) {
;     ...
;     LDB8(B0, 0, 0); SCHED; LDA8(0, 0); STG_A(1, 1, t + 1);
;     WAIT_L(8); BAR; WAIT_L(0); MMA8(0, 0, B0); BAR; SCHED;
;     LDB8(B1, 0, 1); STG_B(0, 0, t + 2);
;     ...
;     LDA8(1, 1); STG_A(1, 0, t + 3);
;     BAR; WAIT_L(0); MMA8(1, 0, B0); BAR; SCHED;
;     STG_B(1, 1, t + 3);
;     WAIT_V(6); BAR; MMA8(1, 1, B1); BAR;
;   }
	ds_read_b128 v[158:161], v130 offset:49152
	ds_read_b128 v[164:167], v130 offset:50176
	ds_read_b128 v[168:171], v130 offset:51200
	ds_read_b128 v[172:175], v130 offset:52224
	ds_read_b128 v[180:183], v130 offset:53248
	ds_read_b128 v[184:187], v130 offset:54272
	ds_read_b128 v[188:191], v130 offset:55296
	ds_read_b128 v[192:195], v130 offset:56320
	s_add_u32 s24, s3, s6
	s_addc_u32 s25, s10, s7
	s_add_u32 s24, s24, 0x180
	s_addc_u32 s25, s25, 0
	s_add_i32 s23, s15, 0x18000
	s_mov_b32 m0, s23
	s_nop 0
	global_load_lds_dwordx4 v132, s[24:25]
	s_add_i32 s23, s15, 0x1a000
	s_mov_b32 m0, s23
	s_nop 0
	global_load_lds_dwordx4 v131, s[24:25]
	s_add_u32 s24, s8, s6
	s_addc_u32 s25, s9, s7
	s_add_u32 s24, s24, 0x180
	s_addc_u32 s25, s25, 0
	s_add_i32 s23, s15, 0x8000
	s_mov_b32 m0, s23
	s_nop 0
	global_load_lds_dwordx4 v132, s[24:25]
	s_add_i32 s23, s15, 0xa000
	s_mov_b32 m0, s23
	s_nop 0
	global_load_lds_dwordx4 v131, s[24:25]
	s_add_u32 s24, s13, s6
	s_addc_u32 s25, s14, s7
	s_add_u32 s24, s24, 0x180
	s_addc_u32 s25, s25, 0
	s_add_i32 s23, s15, 0x1c000
	s_mov_b32 m0, s23
	s_nop 0
	global_load_lds_dwordx4 v132, s[24:25]
	s_add_i32 s23, s15, 0x1e000
	s_mov_b32 m0, s23
	s_nop 0
	global_load_lds_dwordx4 v131, s[24:25]
	s_waitcnt vmcnt(8) lgkmcnt(0)
	s_barrier
	s_setprio 1
	v_mfma_f32_16x16x32_bf16 v[62:65], v[158:161], v[142:145], v[62:65]
	v_mfma_f32_16x16x32_bf16 v[58:61], v[158:161], v[150:153], v[58:61]
	v_mfma_f32_16x16x32_bf16 v[50:53], v[168:171], v[150:153], v[50:53]
	v_mfma_f32_16x16x32_bf16 v[54:57], v[168:171], v[142:145], v[54:57]
	v_mfma_f32_16x16x32_bf16 v[46:49], v[180:183], v[142:145], v[46:49]
	v_mfma_f32_16x16x32_bf16 v[42:45], v[180:183], v[150:153], v[42:45]
	v_mfma_f32_16x16x32_bf16 v[34:37], v[188:191], v[150:153], v[34:37]
	v_mfma_f32_16x16x32_bf16 v[38:41], v[188:191], v[142:145], v[38:41]
	v_mfma_f32_16x16x32_bf16 v[62:65], v[164:167], v[146:149], v[62:65]
	v_mfma_f32_16x16x32_bf16 v[58:61], v[164:167], v[154:157], v[58:61]
	v_mfma_f32_16x16x32_bf16 v[50:53], v[172:175], v[154:157], v[50:53]
	v_mfma_f32_16x16x32_bf16 v[54:57], v[172:175], v[146:149], v[54:57]
	v_mfma_f32_16x16x32_bf16 v[46:49], v[184:187], v[146:149], v[46:49]
	v_mfma_f32_16x16x32_bf16 v[42:45], v[184:187], v[154:157], v[42:45]
	v_mfma_f32_16x16x32_bf16 v[34:37], v[192:195], v[154:157], v[34:37]
	v_mfma_f32_16x16x32_bf16 v[38:41], v[192:195], v[146:149], v[38:41]
	v_mfma_f32_16x16x32_bf16 v[30:33], v[158:161], v[196:199], v[30:33]
	v_mfma_f32_16x16x32_bf16 v[26:29], v[158:161], v[204:207], v[26:29]
	v_mfma_f32_16x16x32_bf16 v[18:21], v[168:171], v[204:207], v[18:21]
	v_mfma_f32_16x16x32_bf16 v[22:25], v[168:171], v[196:199], v[22:25]
	v_mfma_f32_16x16x32_bf16 v[14:17], v[180:183], v[196:199], v[14:17]
	v_mfma_f32_16x16x32_bf16 v[10:13], v[180:183], v[204:207], v[10:13]
	v_mfma_f32_16x16x32_bf16 v[2:5], v[188:191], v[204:207], v[2:5]
	v_mfma_f32_16x16x32_bf16 v[6:9], v[188:191], v[196:199], v[6:9]
	v_mfma_f32_16x16x32_bf16 v[30:33], v[164:167], v[200:203], v[30:33]
	v_mfma_f32_16x16x32_bf16 v[26:29], v[164:167], v[208:211], v[26:29]
	v_mfma_f32_16x16x32_bf16 v[18:21], v[172:175], v[208:211], v[18:21]
	v_mfma_f32_16x16x32_bf16 v[22:25], v[172:175], v[200:203], v[22:25]
	v_mfma_f32_16x16x32_bf16 v[14:17], v[184:187], v[200:203], v[14:17]
	v_mfma_f32_16x16x32_bf16 v[10:13], v[184:187], v[208:211], v[10:13]
	v_mfma_f32_16x16x32_bf16 v[2:5], v[192:195], v[208:211], v[2:5]
	v_mfma_f32_16x16x32_bf16 v[6:9], v[192:195], v[200:203], v[6:9]
	s_setprio 0
	s_barrier
	s_add_i32 s20, s20, 2
	s_add_u32 s6, s6, 0x100
	s_addc_u32 s7, s7, 0
	s_cmp_lt_u32 s20, 12
	s_cbranch_scc0 .Lk_ret_in_exit
.Lk_ret_in:
	v_add_u32_e32 v154, 0x10000, v133
	ds_read_b128 v[142:145], v154
	ds_read_b128 v[146:149], v154 offset:1024
	ds_read_b128 v[150:153], v154 offset:2048
	ds_read_b128 v[154:157], v154 offset:3072
	ds_read_b128 v[158:161], v130
	ds_read_b128 v[164:167], v130 offset:1024
	ds_read_b128 v[168:171], v130 offset:2048
	ds_read_b128 v[172:175], v130 offset:3072
	ds_read_b128 v[180:183], v130 offset:4096
	ds_read_b128 v[184:187], v130 offset:5120
	ds_read_b128 v[188:191], v130 offset:6144
	ds_read_b128 v[192:195], v130 offset:7168
	v_add_u32_e32 v208, 0x14000, v133
	ds_read_b128 v[196:199], v208
	ds_read_b128 v[200:203], v208 offset:1024
	ds_read_b128 v[204:207], v208 offset:2048
	ds_read_b128 v[208:211], v208 offset:3072
	s_add_u32 s24, s18, s6
	s_addc_u32 s25, s19, s7
	s_add_u32 s24, s24, 0x80
	s_addc_u32 s25, s25, 0
	s_add_i32 s23, s15, 0xc000
	s_mov_b32 m0, s23
	s_nop 0
	global_load_lds_dwordx4 v132, s[24:25]
	s_add_i32 s23, s15, 0xe000
	s_mov_b32 m0, s23
	s_nop 0
	global_load_lds_dwordx4 v131, s[24:25]
	s_waitcnt vmcnt(8) lgkmcnt(0)
	s_barrier
; #define WAIT_V(n) asm volatile("s_waitcnt vmcnt(" #n ")" ::: "memory")
; #define WAIT_L(n) asm volatile("s_waitcnt lgkmcnt(" #n ")" ::: "memory")
; #define BAR __builtin_amdgcn_s_barrier()
; #define SCHED __builtin_amdgcn_sched_barrier(0)
; #define STG_A(b, h, kt) stage_half_s(lds0 + ((b) * 2 + (h)) * HT_B, ((h) ? A1 : Ap) + (kt) * BK, off0, off1)
; #define STG_B(b, h, kt) stage_half_s(lds0 + (4 + (b) * 2 + (h)) * HT_B, ((h) ? B1p : Bp) + (kt) * BK, off0, off1)
; #define STG_A(b, h, kt) stage_half_s(lds0 + ((b) * 2 + (h)) * HT_B, ((h) ? A1 : Ap) + (kt) * BK, off0, off1)
; #define STG_B(b, h, kt) stage_half_s(lds0 + (4 + (b) * 2 + (h)) * HT_B, ((h) ? B1p : Bp) + (kt) * BK, off0, off1)
; #define LDA8(b, h) _Pragma("unroll") for (int m = 0; m < 4; ++m) _Pragma("unroll") for (int k = 0; k < 2; ++k) \
;     At[m][k] = *(const bf16x8*)(SA_(shm, b, h) + abase + (m * 2 + k) * 1024)
; #define LDB8(dst, b, h) _Pragma("unroll") for (int n = 0; n < 2; ++n) _Pragma("unroll") for (int k = 0; k < 2; ++k) \
;     dst[n][k] = *(const bf16x8*)(SB_(shm, b, h) + bbase + (n * 2 + k) * 1024)
; #define MMA8(ai, bj, Bx) do { __builtin_amdgcn_s_setprio(1); \
;     _Pragma("unroll") for (int m = 0; m < 4; ++m) _Pragma("unroll") for (int n = 0; n < 2; ++n) _Pragma("unroll") for (int k = 0; k < 2; ++k) \
;       acc[ai][bj][m][n] = __builtin_amdgcn_mfma_f32_16x16x32_bf16(At[m][k], Bx[n][k], acc[ai][bj][m][n], 0, 0, 0); \
;     __builtin_amdgcn_s_setprio(0); } while (0)
; template <bool HS>
; __device__ __forceinline__ void gemm_tile8(const u16* __restrict__ Ap, const u16* __restrict__ Bp, int K,
;                                            f32x4 (&acc)[2][2][4][2], char* shm, const int tid, const float* hsr = nullptr) {
;     ...
;     WAIT_L(8); BAR; WAIT_L(0); MMA8(0, 0, B0); BAR; SCHED;
;     LDB8(B1, 0, 1); STG_B(0, 0, t + 2);
;     BAR; WAIT_L(0); MMA8(0, 1, B1); BAR;
;     LDA8(0, 1); STG_A(0, 0, t + 2);
;     BAR; WAIT_L(0); MMA8(1, 0, B0); BAR; SCHED;
;     STG_B(0, 1, t + 2);
;     WAIT_V(6); BAR; MMA8(1, 1, B1); BAR;
;     LDB8(B0, 1, 0); SCHED; LDA8(1, 0); STG_A(0, 1, t + 2);
;     WAIT_L(8); BAR; WAIT_L(0); MMA8(0, 0, B0); BAR; SCHED;
;     LDB8(B1, 1, 1); STG_B(1, 0, t + 3);
;     BAR; WAIT_L(0); MMA8(0, 1, B1); BAR;
	s_setprio 1
	v_mfma_f32_16x16x32_bf16 v[126:129], v[158:161], v[142:145], v[126:129]
	v_mfma_f32_16x16x32_bf16 v[122:125], v[158:161], v[150:153], v[122:125]
	v_mfma_f32_16x16x32_bf16 v[114:117], v[168:171], v[150:153], v[114:117]
	v_mfma_f32_16x16x32_bf16 v[118:121], v[168:171], v[142:145], v[118:121]
	v_mfma_f32_16x16x32_bf16 v[110:113], v[180:183], v[142:145], v[110:113]
	v_mfma_f32_16x16x32_bf16 v[106:109], v[180:183], v[150:153], v[106:109]
	v_mfma_f32_16x16x32_bf16 v[98:101], v[188:191], v[150:153], v[98:101]
	v_mfma_f32_16x16x32_bf16 v[102:105], v[188:191], v[142:145], v[102:105]
	v_mfma_f32_16x16x32_bf16 v[126:129], v[164:167], v[146:149], v[126:129]
	v_mfma_f32_16x16x32_bf16 v[122:125], v[164:167], v[154:157], v[122:125]
	v_mfma_f32_16x16x32_bf16 v[114:117], v[172:175], v[154:157], v[114:117]
	v_mfma_f32_16x16x32_bf16 v[118:121], v[172:175], v[146:149], v[118:121]
	v_mfma_f32_16x16x32_bf16 v[110:113], v[184:187], v[146:149], v[110:113]
	v_mfma_f32_16x16x32_bf16 v[106:109], v[184:187], v[154:157], v[106:109]
	v_mfma_f32_16x16x32_bf16 v[98:101], v[192:195], v[154:157], v[98:101]
	v_mfma_f32_16x16x32_bf16 v[102:105], v[192:195], v[146:149], v[102:105]
	v_mfma_f32_16x16x32_bf16 v[94:97], v[158:161], v[196:199], v[94:97]
	v_mfma_f32_16x16x32_bf16 v[90:93], v[158:161], v[204:207], v[90:93]
	v_mfma_f32_16x16x32_bf16 v[82:85], v[168:171], v[204:207], v[82:85]
	v_mfma_f32_16x16x32_bf16 v[86:89], v[168:171], v[196:199], v[86:89]
	v_mfma_f32_16x16x32_bf16 v[78:81], v[180:183], v[196:199], v[78:81]
	v_mfma_f32_16x16x32_bf16 v[74:77], v[180:183], v[204:207], v[74:77]
	v_mfma_f32_16x16x32_bf16 v[66:69], v[188:191], v[204:207], v[66:69]
	v_mfma_f32_16x16x32_bf16 v[70:73], v[188:191], v[196:199], v[70:73]
	v_mfma_f32_16x16x32_bf16 v[94:97], v[164:167], v[200:203], v[94:97]
	v_mfma_f32_16x16x32_bf16 v[90:93], v[164:167], v[208:211], v[90:93]
	v_mfma_f32_16x16x32_bf16 v[82:85], v[172:175], v[208:211], v[82:85]
	v_mfma_f32_16x16x32_bf16 v[86:89], v[172:175], v[200:203], v[86:89]
	v_mfma_f32_16x16x32_bf16 v[78:81], v[184:187], v[200:203], v[78:81]
	v_mfma_f32_16x16x32_bf16 v[74:77], v[184:187], v[208:211], v[74:77]
	v_mfma_f32_16x16x32_bf16 v[66:69], v[192:195], v[208:211], v[66:69]
	v_mfma_f32_16x16x32_bf16 v[70:73], v[192:195], v[200:203], v[70:73]
	s_setprio 0
	s_barrier
	ds_read_b128 v[158:161], v130 offset:16384
	ds_read_b128 v[164:167], v130 offset:17408
	ds_read_b128 v[168:171], v130 offset:18432
	ds_read_b128 v[172:175], v130 offset:19456
	ds_read_b128 v[180:183], v130 offset:20480
	ds_read_b128 v[184:187], v130 offset:21504
	ds_read_b128 v[188:191], v130 offset:22528
	ds_read_b128 v[192:195], v130 offset:23552
	s_add_u32 s24, s3, s6
	s_addc_u32 s25, s10, s7
	s_add_u32 s24, s24, 0x100
	s_addc_u32 s25, s25, 0
	s_add_i32 s23, s15, 0x10000
	s_mov_b32 m0, s23
	s_nop 0
	global_load_lds_dwordx4 v132, s[24:25]
	s_add_i32 s23, s15, 0x12000
	s_mov_b32 m0, s23
	s_nop 0
	global_load_lds_dwordx4 v131, s[24:25]
	s_add_u32 s24, s8, s6
	s_addc_u32 s25, s9, s7
	s_add_u32 s24, s24, 0x100
	s_addc_u32 s25, s25, 0
	s_mov_b32 m0, s15
	s_nop 0
	global_load_lds_dwordx4 v132, s[24:25]
	s_add_i32 s23, s15, 0x2000
	s_mov_b32 m0, s23
	s_nop 0
	global_load_lds_dwordx4 v131, s[24:25]
	s_add_u32 s24, s13, s6
	s_addc_u32 s25, s14, s7
	s_add_u32 s24, s24, 0x100
	s_addc_u32 s25, s25, 0
	s_add_i32 s23, s15, 0x14000
	s_mov_b32 m0, s23
	s_nop 0
	global_load_lds_dwordx4 v132, s[24:25]
	s_add_i32 s23, s15, 0x16000
	s_mov_b32 m0, s23
	s_nop 0
	global_load_lds_dwordx4 v131, s[24:25]
	s_waitcnt vmcnt(8) lgkmcnt(0)
	s_barrier
	s_setprio 1
	v_mfma_f32_16x16x32_bf16 v[62:65], v[158:161], v[142:145], v[62:65]
	v_mfma_f32_16x16x32_bf16 v[58:61], v[158:161], v[150:153], v[58:61]
	v_mfma_f32_16x16x32_bf16 v[50:53], v[168:171], v[150:153], v[50:53]
	v_mfma_f32_16x16x32_bf16 v[54:57], v[168:171], v[142:145], v[54:57]
	v_mfma_f32_16x16x32_bf16 v[46:49], v[180:183], v[142:145], v[46:49]
	v_mfma_f32_16x16x32_bf16 v[42:45], v[180:183], v[150:153], v[42:45]
	v_mfma_f32_16x16x32_bf16 v[34:37], v[188:191], v[150:153], v[34:37]
	v_mfma_f32_16x16x32_bf16 v[38:41], v[188:191], v[142:145], v[38:41]
	v_mfma_f32_16x16x32_bf16 v[62:65], v[164:167], v[146:149], v[62:65]
	v_mfma_f32_16x16x32_bf16 v[58:61], v[164:167], v[154:157], v[58:61]
	v_mfma_f32_16x16x32_bf16 v[50:53], v[172:175], v[154:157], v[50:53]
	v_mfma_f32_16x16x32_bf16 v[54:57], v[172:175], v[146:149], v[54:57]
	v_mfma_f32_16x16x32_bf16 v[46:49], v[184:187], v[146:149], v[46:49]
	v_mfma_f32_16x16x32_bf16 v[42:45], v[184:187], v[154:157], v[42:45]
	v_mfma_f32_16x16x32_bf16 v[34:37], v[192:195], v[154:157], v[34:37]
	v_mfma_f32_16x16x32_bf16 v[38:41], v[192:195], v[146:149], v[38:41]
	v_mfma_f32_16x16x32_bf16 v[30:33], v[158:161], v[196:199], v[30:33]
	v_mfma_f32_16x16x32_bf16 v[26:29], v[158:161], v[204:207], v[26:29]
	v_mfma_f32_16x16x32_bf16 v[18:21], v[168:171], v[204:207], v[18:21]
	v_mfma_f32_16x16x32_bf16 v[22:25], v[168:171], v[196:199], v[22:25]
	v_mfma_f32_16x16x32_bf16 v[14:17], v[180:183], v[196:199], v[14:17]
	v_mfma_f32_16x16x32_bf16 v[10:13], v[180:183], v[204:207], v[10:13]
	v_mfma_f32_16x16x32_bf16 v[2:5], v[188:191], v[204:207], v[2:5]
	v_mfma_f32_16x16x32_bf16 v[6:9], v[188:191], v[196:199], v[6:9]
	v_mfma_f32_16x16x32_bf16 v[30:33], v[164:167], v[200:203], v[30:33]
	v_mfma_f32_16x16x32_bf16 v[26:29], v[164:167], v[208:211], v[26:29]
	v_mfma_f32_16x16x32_bf16 v[18:21], v[172:175], v[208:211], v[18:21]
	v_mfma_f32_16x16x32_bf16 v[22:25], v[172:175], v[200:203], v[22:25]
	v_mfma_f32_16x16x32_bf16 v[14:17], v[184:187], v[200:203], v[14:17]
	v_mfma_f32_16x16x32_bf16 v[10:13], v[184:187], v[208:211], v[10:13]
	v_mfma_f32_16x16x32_bf16 v[2:5], v[192:195], v[208:211], v[2:5]
	v_mfma_f32_16x16x32_bf16 v[6:9], v[192:195], v[200:203], v[6:9]
	s_setprio 0
	s_barrier
; #define WAIT_V(n) asm volatile("s_waitcnt vmcnt(" #n ")" ::: "memory")
; #define WAIT_L(n) asm volatile("s_waitcnt lgkmcnt(" #n ")" ::: "memory")
; #define BAR __builtin_amdgcn_s_barrier()
; #define SCHED __builtin_amdgcn_sched_barrier(0)
; #define STG_A(b, h, kt) stage_half_s(lds0 + ((b) * 2 + (h)) * HT_B, ((h) ? A1 : Ap) + (kt) * BK, off0, off1)
; #define STG_B(b, h, kt) stage_half_s(lds0 + (4 + (b) * 2 + (h)) * HT_B, ((h) ? B1p : Bp) + (kt) * BK, off0, off1)
; #define STG_A(b, h, kt) stage_half_s(lds0 + ((b) * 2 + (h)) * HT_B, ((h) ? A1 : Ap) + (kt) * BK, off0, off1)
; #define STG_B(b, h, kt) stage_half_s(lds0 + (4 + (b) * 2 + (h)) * HT_B, ((h) ? B1p : Bp) + (kt) * BK, off0, off1)
; #define LDA8(b, h) _Pragma("unroll") for (int m = 0; m < 4; ++m) _Pragma("unroll") for (int k = 0; k < 2; ++k) \
;     At[m][k] = *(const bf16x8*)(SA_(shm, b, h) + abase + (m * 2 + k) * 1024)
; #define LDB8(dst, b, h) _Pragma("unroll") for (int n = 0; n < 2; ++n) _Pragma("unroll") for (int k = 0; k < 2; ++k) \
;     dst[n][k] = *(const bf16x8*)(SB_(shm, b, h) + bbase + (n * 2 + k) * 1024)
; #define MMA8(ai, bj, Bx) do { __builtin_amdgcn_s_setprio(1); \
;     _Pragma("unroll") for (int m = 0; m < 4; ++m) _Pragma("unroll") for (int n = 0; n < 2; ++n) _Pragma("unroll") for (int k = 0; k < 2; ++k) \
;       acc[ai][bj][m][n] = __builtin_amdgcn_mfma_f32_16x16x32_bf16(At[m][k], Bx[n][k], acc[ai][bj][m][n], 0, 0, 0); \
;     __builtin_amdgcn_s_setprio(0); } while (0)
; template <bool HS>
; __device__ __forceinline__ void gemm_tile8(const u16* __restrict__ Ap, const u16* __restrict__ Bp, int K,
;                                            f32x4 (&acc)[2][2][4][2], char* shm, const int tid, const float* hsr = nullptr) {
;     ...
;     LDB8(B0, 1, 0); SCHED; LDA8(1, 0); STG_A(0, 1, t + 2);
;     WAIT_L(8); BAR; WAIT_L(0); MMA8(0, 0, B0); BAR; SCHED;
;     LDB8(B1, 1, 1); STG_B(1, 0, t + 3);
;     BAR; WAIT_L(0); MMA8(0, 1, B1); BAR;
;     LDA8(1, 1); STG_A(1, 0, t + 3);
;     BAR; WAIT_L(0); MMA8(1, 0, B0); BAR; SCHED;
;     STG_B(1, 1, t + 3);
;     WAIT_V(6); BAR; MMA8(1, 1, B1); BAR;
;   }
	v_add_u32_e32 v154, 0x18000, v133
	ds_read_b128 v[142:145], v154
	ds_read_b128 v[146:149], v154 offset:1024
	ds_read_b128 v[150:153], v154 offset:2048
	ds_read_b128 v[154:157], v154 offset:3072
	ds_read_b128 v[158:161], v130 offset:32768
	ds_read_b128 v[164:167], v130 offset:33792
	ds_read_b128 v[168:171], v130 offset:34816
	ds_read_b128 v[172:175], v130 offset:35840
	ds_read_b128 v[180:183], v130 offset:36864
	ds_read_b128 v[184:187], v130 offset:37888
	ds_read_b128 v[188:191], v130 offset:38912
	ds_read_b128 v[192:195], v130 offset:39936
	v_add_u32_e32 v208, 0x1c000, v133
	ds_read_b128 v[196:199], v208
	ds_read_b128 v[200:203], v208 offset:1024
	ds_read_b128 v[204:207], v208 offset:2048
	ds_read_b128 v[208:211], v208 offset:3072
	s_add_u32 s24, s18, s6
	s_addc_u32 s25, s19, s7
	s_add_u32 s24, s24, 0x100
	s_addc_u32 s25, s25, 0
	s_add_i32 s23, s15, 0x4000
	s_mov_b32 m0, s23
	s_nop 0
	global_load_lds_dwordx4 v132, s[24:25]
	s_add_i32 s23, s15, 0x6000
	s_mov_b32 m0, s23
	s_nop 0
	global_load_lds_dwordx4 v131, s[24:25]
	s_waitcnt vmcnt(8) lgkmcnt(0)
	s_barrier
	s_setprio 1
	v_mfma_f32_16x16x32_bf16 v[126:129], v[158:161], v[142:145], v[126:129]
	v_mfma_f32_16x16x32_bf16 v[122:125], v[158:161], v[150:153], v[122:125]
	v_mfma_f32_16x16x32_bf16 v[114:117], v[168:171], v[150:153], v[114:117]
	v_mfma_f32_16x16x32_bf16 v[118:121], v[168:171], v[142:145], v[118:121]
	v_mfma_f32_16x16x32_bf16 v[110:113], v[180:183], v[142:145], v[110:113]
	v_mfma_f32_16x16x32_bf16 v[106:109], v[180:183], v[150:153], v[106:109]
	v_mfma_f32_16x16x32_bf16 v[98:101], v[188:191], v[150:153], v[98:101]
	v_mfma_f32_16x16x32_bf16 v[102:105], v[188:191], v[142:145], v[102:105]
	v_mfma_f32_16x16x32_bf16 v[126:129], v[164:167], v[146:149], v[126:129]
	v_mfma_f32_16x16x32_bf16 v[122:125], v[164:167], v[154:157], v[122:125]
	v_mfma_f32_16x16x32_bf16 v[114:117], v[172:175], v[154:157], v[114:117]
	v_mfma_f32_16x16x32_bf16 v[118:121], v[172:175], v[146:149], v[118:121]
	v_mfma_f32_16x16x32_bf16 v[110:113], v[184:187], v[146:149], v[110:113]
	v_mfma_f32_16x16x32_bf16 v[106:109], v[184:187], v[154:157], v[106:109]
	v_mfma_f32_16x16x32_bf16 v[98:101], v[192:195], v[154:157], v[98:101]
	v_mfma_f32_16x16x32_bf16 v[102:105], v[192:195], v[146:149], v[102:105]
	v_mfma_f32_16x16x32_bf16 v[94:97], v[158:161], v[196:199], v[94:97]
	v_mfma_f32_16x16x32_bf16 v[90:93], v[158:161], v[204:207], v[90:93]
	v_mfma_f32_16x16x32_bf16 v[82:85], v[168:171], v[204:207], v[82:85]
	v_mfma_f32_16x16x32_bf16 v[86:89], v[168:171], v[196:199], v[86:89]
	v_mfma_f32_16x16x32_bf16 v[78:81], v[180:183], v[196:199], v[78:81]
	v_mfma_f32_16x16x32_bf16 v[74:77], v[180:183], v[204:207], v[74:77]
	v_mfma_f32_16x16x32_bf16 v[66:69], v[188:191], v[204:207], v[66:69]
	v_mfma_f32_16x16x32_bf16 v[70:73], v[188:191], v[196:199], v[70:73]
	v_mfma_f32_16x16x32_bf16 v[94:97], v[164:167], v[200:203], v[94:97]
	v_mfma_f32_16x16x32_bf16 v[90:93], v[164:167], v[208:211], v[90:93]
	v_mfma_f32_16x16x32_bf16 v[82:85], v[172:175], v[208:211], v[82:85]
	v_mfma_f32_16x16x32_bf16 v[86:89], v[172:175], v[200:203], v[86:89]
	v_mfma_f32_16x16x32_bf16 v[78:81], v[184:187], v[200:203], v[78:81]
	v_mfma_f32_16x16x32_bf16 v[74:77], v[184:187], v[208:211], v[74:77]
	v_mfma_f32_16x16x32_bf16 v[66:69], v[192:195], v[208:211], v[66:69]
	v_mfma_f32_16x16x32_bf16 v[70:73], v[192:195], v[200:203], v[70:73]
	s_setprio 0
	s_barrier
	ds_read_b128 v[158:161], v130 offset:49152
	ds_read_b128 v[164:167], v130 offset:50176
	ds_read_b128 v[168:171], v130 offset:51200
	ds_read_b128 v[172:175], v130 offset:52224
	ds_read_b128 v[180:183], v130 offset:53248
	ds_read_b128 v[184:187], v130 offset:54272
	ds_read_b128 v[188:191], v130 offset:55296
	ds_read_b128 v[192:195], v130 offset:56320
	s_add_u32 s24, s3, s6
	s_addc_u32 s25, s10, s7
	s_add_u32 s24, s24, 0x180
	s_addc_u32 s25, s25, 0
	s_add_i32 s23, s15, 0x18000
	s_mov_b32 m0, s23
	s_nop 0
	global_load_lds_dwordx4 v132, s[24:25]
	s_add_i32 s23, s15, 0x1a000
	s_mov_b32 m0, s23
	s_nop 0
	global_load_lds_dwordx4 v131, s[24:25]
	s_add_u32 s24, s8, s6
	s_addc_u32 s25, s9, s7
	s_add_u32 s24, s24, 0x180
	s_addc_u32 s25, s25, 0
	s_add_i32 s23, s15, 0x8000
	s_mov_b32 m0, s23
	s_nop 0
	global_load_lds_dwordx4 v132, s[24:25]
	s_add_i32 s23, s15, 0xa000
	s_mov_b32 m0, s23
	s_nop 0
	global_load_lds_dwordx4 v131, s[24:25]
	s_add_u32 s24, s13, s6
	s_addc_u32 s25, s14, s7
	s_add_u32 s24, s24, 0x180
	s_addc_u32 s25, s25, 0
	s_add_i32 s23, s15, 0x1c000
	s_mov_b32 m0, s23
	s_nop 0
	global_load_lds_dwordx4 v132, s[24:25]
	s_add_i32 s23, s15, 0x1e000
	s_mov_b32 m0, s23
	s_nop 0
	global_load_lds_dwordx4 v131, s[24:25]
	s_waitcnt vmcnt(8) lgkmcnt(0)
	s_barrier
	s_setprio 1
	v_mfma_f32_16x16x32_bf16 v[62:65], v[158:161], v[142:145], v[62:65]
	v_mfma_f32_16x16x32_bf16 v[58:61], v[158:161], v[150:153], v[58:61]
	v_mfma_f32_16x16x32_bf16 v[50:53], v[168:171], v[150:153], v[50:53]
	v_mfma_f32_16x16x32_bf16 v[54:57], v[168:171], v[142:145], v[54:57]
	v_mfma_f32_16x16x32_bf16 v[46:49], v[180:183], v[142:145], v[46:49]
	v_mfma_f32_16x16x32_bf16 v[42:45], v[180:183], v[150:153], v[42:45]
	v_mfma_f32_16x16x32_bf16 v[34:37], v[188:191], v[150:153], v[34:37]
	v_mfma_f32_16x16x32_bf16 v[38:41], v[188:191], v[142:145], v[38:41]
	v_mfma_f32_16x16x32_bf16 v[62:65], v[164:167], v[146:149], v[62:65]
	v_mfma_f32_16x16x32_bf16 v[58:61], v[164:167], v[154:157], v[58:61]
	v_mfma_f32_16x16x32_bf16 v[50:53], v[172:175], v[154:157], v[50:53]
	v_mfma_f32_16x16x32_bf16 v[54:57], v[172:175], v[146:149], v[54:57]
	v_mfma_f32_16x16x32_bf16 v[46:49], v[184:187], v[146:149], v[46:49]
	v_mfma_f32_16x16x32_bf16 v[42:45], v[184:187], v[154:157], v[42:45]
	v_mfma_f32_16x16x32_bf16 v[34:37], v[192:195], v[154:157], v[34:37]
	v_mfma_f32_16x16x32_bf16 v[38:41], v[192:195], v[146:149], v[38:41]
	v_mfma_f32_16x16x32_bf16 v[30:33], v[158:161], v[196:199], v[30:33]
	v_mfma_f32_16x16x32_bf16 v[26:29], v[158:161], v[204:207], v[26:29]
	v_mfma_f32_16x16x32_bf16 v[18:21], v[168:171], v[204:207], v[18:21]
	v_mfma_f32_16x16x32_bf16 v[22:25], v[168:171], v[196:199], v[22:25]
	v_mfma_f32_16x16x32_bf16 v[14:17], v[180:183], v[196:199], v[14:17]
	v_mfma_f32_16x16x32_bf16 v[10:13], v[180:183], v[204:207], v[10:13]
	v_mfma_f32_16x16x32_bf16 v[2:5], v[188:191], v[204:207], v[2:5]
	v_mfma_f32_16x16x32_bf16 v[6:9], v[188:191], v[196:199], v[6:9]
	v_mfma_f32_16x16x32_bf16 v[30:33], v[164:167], v[200:203], v[30:33]
	v_mfma_f32_16x16x32_bf16 v[26:29], v[164:167], v[208:211], v[26:29]
	v_mfma_f32_16x16x32_bf16 v[18:21], v[172:175], v[208:211], v[18:21]
	v_mfma_f32_16x16x32_bf16 v[22:25], v[172:175], v[200:203], v[22:25]
	v_mfma_f32_16x16x32_bf16 v[14:17], v[184:187], v[200:203], v[14:17]
	v_mfma_f32_16x16x32_bf16 v[10:13], v[184:187], v[208:211], v[10:13]
	v_mfma_f32_16x16x32_bf16 v[2:5], v[192:195], v[208:211], v[2:5]
	v_mfma_f32_16x16x32_bf16 v[6:9], v[192:195], v[200:203], v[6:9]
	s_setprio 0
	s_barrier
	s_add_i32 s20, s20, 2
	s_add_u32 s6, s6, 0x100
	s_addc_u32 s7, s7, 0
	s_cmp_lt_u32 s20, 12
	s_cbranch_scc1 .Lk_ret_in

; #define WAIT_V(n) asm volatile("s_waitcnt vmcnt(" #n ")" ::: "memory")
; #define WAIT_L(n) asm volatile("s_waitcnt lgkmcnt(" #n ")" ::: "memory")
; #define BAR __builtin_amdgcn_s_barrier()
; #define SCHED __builtin_amdgcn_sched_barrier(0)
; template <bool HS>
; __device__ __forceinline__ void gemm_tile8(const u16* __restrict__ Ap, const u16* __restrict__ Bp, int K,
;                                            f32x4 (&acc)[2][2][4][2], char* shm, const int tid, const float* hsr = nullptr) {
;   const int wid = tid >> 6, lane = tid & 63, wr = wid >> 2, wc = wid & 3, fr = lane & 15, fq = lane >> 4;
;   int r0, c0, r1, c1;
;   stage_rc(tid * 16, r0, c0);
;   stage_rc(tid * 16 + 8192, r1, c1);
;   const unsigned off0 = (unsigned)(r0 * K + c0) * 2u, off1 = (unsigned)(r1 * K + c1) * 2u;
;   const int wvoff = __builtin_amdgcn_readfirstlane(tid >> 6) * 1024;
;   const u16* A1 = Ap + (size_t)128 * K;
;   const u16* B1p = Bp + (size_t)128 * K;
; #pragma unroll
;   for (int a = 0; a < 2; ++a)
; #pragma unroll
;     for (int b = 0; b < 2; ++b)
; #pragma unroll
;       for (int m = 0; m < 4; ++m)
; #pragma unroll
;         for (int n = 0; n < 2; ++n) acc[a][b][m][n] = f32x4{0.f, 0.f, 0.f, 0.f};
;   const int abase = lds_byte(wr * 64 + fr, fq * 8), bbase = lds_byte(wc * 32 + fr, fq * 8);
;   bf16x8 At[4][2], B0[2][2], B1[2][2];
;   const unsigned lds0 = (unsigned)(size_t)(__attribute__((address_space(3))) char*)shm + (unsigned)wvoff;
;     ...
;   const int nt = K / BK;
;   WAIT_V(0);
;   if (wr == 1) BAR;
;   BAR;
;   BAR;
;   for (int t = 0; t < nt - 2; t += 2) {
;     if constexpr (HS) {
;       if (t > 0 && (t & 7) == 0) {
;         const float* rt = hsr + ((t >> 3) - 1) * 256 + wr * 64 + fq * 4;
; #pragma unroll
;         for (int ai = 0; ai < 2; ++ai)
; #pragma unroll
;           for (int m = 0; m < 4; ++m) {
;             const f32x4 q4 = *(const f32x4*)(rt + ai * 128 + m * 16);
; #pragma unroll
;             for (int bj = 0; bj < 2; ++bj)
; #pragma unroll
;               for (int n = 0; n < 2; ++n) acc[ai][bj][m][n] *= q4;
;             SCHED;
;           }
;       }
;     }
;     LDB8(B0, 0, 0); SCHED; LDA8(0, 0); STG_A(1, 1, t + 1);
;     WAIT_L(8); BAR; WAIT_L(0); MMA8(0, 0, B0); BAR; SCHED;
;     LDB8(B1, 0, 1); STG_B(0, 0, t + 2);
;     BAR; WAIT_L(0); MMA8(0, 1, B1); BAR;
.LBB0_650:
	s_or_b64 exec, exec, s[0:1]
	v_bfe_i32 v6, v0, 27, 1
	v_lshlrev_b32_e32 v4, 4, v0
	v_lshrrev_b32_e32 v6, 22, v6
	v_add_u32_e32 v6, v4, v6
	v_and_b32_e32 v6, 0xfffffc00, v6
	v_ashrrev_i32_e32 v5, 31, v0
	v_sub_u32_e32 v6, v4, v6
	v_lshrrev_b32_e32 v5, 26, v5
	v_lshrrev_b32_e32 v7, 4, v6
	v_add_u32_e32 v5, v0, v5
	v_bitop3_b32 v7, v7, v6, 32 bitop3:0x6c
	v_ashrrev_i32_e32 v6, 31, v6
	v_ashrrev_i32_e32 v5, 6, v5
	v_lshrrev_b32_e32 v6, 26, v6
	v_lshlrev_b32_e32 v8, 3, v5
	v_add_u32_e32 v6, v7, v6
	v_and_b32_e32 v8, 0xfffff0, v8
	v_ashrrev_i32_e32 v6, 6, v6
	v_add_u32_e32 v8, v6, v8
	v_mul_i32_i24_e32 v6, 64, v6
	v_add_u32_e32 v4, 0x2000, v4
	v_sub_u32_e32 v6, v7, v6
	v_ashrrev_i32_e32 v7, 31, v4
	v_lshrrev_b32_e32 v7, 22, v7
	v_add_u32_e32 v7, v4, v7
	v_ashrrev_i32_e32 v7, 10, v7
	v_mul_i32_i24_e32 v9, 0x400, v7
	v_sub_u32_e32 v4, v4, v9
	v_lshrrev_b32_e32 v9, 4, v4
	s_ashr_i32 s5, s4, 31
	s_mul_i32 s1, s4, 0x1600
	v_bitop3_b32 v4, v9, v4, 32 bitop3:0x6c
	s_mul_hi_i32 s0, s4, 0x1600
	s_add_u32 s3, s90, s1
	v_ashrrev_i32_e32 v10, 31, v4
	s_addc_u32 s8, s91, s0
	s_mul_i32 s0, s10, 0x160000
	v_lshrrev_b32_e32 v10, 26, v10
	s_ashr_i32 s1, s0, 31
	v_lshlrev_b32_e32 v9, 3, v7
	v_add_u32_e32 v10, v4, v10
	v_lshl_add_u64 v[130:131], v[146:147], 0, s[0:1]
	v_and_b32_e32 v9, 0xfffff0, v9
	v_lshrrev_b32_e32 v11, 6, v10
	v_and_b32_e32 v10, 0xc0, v10
	s_movk_i32 s0, 0xb00
	v_lshlrev_b32_e32 v5, 5, v5
	v_add_u32_e32 v9, v11, v9
	v_sub_u32_e32 v4, v4, v10
	v_mul_lo_u32 v8, v8, s0
	v_lshlrev_b32_e32 v7, 5, v7
	v_ashrrev_i16_sdwa v4, v178, sext(v4) dst_sel:DWORD dst_unused:UNUSED_PAD src0_sel:DWORD src1_sel:BYTE_0
	v_and_or_b32 v5, v5, 32, v8
	v_mul_lo_u32 v8, v9, s0
	v_ashrrev_i16_sdwa v6, v178, sext(v6) dst_sel:DWORD dst_unused:UNUSED_PAD src0_sel:DWORD src1_sel:BYTE_0
	v_bfe_i32 v4, v4, 0, 16
	v_and_or_b32 v7, v7, 32, v8
	v_bfe_i32 v6, v6, 0, 16
	s_add_u32 s9, s3, 0xb0000
	v_and_b32_e32 v8, 15, v0
	v_add_lshl_u32 v135, v7, v4, 1
	v_lshlrev_b32_e32 v7, 2, v0
	s_addc_u32 s11, s8, 0
	v_add_lshl_u32 v136, v5, v6, 1
	s_lshl_b32 s12, s12, 10
	s_mov_b64 s[0:1], 0xb0000
	v_and_b32_e32 v4, 48, v0
	v_lshlrev_b32_e32 v5, 6, v8
	v_and_b32_e32 v7, 32, v7
	v_lshl_add_u64 v[132:133], v[130:131], 0, s[0:1]
	v_or_b32_e32 v6, v5, v4
	v_lshlrev_b32_e32 v3, 13, v3
	v_bitop3_b32 v4, v5, v7, v4 bitop3:0x36
	v_lshlrev_b32_e32 v2, 12, v2
	s_movk_i32 s0, 0x3000
	s_add_i32 s13, s12, 0
	v_bitop3_b32 v3, v6, v3, v7 bitop3:0xde
	v_and_or_b32 v137, v2, s0, v4
	s_add_u32 s14, s3, 0xb0100
	v_mov_b32_e32 v2, 0
	s_addc_u32 s15, s8, 0
	s_mov_b32 s16, -2
	s_mov_b64 s[0:1], 0
	v_add_u32_e32 v134, 0, v3
	s_waitcnt lgkmcnt(0)
	v_readfirstlane_b32 s22, v130
	v_readfirstlane_b32 s23, v131
	v_readfirstlane_b32 s18, v132
	v_readfirstlane_b32 s19, v133
	s_barrier
	s_barrier
	v_add_u32_e32 v164, 0x10000, v137
	ds_read_b128 v[138:141], v164
	ds_read_b128 v[142:145], v164 offset:1024
	ds_read_b128 v[156:159], v164 offset:2048
	ds_read_b128 v[164:167], v164 offset:3072
	ds_read_b128 v[168:171], v134
	ds_read_b128 v[172:175], v134 offset:1024
	ds_read_b128 v[180:183], v134 offset:2048
	ds_read_b128 v[184:187], v134 offset:3072
	ds_read_b128 v[188:191], v134 offset:4096
	ds_read_b128 v[192:195], v134 offset:5120
	ds_read_b128 v[196:199], v134 offset:6144
	ds_read_b128 v[200:203], v134 offset:7168
	v_add_u32_e32 v220, 0x14000, v137
	ds_read_b128 v[204:207], v220
	ds_read_b128 v[208:211], v220 offset:1024
	ds_read_b128 v[212:215], v220 offset:2048
	ds_read_b128 v[220:223], v220 offset:3072
	s_add_u32 s20, s9, s0
	s_addc_u32 s21, s11, s1
	s_add_u32 s20, s20, 0x80
	s_addc_u32 s21, s21, 0
	s_add_i32 s17, s13, 0xc000
	s_mov_b32 m0, s17
	s_nop 0
	global_load_lds_dwordx4 v136, s[20:21]
	s_add_i32 s17, s13, 0xe000
	s_mov_b32 m0, s17
	s_nop 0
	global_load_lds_dwordx4 v135, s[20:21]
	s_waitcnt vmcnt(8) lgkmcnt(0)
	s_barrier
	s_setprio 1
	v_mfma_f32_16x16x32_bf16 v[126:129], v[168:171], v[138:141], 0
	v_mfma_f32_16x16x32_bf16 v[122:125], v[168:171], v[156:159], 0
	v_mfma_f32_16x16x32_bf16 v[114:117], v[180:183], v[156:159], 0
	v_mfma_f32_16x16x32_bf16 v[118:121], v[180:183], v[138:141], 0
	v_mfma_f32_16x16x32_bf16 v[110:113], v[188:191], v[138:141], 0
	v_mfma_f32_16x16x32_bf16 v[106:109], v[188:191], v[156:159], 0
	v_mfma_f32_16x16x32_bf16 v[98:101], v[196:199], v[156:159], 0
	v_mfma_f32_16x16x32_bf16 v[102:105], v[196:199], v[138:141], 0
	v_mfma_f32_16x16x32_bf16 v[126:129], v[172:175], v[142:145], v[126:129]
	v_mfma_f32_16x16x32_bf16 v[122:125], v[172:175], v[164:167], v[122:125]
	v_mfma_f32_16x16x32_bf16 v[114:117], v[184:187], v[164:167], v[114:117]
	v_mfma_f32_16x16x32_bf16 v[118:121], v[184:187], v[142:145], v[118:121]
	v_mfma_f32_16x16x32_bf16 v[110:113], v[192:195], v[142:145], v[110:113]
	v_mfma_f32_16x16x32_bf16 v[106:109], v[192:195], v[164:167], v[106:109]
	v_mfma_f32_16x16x32_bf16 v[98:101], v[200:203], v[164:167], v[98:101]
	v_mfma_f32_16x16x32_bf16 v[102:105], v[200:203], v[142:145], v[102:105]
	v_mfma_f32_16x16x32_bf16 v[94:97], v[168:171], v[204:207], 0
	v_mfma_f32_16x16x32_bf16 v[90:93], v[168:171], v[212:215], 0
	v_mfma_f32_16x16x32_bf16 v[82:85], v[180:183], v[212:215], 0
	v_mfma_f32_16x16x32_bf16 v[86:89], v[180:183], v[204:207], 0
	v_mfma_f32_16x16x32_bf16 v[78:81], v[188:191], v[204:207], 0
	v_mfma_f32_16x16x32_bf16 v[74:77], v[188:191], v[212:215], 0
	v_mfma_f32_16x16x32_bf16 v[66:69], v[196:199], v[212:215], 0
	v_mfma_f32_16x16x32_bf16 v[70:73], v[196:199], v[204:207], 0
	v_mfma_f32_16x16x32_bf16 v[94:97], v[172:175], v[208:211], v[94:97]
	v_mfma_f32_16x16x32_bf16 v[90:93], v[172:175], v[220:223], v[90:93]
	v_mfma_f32_16x16x32_bf16 v[82:85], v[184:187], v[220:223], v[82:85]
	v_mfma_f32_16x16x32_bf16 v[86:89], v[184:187], v[208:211], v[86:89]
	v_mfma_f32_16x16x32_bf16 v[78:81], v[192:195], v[208:211], v[78:81]
	v_mfma_f32_16x16x32_bf16 v[74:77], v[192:195], v[220:223], v[74:77]
	v_mfma_f32_16x16x32_bf16 v[66:69], v[200:203], v[220:223], v[66:69]
	v_mfma_f32_16x16x32_bf16 v[70:73], v[200:203], v[208:211], v[70:73]
	s_setprio 0
	s_barrier
; #define WAIT_V(n) asm volatile("s_waitcnt vmcnt(" #n ")" ::: "memory")
; #define WAIT_L(n) asm volatile("s_waitcnt lgkmcnt(" #n ")" ::: "memory")
; #define BAR __builtin_amdgcn_s_barrier()
; #define SCHED __builtin_amdgcn_sched_barrier(0)
; #define STG_A(b, h, kt) stage_half_s(lds0 + ((b) * 2 + (h)) * HT_B, ((h) ? A1 : Ap) + (kt) * BK, off0, off1)
; #define STG_B(b, h, kt) stage_half_s(lds0 + (4 + (b) * 2 + (h)) * HT_B, ((h) ? B1p : Bp) + (kt) * BK, off0, off1)
; #define STG_A(b, h, kt) stage_half_s(lds0 + ((b) * 2 + (h)) * HT_B, ((h) ? A1 : Ap) + (kt) * BK, off0, off1)
; #define STG_B(b, h, kt) stage_half_s(lds0 + (4 + (b) * 2 + (h)) * HT_B, ((h) ? B1p : Bp) + (kt) * BK, off0, off1)
; #define LDA8(b, h) _Pragma("unroll") for (int m = 0; m < 4; ++m) _Pragma("unroll") for (int k = 0; k < 2; ++k) \
;     At[m][k] = *(const bf16x8*)(SA_(shm, b, h) + abase + (m * 2 + k) * 1024)
; #define LDB8(dst, b, h) _Pragma("unroll") for (int n = 0; n < 2; ++n) _Pragma("unroll") for (int k = 0; k < 2; ++k) \
;     dst[n][k] = *(const bf16x8*)(SB_(shm, b, h) + bbase + (n * 2 + k) * 1024)
; template <bool HS>
; __device__ __forceinline__ void gemm_tile8(const u16* __restrict__ Ap, const u16* __restrict__ Bp, int K,
;                                            f32x4 (&acc)[2][2][4][2], char* shm, const int tid, const float* hsr = nullptr) {
;     ...
;     LDB8(B0, 0, 0); SCHED; LDA8(0, 0); STG_A(1, 1, t + 1);
;     WAIT_L(8); BAR; WAIT_L(0); MMA8(0, 0, B0); BAR; SCHED;
;     LDB8(B1, 0, 1); STG_B(0, 0, t + 2);
;     BAR; WAIT_L(0); MMA8(0, 1, B1); BAR;
;     LDA8(0, 1); STG_A(0, 0, t + 2);
;     BAR; WAIT_L(0); MMA8(1, 0, B0); BAR; SCHED;
;     STG_B(0, 1, t + 2);
;     WAIT_V(6); BAR; MMA8(1, 1, B1); BAR;
;     LDB8(B0, 1, 0); SCHED; LDA8(1, 0); STG_A(0, 1, t + 2);
;     WAIT_L(8); BAR; WAIT_L(0); MMA8(0, 0, B0); BAR; SCHED;
;     LDB8(B1, 1, 1); STG_B(1, 0, t + 3);
;     BAR; WAIT_L(0); MMA8(0, 1, B1); BAR;
;     LDA8(1, 1); STG_A(1, 0, t + 3);
;     BAR; WAIT_L(0); MMA8(1, 0, B0); BAR; SCHED;
;     STG_B(1, 1, t + 3);
;     WAIT_V(6); BAR; MMA8(1, 1, B1); BAR;
	ds_read_b128 v[168:171], v134 offset:16384
	ds_read_b128 v[172:175], v134 offset:17408
	ds_read_b128 v[180:183], v134 offset:18432
	ds_read_b128 v[184:187], v134 offset:19456
	ds_read_b128 v[188:191], v134 offset:20480
	ds_read_b128 v[192:195], v134 offset:21504
	ds_read_b128 v[196:199], v134 offset:22528
	ds_read_b128 v[200:203], v134 offset:23552
	s_add_u32 s20, s22, s0
	s_addc_u32 s21, s23, s1
	s_add_u32 s20, s20, 0x100
	s_addc_u32 s21, s21, 0
	s_add_i32 s17, s13, 0x10000
	s_mov_b32 m0, s17
	s_nop 0
	global_load_lds_dwordx4 v136, s[20:21]
	s_add_i32 s17, s13, 0x12000
	s_mov_b32 m0, s17
	s_nop 0
	global_load_lds_dwordx4 v135, s[20:21]
	s_add_u32 s20, s3, s0
	s_addc_u32 s21, s8, s1
	s_add_u32 s20, s20, 0x100
	s_addc_u32 s21, s21, 0
	s_mov_b32 m0, s13
	s_nop 0
	global_load_lds_dwordx4 v136, s[20:21]
	s_add_i32 s17, s13, 0x2000
	s_mov_b32 m0, s17
	s_nop 0
	global_load_lds_dwordx4 v135, s[20:21]
	s_add_u32 s20, s18, s0
	s_addc_u32 s21, s19, s1
	s_add_u32 s20, s20, 0x100
	s_addc_u32 s21, s21, 0
	s_add_i32 s17, s13, 0x14000
	s_mov_b32 m0, s17
	s_nop 0
	global_load_lds_dwordx4 v136, s[20:21]
	s_add_i32 s17, s13, 0x16000
	s_mov_b32 m0, s17
	s_nop 0
	global_load_lds_dwordx4 v135, s[20:21]
	s_waitcnt vmcnt(8) lgkmcnt(0)
	s_barrier
	s_setprio 1
	v_mfma_f32_16x16x32_bf16 v[62:65], v[168:171], v[138:141], 0
	v_mfma_f32_16x16x32_bf16 v[58:61], v[168:171], v[156:159], 0
	v_mfma_f32_16x16x32_bf16 v[50:53], v[180:183], v[156:159], 0
	v_mfma_f32_16x16x32_bf16 v[54:57], v[180:183], v[138:141], 0
	v_mfma_f32_16x16x32_bf16 v[46:49], v[188:191], v[138:141], 0
	v_mfma_f32_16x16x32_bf16 v[42:45], v[188:191], v[156:159], 0
	v_mfma_f32_16x16x32_bf16 v[34:37], v[196:199], v[156:159], 0
	v_mfma_f32_16x16x32_bf16 v[38:41], v[196:199], v[138:141], 0
	v_mfma_f32_16x16x32_bf16 v[62:65], v[172:175], v[142:145], v[62:65]
	v_mfma_f32_16x16x32_bf16 v[58:61], v[172:175], v[164:167], v[58:61]
	v_mfma_f32_16x16x32_bf16 v[50:53], v[184:187], v[164:167], v[50:53]
	v_mfma_f32_16x16x32_bf16 v[54:57], v[184:187], v[142:145], v[54:57]
	v_mfma_f32_16x16x32_bf16 v[46:49], v[192:195], v[142:145], v[46:49]
	v_mfma_f32_16x16x32_bf16 v[42:45], v[192:195], v[164:167], v[42:45]
	v_mfma_f32_16x16x32_bf16 v[34:37], v[200:203], v[164:167], v[34:37]
	v_mfma_f32_16x16x32_bf16 v[38:41], v[200:203], v[142:145], v[38:41]
	v_mfma_f32_16x16x32_bf16 v[30:33], v[168:171], v[204:207], 0
	v_mfma_f32_16x16x32_bf16 v[26:29], v[168:171], v[212:215], 0
	v_mfma_f32_16x16x32_bf16 v[18:21], v[180:183], v[212:215], 0
	v_mfma_f32_16x16x32_bf16 v[22:25], v[180:183], v[204:207], 0
	v_mfma_f32_16x16x32_bf16 v[14:17], v[188:191], v[204:207], 0
	v_mfma_f32_16x16x32_bf16 v[10:13], v[188:191], v[212:215], 0
	v_mfma_f32_16x16x32_bf16 v[2:5], v[196:199], v[212:215], 0
	v_mfma_f32_16x16x32_bf16 v[6:9], v[196:199], v[204:207], 0
	v_mfma_f32_16x16x32_bf16 v[30:33], v[172:175], v[208:211], v[30:33]
	v_mfma_f32_16x16x32_bf16 v[26:29], v[172:175], v[220:223], v[26:29]
	v_mfma_f32_16x16x32_bf16 v[18:21], v[184:187], v[220:223], v[18:21]
	v_mfma_f32_16x16x32_bf16 v[22:25], v[184:187], v[208:211], v[22:25]
	v_mfma_f32_16x16x32_bf16 v[14:17], v[192:195], v[208:211], v[14:17]
	v_mfma_f32_16x16x32_bf16 v[10:13], v[192:195], v[220:223], v[10:13]
	v_mfma_f32_16x16x32_bf16 v[2:5], v[200:203], v[220:223], v[2:5]
	v_mfma_f32_16x16x32_bf16 v[6:9], v[200:203], v[208:211], v[6:9]
	s_setprio 0
	s_barrier
	v_add_u32_e32 v164, 0x18000, v137
	ds_read_b128 v[138:141], v164
	ds_read_b128 v[142:145], v164 offset:1024
	ds_read_b128 v[156:159], v164 offset:2048
	ds_read_b128 v[164:167], v164 offset:3072
	ds_read_b128 v[168:171], v134 offset:32768
	ds_read_b128 v[172:175], v134 offset:33792
	ds_read_b128 v[180:183], v134 offset:34816
	ds_read_b128 v[184:187], v134 offset:35840
	ds_read_b128 v[188:191], v134 offset:36864
	ds_read_b128 v[192:195], v134 offset:37888
	ds_read_b128 v[196:199], v134 offset:38912
	ds_read_b128 v[200:203], v134 offset:39936
	v_add_u32_e32 v220, 0x1c000, v137
	ds_read_b128 v[204:207], v220
	ds_read_b128 v[208:211], v220 offset:1024
	ds_read_b128 v[212:215], v220 offset:2048
	ds_read_b128 v[220:223], v220 offset:3072
	s_add_u32 s20, s9, s0
	s_addc_u32 s21, s11, s1
	s_add_u32 s20, s20, 0x100
	s_addc_u32 s21, s21, 0
	s_add_i32 s17, s13, 0x4000
	s_mov_b32 m0, s17
	s_nop 0
	global_load_lds_dwordx4 v136, s[20:21]
	s_add_i32 s17, s13, 0x6000
	s_mov_b32 m0, s17
	s_nop 0
	global_load_lds_dwordx4 v135, s[20:21]
	s_waitcnt vmcnt(8) lgkmcnt(0)
	s_barrier
	s_setprio 1
	v_mfma_f32_16x16x32_bf16 v[126:129], v[168:171], v[138:141], v[126:129]
	v_mfma_f32_16x16x32_bf16 v[122:125], v[168:171], v[156:159], v[122:125]
	v_mfma_f32_16x16x32_bf16 v[114:117], v[180:183], v[156:159], v[114:117]
	v_mfma_f32_16x16x32_bf16 v[118:121], v[180:183], v[138:141], v[118:121]
	v_mfma_f32_16x16x32_bf16 v[110:113], v[188:191], v[138:141], v[110:113]
	v_mfma_f32_16x16x32_bf16 v[106:109], v[188:191], v[156:159], v[106:109]
	v_mfma_f32_16x16x32_bf16 v[98:101], v[196:199], v[156:159], v[98:101]
	v_mfma_f32_16x16x32_bf16 v[102:105], v[196:199], v[138:141], v[102:105]
	v_mfma_f32_16x16x32_bf16 v[126:129], v[172:175], v[142:145], v[126:129]
	v_mfma_f32_16x16x32_bf16 v[122:125], v[172:175], v[164:167], v[122:125]
	v_mfma_f32_16x16x32_bf16 v[114:117], v[184:187], v[164:167], v[114:117]
	v_mfma_f32_16x16x32_bf16 v[118:121], v[184:187], v[142:145], v[118:121]
	v_mfma_f32_16x16x32_bf16 v[110:113], v[192:195], v[142:145], v[110:113]
	v_mfma_f32_16x16x32_bf16 v[106:109], v[192:195], v[164:167], v[106:109]
	v_mfma_f32_16x16x32_bf16 v[98:101], v[200:203], v[164:167], v[98:101]
	v_mfma_f32_16x16x32_bf16 v[102:105], v[200:203], v[142:145], v[102:105]
	v_mfma_f32_16x16x32_bf16 v[94:97], v[168:171], v[204:207], v[94:97]
	v_mfma_f32_16x16x32_bf16 v[90:93], v[168:171], v[212:215], v[90:93]
	v_mfma_f32_16x16x32_bf16 v[82:85], v[180:183], v[212:215], v[82:85]
	v_mfma_f32_16x16x32_bf16 v[86:89], v[180:183], v[204:207], v[86:89]
	v_mfma_f32_16x16x32_bf16 v[78:81], v[188:191], v[204:207], v[78:81]
	v_mfma_f32_16x16x32_bf16 v[74:77], v[188:191], v[212:215], v[74:77]
	v_mfma_f32_16x16x32_bf16 v[66:69], v[196:199], v[212:215], v[66:69]
	v_mfma_f32_16x16x32_bf16 v[70:73], v[196:199], v[204:207], v[70:73]
	v_mfma_f32_16x16x32_bf16 v[94:97], v[172:175], v[208:211], v[94:97]
	v_mfma_f32_16x16x32_bf16 v[90:93], v[172:175], v[220:223], v[90:93]
	v_mfma_f32_16x16x32_bf16 v[82:85], v[184:187], v[220:223], v[82:85]
	v_mfma_f32_16x16x32_bf16 v[86:89], v[184:187], v[208:211], v[86:89]
	v_mfma_f32_16x16x32_bf16 v[78:81], v[192:195], v[208:211], v[78:81]
	v_mfma_f32_16x16x32_bf16 v[74:77], v[192:195], v[220:223], v[74:77]
	v_mfma_f32_16x16x32_bf16 v[66:69], v[200:203], v[220:223], v[66:69]
	v_mfma_f32_16x16x32_bf16 v[70:73], v[200:203], v[208:211], v[70:73]
	s_setprio 0
	s_barrier
; #define WAIT_V(n) asm volatile("s_waitcnt vmcnt(" #n ")" ::: "memory")
; #define WAIT_L(n) asm volatile("s_waitcnt lgkmcnt(" #n ")" ::: "memory")
; #define BAR __builtin_amdgcn_s_barrier()
; #define SCHED __builtin_amdgcn_sched_barrier(0)
; #define STG_A(b, h, kt) stage_half_s(lds0 + ((b) * 2 + (h)) * HT_B, ((h) ? A1 : Ap) + (kt) * BK, off0, off1)
; #define STG_B(b, h, kt) stage_half_s(lds0 + (4 + (b) * 2 + (h)) * HT_B, ((h) ? B1p : Bp) + (kt) * BK, off0, off1)
; #define STG_A(b, h, kt) stage_half_s(lds0 + ((b) * 2 + (h)) * HT_B, ((h) ? A1 : Ap) + (kt) * BK, off0, off1)
; #define STG_B(b, h, kt) stage_half_s(lds0 + (4 + (b) * 2 + (h)) * HT_B, ((h) ? B1p : Bp) + (kt) * BK, off0, off1)
; #define LDA8(b, h) _Pragma("unroll") for (int m = 0; m < 4; ++m) _Pragma("unroll") for (int k = 0; k < 2; ++k) \
;     At[m][k] = *(const bf16x8*)(SA_(shm, b, h) + abase + (m * 2 + k) * 1024)
; #define LDB8(dst, b, h) _Pragma("unroll") for (int n = 0; n < 2; ++n) _Pragma("unroll") for (int k = 0; k < 2; ++k) \
;     dst[n][k] = *(const bf16x8*)(SB_(shm, b, h) + bbase + (n * 2 + k) * 1024)
; template <bool HS>
; __device__ __forceinline__ void gemm_tile8(const u16* __restrict__ Ap, const u16* __restrict__ Bp, int K,
;                                            f32x4 (&acc)[2][2][4][2], char* shm, const int tid, const float* hsr = nullptr) {
;     ...
;     LDB8(B0, 0, 0); SCHED; LDA8(0, 0); STG_A(1, 1, t + 1);
;     WAIT_L(8); BAR; WAIT_L(0); MMA8(0, 0, B0); BAR; SCHED;
;     LDB8(B1, 0, 1); STG_B(0, 0, t + 2);
;     BAR; WAIT_L(0); MMA8(0, 1, B1); BAR;
;     LDA8(0, 1); STG_A(0, 0, t + 2);
;     BAR; WAIT_L(0); MMA8(1, 0, B0); BAR; SCHED;
;     STG_B(0, 1, t + 2);
;     WAIT_V(6); BAR; MMA8(1, 1, B1); BAR;
;     LDB8(B0, 1, 0); SCHED; LDA8(1, 0); STG_A(0, 1, t + 2);
;     WAIT_L(8); BAR; WAIT_L(0); MMA8(0, 0, B0); BAR; SCHED;
;     LDB8(B1, 1, 1); STG_B(1, 0, t + 3);
;     BAR; WAIT_L(0); MMA8(0, 1, B1); BAR;
;     LDA8(1, 1); STG_A(1, 0, t + 3);
;     BAR; WAIT_L(0); MMA8(1, 0, B0); BAR; SCHED;
;     STG_B(1, 1, t + 3);
;     WAIT_V(6); BAR; MMA8(1, 1, B1); BAR;
	ds_read_b128 v[168:171], v134 offset:49152
	ds_read_b128 v[172:175], v134 offset:50176
	ds_read_b128 v[180:183], v134 offset:51200
	ds_read_b128 v[184:187], v134 offset:52224
	ds_read_b128 v[188:191], v134 offset:53248
	ds_read_b128 v[192:195], v134 offset:54272
	ds_read_b128 v[196:199], v134 offset:55296
	ds_read_b128 v[200:203], v134 offset:56320
	s_add_u32 s20, s22, s0
	s_addc_u32 s21, s23, s1
	s_add_u32 s20, s20, 0x180
	s_addc_u32 s21, s21, 0
	s_add_i32 s17, s13, 0x18000
	s_mov_b32 m0, s17
	s_nop 0
	global_load_lds_dwordx4 v136, s[20:21]
	s_add_i32 s17, s13, 0x1a000
	s_mov_b32 m0, s17
	s_nop 0
	global_load_lds_dwordx4 v135, s[20:21]
	s_add_u32 s20, s3, s0
	s_addc_u32 s21, s8, s1
	s_add_u32 s20, s20, 0x180
	s_addc_u32 s21, s21, 0
	s_add_i32 s17, s13, 0x8000
	s_mov_b32 m0, s17
	s_nop 0
	global_load_lds_dwordx4 v136, s[20:21]
	s_add_i32 s17, s13, 0xa000
	s_mov_b32 m0, s17
	s_nop 0
	global_load_lds_dwordx4 v135, s[20:21]
	s_add_u32 s20, s18, s0
	s_addc_u32 s21, s19, s1
	s_add_u32 s20, s20, 0x180
	s_addc_u32 s21, s21, 0
	s_add_i32 s17, s13, 0x1c000
	s_mov_b32 m0, s17
	s_nop 0
	global_load_lds_dwordx4 v136, s[20:21]
	s_add_i32 s17, s13, 0x1e000
	s_mov_b32 m0, s17
	s_nop 0
	global_load_lds_dwordx4 v135, s[20:21]
	s_waitcnt vmcnt(8) lgkmcnt(0)
	s_barrier
	s_setprio 1
	v_mfma_f32_16x16x32_bf16 v[62:65], v[168:171], v[138:141], v[62:65]
	v_mfma_f32_16x16x32_bf16 v[58:61], v[168:171], v[156:159], v[58:61]
	v_mfma_f32_16x16x32_bf16 v[50:53], v[180:183], v[156:159], v[50:53]
	v_mfma_f32_16x16x32_bf16 v[54:57], v[180:183], v[138:141], v[54:57]
	v_mfma_f32_16x16x32_bf16 v[46:49], v[188:191], v[138:141], v[46:49]
	v_mfma_f32_16x16x32_bf16 v[42:45], v[188:191], v[156:159], v[42:45]
	v_mfma_f32_16x16x32_bf16 v[34:37], v[196:199], v[156:159], v[34:37]
	v_mfma_f32_16x16x32_bf16 v[38:41], v[196:199], v[138:141], v[38:41]
	v_mfma_f32_16x16x32_bf16 v[62:65], v[172:175], v[142:145], v[62:65]
	v_mfma_f32_16x16x32_bf16 v[58:61], v[172:175], v[164:167], v[58:61]
	v_mfma_f32_16x16x32_bf16 v[50:53], v[184:187], v[164:167], v[50:53]
	v_mfma_f32_16x16x32_bf16 v[54:57], v[184:187], v[142:145], v[54:57]
	v_mfma_f32_16x16x32_bf16 v[46:49], v[192:195], v[142:145], v[46:49]
	v_mfma_f32_16x16x32_bf16 v[42:45], v[192:195], v[164:167], v[42:45]
	v_mfma_f32_16x16x32_bf16 v[34:37], v[200:203], v[164:167], v[34:37]
	v_mfma_f32_16x16x32_bf16 v[38:41], v[200:203], v[142:145], v[38:41]
	v_mfma_f32_16x16x32_bf16 v[30:33], v[168:171], v[204:207], v[30:33]
	v_mfma_f32_16x16x32_bf16 v[26:29], v[168:171], v[212:215], v[26:29]
	v_mfma_f32_16x16x32_bf16 v[18:21], v[180:183], v[212:215], v[18:21]
	v_mfma_f32_16x16x32_bf16 v[22:25], v[180:183], v[204:207], v[22:25]
	v_mfma_f32_16x16x32_bf16 v[14:17], v[188:191], v[204:207], v[14:17]
	v_mfma_f32_16x16x32_bf16 v[10:13], v[188:191], v[212:215], v[10:13]
	v_mfma_f32_16x16x32_bf16 v[2:5], v[196:199], v[212:215], v[2:5]
	v_mfma_f32_16x16x32_bf16 v[6:9], v[196:199], v[204:207], v[6:9]
	v_mfma_f32_16x16x32_bf16 v[30:33], v[172:175], v[208:211], v[30:33]
	v_mfma_f32_16x16x32_bf16 v[26:29], v[172:175], v[220:223], v[26:29]
	v_mfma_f32_16x16x32_bf16 v[18:21], v[184:187], v[220:223], v[18:21]
	v_mfma_f32_16x16x32_bf16 v[22:25], v[184:187], v[208:211], v[22:25]
	v_mfma_f32_16x16x32_bf16 v[14:17], v[192:195], v[208:211], v[14:17]
	v_mfma_f32_16x16x32_bf16 v[10:13], v[192:195], v[220:223], v[10:13]
	v_mfma_f32_16x16x32_bf16 v[2:5], v[200:203], v[220:223], v[2:5]
	v_mfma_f32_16x16x32_bf16 v[6:9], v[200:203], v[208:211], v[6:9]
	s_setprio 0
	s_barrier
	s_add_i32 s16, s16, 2
	s_add_u32 s0, s0, 0x100
	s_addc_u32 s1, s1, 0
	s_cmp_lt_u32 s16, 40
	s_cbranch_scc0 .Lk_ffn_out_exit
.Lk_ffn_out:
	v_add_u32_e32 v164, 0x10000, v137
	ds_read_b128 v[138:141], v164
	ds_read_b128 v[142:145], v164 offset:1024
	ds_read_b128 v[156:159], v164 offset:2048
	ds_read_b128 v[164:167], v164 offset:3072
	ds_read_b128 v[168:171], v134
	ds_read_b128 v[172:175], v134 offset:1024
	ds_read_b128 v[180:183], v134 offset:2048
	ds_read_b128 v[184:187], v134 offset:3072
	ds_read_b128 v[188:191], v134 offset:4096
	ds_read_b128 v[192:195], v134 offset:5120
	ds_read_b128 v[196:199], v134 offset:6144
	ds_read_b128 v[200:203], v134 offset:7168
	v_add_u32_e32 v220, 0x14000, v137
	ds_read_b128 v[204:207], v220
	ds_read_b128 v[208:211], v220 offset:1024
	ds_read_b128 v[212:215], v220 offset:2048
	ds_read_b128 v[220:223], v220 offset:3072
	s_add_u32 s20, s9, s0
	s_addc_u32 s21, s11, s1
	s_add_u32 s20, s20, 0x80
	s_addc_u32 s21, s21, 0
	s_add_i32 s17, s13, 0xc000
	s_mov_b32 m0, s17
	s_nop 0
	global_load_lds_dwordx4 v136, s[20:21]
	s_add_i32 s17, s13, 0xe000
	s_mov_b32 m0, s17
	s_nop 0
	global_load_lds_dwordx4 v135, s[20:21]
	s_waitcnt vmcnt(8) lgkmcnt(0)
	s_barrier
; #define WAIT_V(n) asm volatile("s_waitcnt vmcnt(" #n ")" ::: "memory")
; #define WAIT_L(n) asm volatile("s_waitcnt lgkmcnt(" #n ")" ::: "memory")
; #define BAR __builtin_amdgcn_s_barrier()
; #define SCHED __builtin_amdgcn_sched_barrier(0)
; #define STG_A(b, h, kt) stage_half_s(lds0 + ((b) * 2 + (h)) * HT_B, ((h) ? A1 : Ap) + (kt) * BK, off0, off1)
; #define STG_B(b, h, kt) stage_half_s(lds0 + (4 + (b) * 2 + (h)) * HT_B, ((h) ? B1p : Bp) + (kt) * BK, off0, off1)
; #define STG_A(b, h, kt) stage_half_s(lds0 + ((b) * 2 + (h)) * HT_B, ((h) ? A1 : Ap) + (kt) * BK, off0, off1)
; #define STG_B(b, h, kt) stage_half_s(lds0 + (4 + (b) * 2 + (h)) * HT_B, ((h) ? B1p : Bp) + (kt) * BK, off0, off1)
; #define LDA8(b, h) _Pragma("unroll") for (int m = 0; m < 4; ++m) _Pragma("unroll") for (int k = 0; k < 2; ++k) \
;     At[m][k] = *(const bf16x8*)(SA_(shm, b, h) + abase + (m * 2 + k) * 1024)
; #define LDB8(dst, b, h) _Pragma("unroll") for (int n = 0; n < 2; ++n) _Pragma("unroll") for (int k = 0; k < 2; ++k) \
;     dst[n][k] = *(const bf16x8*)(SB_(shm, b, h) + bbase + (n * 2 + k) * 1024)
; template <bool HS>
; __device__ __forceinline__ void gemm_tile8(const u16* __restrict__ Ap, const u16* __restrict__ Bp, int K,
;                                            f32x4 (&acc)[2][2][4][2], char* shm, const int tid, const float* hsr = nullptr) {
;     ...
;     LDB8(B0, 0, 0); SCHED; LDA8(0, 0); STG_A(1, 1, t + 1);
;     WAIT_L(8); BAR; WAIT_L(0); MMA8(0, 0, B0); BAR; SCHED;
;     LDB8(B1, 0, 1); STG_B(0, 0, t + 2);
;     BAR; WAIT_L(0); MMA8(0, 1, B1); BAR;
;     LDA8(0, 1); STG_A(0, 0, t + 2);
;     BAR; WAIT_L(0); MMA8(1, 0, B0); BAR; SCHED;
;     STG_B(0, 1, t + 2);
;     WAIT_V(6); BAR; MMA8(1, 1, B1); BAR;
;     LDB8(B0, 1, 0); SCHED; LDA8(1, 0); STG_A(0, 1, t + 2);
;     WAIT_L(8); BAR; WAIT_L(0); MMA8(0, 0, B0); BAR; SCHED;
;     LDB8(B1, 1, 1); STG_B(1, 0, t + 3);
;     BAR; WAIT_L(0); MMA8(0, 1, B1); BAR;
;     LDA8(1, 1); STG_A(1, 0, t + 3);
;     BAR; WAIT_L(0); MMA8(1, 0, B0); BAR; SCHED;
;     STG_B(1, 1, t + 3);
;     WAIT_V(6); BAR; MMA8(1, 1, B1); BAR;
	s_setprio 1
	v_mfma_f32_16x16x32_bf16 v[126:129], v[168:171], v[138:141], v[126:129]
	v_mfma_f32_16x16x32_bf16 v[122:125], v[168:171], v[156:159], v[122:125]
	v_mfma_f32_16x16x32_bf16 v[114:117], v[180:183], v[156:159], v[114:117]
	v_mfma_f32_16x16x32_bf16 v[118:121], v[180:183], v[138:141], v[118:121]
	v_mfma_f32_16x16x32_bf16 v[110:113], v[188:191], v[138:141], v[110:113]
	v_mfma_f32_16x16x32_bf16 v[106:109], v[188:191], v[156:159], v[106:109]
	v_mfma_f32_16x16x32_bf16 v[98:101], v[196:199], v[156:159], v[98:101]
	v_mfma_f32_16x16x32_bf16 v[102:105], v[196:199], v[138:141], v[102:105]
	v_mfma_f32_16x16x32_bf16 v[126:129], v[172:175], v[142:145], v[126:129]
	v_mfma_f32_16x16x32_bf16 v[122:125], v[172:175], v[164:167], v[122:125]
	v_mfma_f32_16x16x32_bf16 v[114:117], v[184:187], v[164:167], v[114:117]
	v_mfma_f32_16x16x32_bf16 v[118:121], v[184:187], v[142:145], v[118:121]
	v_mfma_f32_16x16x32_bf16 v[110:113], v[192:195], v[142:145], v[110:113]
	v_mfma_f32_16x16x32_bf16 v[106:109], v[192:195], v[164:167], v[106:109]
	v_mfma_f32_16x16x32_bf16 v[98:101], v[200:203], v[164:167], v[98:101]
	v_mfma_f32_16x16x32_bf16 v[102:105], v[200:203], v[142:145], v[102:105]
	v_mfma_f32_16x16x32_bf16 v[94:97], v[168:171], v[204:207], v[94:97]
	v_mfma_f32_16x16x32_bf16 v[90:93], v[168:171], v[212:215], v[90:93]
	v_mfma_f32_16x16x32_bf16 v[82:85], v[180:183], v[212:215], v[82:85]
	v_mfma_f32_16x16x32_bf16 v[86:89], v[180:183], v[204:207], v[86:89]
	v_mfma_f32_16x16x32_bf16 v[78:81], v[188:191], v[204:207], v[78:81]
	v_mfma_f32_16x16x32_bf16 v[74:77], v[188:191], v[212:215], v[74:77]
	v_mfma_f32_16x16x32_bf16 v[66:69], v[196:199], v[212:215], v[66:69]
	v_mfma_f32_16x16x32_bf16 v[70:73], v[196:199], v[204:207], v[70:73]
	v_mfma_f32_16x16x32_bf16 v[94:97], v[172:175], v[208:211], v[94:97]
	v_mfma_f32_16x16x32_bf16 v[90:93], v[172:175], v[220:223], v[90:93]
	v_mfma_f32_16x16x32_bf16 v[82:85], v[184:187], v[220:223], v[82:85]
	v_mfma_f32_16x16x32_bf16 v[86:89], v[184:187], v[208:211], v[86:89]
	v_mfma_f32_16x16x32_bf16 v[78:81], v[192:195], v[208:211], v[78:81]
	v_mfma_f32_16x16x32_bf16 v[74:77], v[192:195], v[220:223], v[74:77]
	v_mfma_f32_16x16x32_bf16 v[66:69], v[200:203], v[220:223], v[66:69]
	v_mfma_f32_16x16x32_bf16 v[70:73], v[200:203], v[208:211], v[70:73]
	s_setprio 0
	s_barrier
	ds_read_b128 v[168:171], v134 offset:16384
	ds_read_b128 v[172:175], v134 offset:17408
	ds_read_b128 v[180:183], v134 offset:18432
	ds_read_b128 v[184:187], v134 offset:19456
	ds_read_b128 v[188:191], v134 offset:20480
	ds_read_b128 v[192:195], v134 offset:21504
	ds_read_b128 v[196:199], v134 offset:22528
	ds_read_b128 v[200:203], v134 offset:23552
	s_add_u32 s20, s22, s0
	s_addc_u32 s21, s23, s1
	s_add_u32 s20, s20, 0x100
	s_addc_u32 s21, s21, 0
	s_add_i32 s17, s13, 0x10000
	s_mov_b32 m0, s17
	s_nop 0
	global_load_lds_dwordx4 v136, s[20:21]
	s_add_i32 s17, s13, 0x12000
	s_mov_b32 m0, s17
	s_nop 0
	global_load_lds_dwordx4 v135, s[20:21]
	s_add_u32 s20, s3, s0
	s_addc_u32 s21, s8, s1
	s_add_u32 s20, s20, 0x100
	s_addc_u32 s21, s21, 0
	s_mov_b32 m0, s13
	s_nop 0
	global_load_lds_dwordx4 v136, s[20:21]
	s_add_i32 s17, s13, 0x2000
	s_mov_b32 m0, s17
	s_nop 0
	global_load_lds_dwordx4 v135, s[20:21]
	s_add_u32 s20, s18, s0
	s_addc_u32 s21, s19, s1
	s_add_u32 s20, s20, 0x100
	s_addc_u32 s21, s21, 0
	s_add_i32 s17, s13, 0x14000
	s_mov_b32 m0, s17
	s_nop 0
	global_load_lds_dwordx4 v136, s[20:21]
	s_add_i32 s17, s13, 0x16000
	s_mov_b32 m0, s17
	s_nop 0
	global_load_lds_dwordx4 v135, s[20:21]
	s_waitcnt vmcnt(8) lgkmcnt(0)
	s_barrier
	s_setprio 1
	v_mfma_f32_16x16x32_bf16 v[62:65], v[168:171], v[138:141], v[62:65]
	v_mfma_f32_16x16x32_bf16 v[58:61], v[168:171], v[156:159], v[58:61]
	v_mfma_f32_16x16x32_bf16 v[50:53], v[180:183], v[156:159], v[50:53]
	v_mfma_f32_16x16x32_bf16 v[54:57], v[180:183], v[138:141], v[54:57]
	v_mfma_f32_16x16x32_bf16 v[46:49], v[188:191], v[138:141], v[46:49]
	v_mfma_f32_16x16x32_bf16 v[42:45], v[188:191], v[156:159], v[42:45]
	v_mfma_f32_16x16x32_bf16 v[34:37], v[196:199], v[156:159], v[34:37]
	v_mfma_f32_16x16x32_bf16 v[38:41], v[196:199], v[138:141], v[38:41]
	v_mfma_f32_16x16x32_bf16 v[62:65], v[172:175], v[142:145], v[62:65]
	v_mfma_f32_16x16x32_bf16 v[58:61], v[172:175], v[164:167], v[58:61]
	v_mfma_f32_16x16x32_bf16 v[50:53], v[184:187], v[164:167], v[50:53]
	v_mfma_f32_16x16x32_bf16 v[54:57], v[184:187], v[142:145], v[54:57]
	v_mfma_f32_16x16x32_bf16 v[46:49], v[192:195], v[142:145], v[46:49]
	v_mfma_f32_16x16x32_bf16 v[42:45], v[192:195], v[164:167], v[42:45]
	v_mfma_f32_16x16x32_bf16 v[34:37], v[200:203], v[164:167], v[34:37]
	v_mfma_f32_16x16x32_bf16 v[38:41], v[200:203], v[142:145], v[38:41]
	v_mfma_f32_16x16x32_bf16 v[30:33], v[168:171], v[204:207], v[30:33]
	v_mfma_f32_16x16x32_bf16 v[26:29], v[168:171], v[212:215], v[26:29]
	v_mfma_f32_16x16x32_bf16 v[18:21], v[180:183], v[212:215], v[18:21]
	v_mfma_f32_16x16x32_bf16 v[22:25], v[180:183], v[204:207], v[22:25]
	v_mfma_f32_16x16x32_bf16 v[14:17], v[188:191], v[204:207], v[14:17]
	v_mfma_f32_16x16x32_bf16 v[10:13], v[188:191], v[212:215], v[10:13]
	v_mfma_f32_16x16x32_bf16 v[2:5], v[196:199], v[212:215], v[2:5]
	v_mfma_f32_16x16x32_bf16 v[6:9], v[196:199], v[204:207], v[6:9]
	v_mfma_f32_16x16x32_bf16 v[30:33], v[172:175], v[208:211], v[30:33]
	v_mfma_f32_16x16x32_bf16 v[26:29], v[172:175], v[220:223], v[26:29]
	v_mfma_f32_16x16x32_bf16 v[18:21], v[184:187], v[220:223], v[18:21]
	v_mfma_f32_16x16x32_bf16 v[22:25], v[184:187], v[208:211], v[22:25]
	v_mfma_f32_16x16x32_bf16 v[14:17], v[192:195], v[208:211], v[14:17]
	v_mfma_f32_16x16x32_bf16 v[10:13], v[192:195], v[220:223], v[10:13]
	v_mfma_f32_16x16x32_bf16 v[2:5], v[200:203], v[220:223], v[2:5]
	v_mfma_f32_16x16x32_bf16 v[6:9], v[200:203], v[208:211], v[6:9]
	s_setprio 0
	s_barrier
; #define WAIT_V(n) asm volatile("s_waitcnt vmcnt(" #n ")" ::: "memory")
; #define WAIT_L(n) asm volatile("s_waitcnt lgkmcnt(" #n ")" ::: "memory")
; #define BAR __builtin_amdgcn_s_barrier()
; #define SCHED __builtin_amdgcn_sched_barrier(0)
; #define STG_A(b, h, kt) stage_half_s(lds0 + ((b) * 2 + (h)) * HT_B, ((h) ? A1 : Ap) + (kt) * BK, off0, off1)
; #define STG_B(b, h, kt) stage_half_s(lds0 + (4 + (b) * 2 + (h)) * HT_B, ((h) ? B1p : Bp) + (kt) * BK, off0, off1)
; #define STG_A(b, h, kt) stage_half_s(lds0 + ((b) * 2 + (h)) * HT_B, ((h) ? A1 : Ap) + (kt) * BK, off0, off1)
; #define STG_B(b, h, kt) stage_half_s(lds0 + (4 + (b) * 2 + (h)) * HT_B, ((h) ? B1p : Bp) + (kt) * BK, off0, off1)
; #define LDA8(b, h) _Pragma("unroll") for (int m = 0; m < 4; ++m) _Pragma("unroll") for (int k = 0; k < 2; ++k) \
;     At[m][k] = *(const bf16x8*)(SA_(shm, b, h) + abase + (m * 2 + k) * 1024)
; #define LDB8(dst, b, h) _Pragma("unroll") for (int n = 0; n < 2; ++n) _Pragma("unroll") for (int k = 0; k < 2; ++k) \
;     dst[n][k] = *(const bf16x8*)(SB_(shm, b, h) + bbase + (n * 2 + k) * 1024)
; template <bool HS>
; __device__ __forceinline__ void gemm_tile8(const u16* __restrict__ Ap, const u16* __restrict__ Bp, int K,
;                                            f32x4 (&acc)[2][2][4][2], char* shm, const int tid, const float* hsr = nullptr) {
;     ...
;     LDB8(B0, 0, 0); SCHED; LDA8(0, 0); STG_A(1, 1, t + 1);
;     WAIT_L(8); BAR; WAIT_L(0); MMA8(0, 0, B0); BAR; SCHED;
;     LDB8(B1, 0, 1); STG_B(0, 0, t + 2);
;     BAR; WAIT_L(0); MMA8(0, 1, B1); BAR;
;     LDA8(0, 1); STG_A(0, 0, t + 2);
;     BAR; WAIT_L(0); MMA8(1, 0, B0); BAR; SCHED;
;     STG_B(0, 1, t + 2);
;     WAIT_V(6); BAR; MMA8(1, 1, B1); BAR;
;     LDB8(B0, 1, 0); SCHED; LDA8(1, 0); STG_A(0, 1, t + 2);
;     WAIT_L(8); BAR; WAIT_L(0); MMA8(0, 0, B0); BAR; SCHED;
;     LDB8(B1, 1, 1); STG_B(1, 0, t + 3);
;     BAR; WAIT_L(0); MMA8(0, 1, B1); BAR;
;     LDA8(1, 1); STG_A(1, 0, t + 3);
;     BAR; WAIT_L(0); MMA8(1, 0, B0); BAR; SCHED;
;     STG_B(1, 1, t + 3);
;     WAIT_V(6); BAR; MMA8(1, 1, B1); BAR;
	v_add_u32_e32 v164, 0x18000, v137
	ds_read_b128 v[138:141], v164
	ds_read_b128 v[142:145], v164 offset:1024
	ds_read_b128 v[156:159], v164 offset:2048
	ds_read_b128 v[164:167], v164 offset:3072
	ds_read_b128 v[168:171], v134 offset:32768
	ds_read_b128 v[172:175], v134 offset:33792
	ds_read_b128 v[180:183], v134 offset:34816
	ds_read_b128 v[184:187], v134 offset:35840
	ds_read_b128 v[188:191], v134 offset:36864
	ds_read_b128 v[192:195], v134 offset:37888
	ds_read_b128 v[196:199], v134 offset:38912
	ds_read_b128 v[200:203], v134 offset:39936
	v_add_u32_e32 v220, 0x1c000, v137
	ds_read_b128 v[204:207], v220
	ds_read_b128 v[208:211], v220 offset:1024
	ds_read_b128 v[212:215], v220 offset:2048
	ds_read_b128 v[220:223], v220 offset:3072
	s_add_u32 s20, s9, s0
	s_addc_u32 s21, s11, s1
	s_add_u32 s20, s20, 0x100
	s_addc_u32 s21, s21, 0
	s_add_i32 s17, s13, 0x4000
	s_mov_b32 m0, s17
	s_nop 0
	global_load_lds_dwordx4 v136, s[20:21]
	s_add_i32 s17, s13, 0x6000
	s_mov_b32 m0, s17
	s_nop 0
	global_load_lds_dwordx4 v135, s[20:21]
	s_waitcnt vmcnt(8) lgkmcnt(0)
	s_barrier
	s_setprio 1
	v_mfma_f32_16x16x32_bf16 v[126:129], v[168:171], v[138:141], v[126:129]
	v_mfma_f32_16x16x32_bf16 v[122:125], v[168:171], v[156:159], v[122:125]
	v_mfma_f32_16x16x32_bf16 v[114:117], v[180:183], v[156:159], v[114:117]
	v_mfma_f32_16x16x32_bf16 v[118:121], v[180:183], v[138:141], v[118:121]
	v_mfma_f32_16x16x32_bf16 v[110:113], v[188:191], v[138:141], v[110:113]
	v_mfma_f32_16x16x32_bf16 v[106:109], v[188:191], v[156:159], v[106:109]
	v_mfma_f32_16x16x32_bf16 v[98:101], v[196:199], v[156:159], v[98:101]
	v_mfma_f32_16x16x32_bf16 v[102:105], v[196:199], v[138:141], v[102:105]
	v_mfma_f32_16x16x32_bf16 v[126:129], v[172:175], v[142:145], v[126:129]
	v_mfma_f32_16x16x32_bf16 v[122:125], v[172:175], v[164:167], v[122:125]
	v_mfma_f32_16x16x32_bf16 v[114:117], v[184:187], v[164:167], v[114:117]
	v_mfma_f32_16x16x32_bf16 v[118:121], v[184:187], v[142:145], v[118:121]
	v_mfma_f32_16x16x32_bf16 v[110:113], v[192:195], v[142:145], v[110:113]
	v_mfma_f32_16x16x32_bf16 v[106:109], v[192:195], v[164:167], v[106:109]
	v_mfma_f32_16x16x32_bf16 v[98:101], v[200:203], v[164:167], v[98:101]
	v_mfma_f32_16x16x32_bf16 v[102:105], v[200:203], v[142:145], v[102:105]
	v_mfma_f32_16x16x32_bf16 v[94:97], v[168:171], v[204:207], v[94:97]
	v_mfma_f32_16x16x32_bf16 v[90:93], v[168:171], v[212:215], v[90:93]
	v_mfma_f32_16x16x32_bf16 v[82:85], v[180:183], v[212:215], v[82:85]
	v_mfma_f32_16x16x32_bf16 v[86:89], v[180:183], v[204:207], v[86:89]
	v_mfma_f32_16x16x32_bf16 v[78:81], v[188:191], v[204:207], v[78:81]
	v_mfma_f32_16x16x32_bf16 v[74:77], v[188:191], v[212:215], v[74:77]
	v_mfma_f32_16x16x32_bf16 v[66:69], v[196:199], v[212:215], v[66:69]
	v_mfma_f32_16x16x32_bf16 v[70:73], v[196:199], v[204:207], v[70:73]
	v_mfma_f32_16x16x32_bf16 v[94:97], v[172:175], v[208:211], v[94:97]
	v_mfma_f32_16x16x32_bf16 v[90:93], v[172:175], v[220:223], v[90:93]
	v_mfma_f32_16x16x32_bf16 v[82:85], v[184:187], v[220:223], v[82:85]
	v_mfma_f32_16x16x32_bf16 v[86:89], v[184:187], v[208:211], v[86:89]
	v_mfma_f32_16x16x32_bf16 v[78:81], v[192:195], v[208:211], v[78:81]
	v_mfma_f32_16x16x32_bf16 v[74:77], v[192:195], v[220:223], v[74:77]
	v_mfma_f32_16x16x32_bf16 v[66:69], v[200:203], v[220:223], v[66:69]
	v_mfma_f32_16x16x32_bf16 v[70:73], v[200:203], v[208:211], v[70:73]
	s_setprio 0
	s_barrier
	ds_read_b128 v[168:171], v134 offset:49152
	ds_read_b128 v[172:175], v134 offset:50176
	ds_read_b128 v[180:183], v134 offset:51200
	ds_read_b128 v[184:187], v134 offset:52224
	ds_read_b128 v[188:191], v134 offset:53248
	ds_read_b128 v[192:195], v134 offset:54272
	ds_read_b128 v[196:199], v134 offset:55296
	ds_read_b128 v[200:203], v134 offset:56320
	s_add_u32 s20, s22, s0
	s_addc_u32 s21, s23, s1
	s_add_u32 s20, s20, 0x180
	s_addc_u32 s21, s21, 0
	s_add_i32 s17, s13, 0x18000
	s_mov_b32 m0, s17
	s_nop 0
	global_load_lds_dwordx4 v136, s[20:21]
	s_add_i32 s17, s13, 0x1a000
	s_mov_b32 m0, s17
	s_nop 0
	global_load_lds_dwordx4 v135, s[20:21]
	s_add_u32 s20, s3, s0
	s_addc_u32 s21, s8, s1
	s_add_u32 s20, s20, 0x180
	s_addc_u32 s21, s21, 0
	s_add_i32 s17, s13, 0x8000
	s_mov_b32 m0, s17
	s_nop 0
	global_load_lds_dwordx4 v136, s[20:21]
	s_add_i32 s17, s13, 0xa000
	s_mov_b32 m0, s17
	s_nop 0
	global_load_lds_dwordx4 v135, s[20:21]
	s_add_u32 s20, s18, s0
	s_addc_u32 s21, s19, s1
	s_add_u32 s20, s20, 0x180
	s_addc_u32 s21, s21, 0
	s_add_i32 s17, s13, 0x1c000
	s_mov_b32 m0, s17
	s_nop 0
	global_load_lds_dwordx4 v136, s[20:21]
	s_add_i32 s17, s13, 0x1e000
	s_mov_b32 m0, s17
	s_nop 0
	global_load_lds_dwordx4 v135, s[20:21]
	s_waitcnt vmcnt(8) lgkmcnt(0)
	s_barrier
	s_setprio 1
	v_mfma_f32_16x16x32_bf16 v[62:65], v[168:171], v[138:141], v[62:65]
	v_mfma_f32_16x16x32_bf16 v[58:61], v[168:171], v[156:159], v[58:61]
	v_mfma_f32_16x16x32_bf16 v[50:53], v[180:183], v[156:159], v[50:53]
	v_mfma_f32_16x16x32_bf16 v[54:57], v[180:183], v[138:141], v[54:57]
	v_mfma_f32_16x16x32_bf16 v[46:49], v[188:191], v[138:141], v[46:49]
	v_mfma_f32_16x16x32_bf16 v[42:45], v[188:191], v[156:159], v[42:45]
	v_mfma_f32_16x16x32_bf16 v[34:37], v[196:199], v[156:159], v[34:37]
	v_mfma_f32_16x16x32_bf16 v[38:41], v[196:199], v[138:141], v[38:41]
	v_mfma_f32_16x16x32_bf16 v[62:65], v[172:175], v[142:145], v[62:65]
	v_mfma_f32_16x16x32_bf16 v[58:61], v[172:175], v[164:167], v[58:61]
	v_mfma_f32_16x16x32_bf16 v[50:53], v[184:187], v[164:167], v[50:53]
	v_mfma_f32_16x16x32_bf16 v[54:57], v[184:187], v[142:145], v[54:57]
	v_mfma_f32_16x16x32_bf16 v[46:49], v[192:195], v[142:145], v[46:49]
	v_mfma_f32_16x16x32_bf16 v[42:45], v[192:195], v[164:167], v[42:45]
	v_mfma_f32_16x16x32_bf16 v[34:37], v[200:203], v[164:167], v[34:37]
	v_mfma_f32_16x16x32_bf16 v[38:41], v[200:203], v[142:145], v[38:41]
	v_mfma_f32_16x16x32_bf16 v[30:33], v[168:171], v[204:207], v[30:33]
	v_mfma_f32_16x16x32_bf16 v[26:29], v[168:171], v[212:215], v[26:29]
	v_mfma_f32_16x16x32_bf16 v[18:21], v[180:183], v[212:215], v[18:21]
	v_mfma_f32_16x16x32_bf16 v[22:25], v[180:183], v[204:207], v[22:25]
	v_mfma_f32_16x16x32_bf16 v[14:17], v[188:191], v[204:207], v[14:17]
	v_mfma_f32_16x16x32_bf16 v[10:13], v[188:191], v[212:215], v[10:13]
	v_mfma_f32_16x16x32_bf16 v[2:5], v[196:199], v[212:215], v[2:5]
	v_mfma_f32_16x16x32_bf16 v[6:9], v[196:199], v[204:207], v[6:9]
	v_mfma_f32_16x16x32_bf16 v[30:33], v[172:175], v[208:211], v[30:33]
	v_mfma_f32_16x16x32_bf16 v[26:29], v[172:175], v[220:223], v[26:29]
	v_mfma_f32_16x16x32_bf16 v[18:21], v[184:187], v[220:223], v[18:21]
	v_mfma_f32_16x16x32_bf16 v[22:25], v[184:187], v[208:211], v[22:25]
	v_mfma_f32_16x16x32_bf16 v[14:17], v[192:195], v[208:211], v[14:17]
	v_mfma_f32_16x16x32_bf16 v[10:13], v[192:195], v[220:223], v[10:13]
	v_mfma_f32_16x16x32_bf16 v[2:5], v[200:203], v[220:223], v[2:5]
	v_mfma_f32_16x16x32_bf16 v[6:9], v[200:203], v[208:211], v[6:9]
	s_setprio 0
	s_barrier
	s_add_i32 s16, s16, 2
	s_add_u32 s0, s0, 0x100
	s_addc_u32 s1, s1, 0
	s_cmp_lt_u32 s16, 40
	s_cbranch_scc1 .Lk_ffn_out

; #define WAIT_V(n) asm volatile("s_waitcnt vmcnt(" #n ")" ::: "memory")
; #define WAIT_L(n) asm volatile("s_waitcnt lgkmcnt(" #n ")" ::: "memory")
; #define BAR __builtin_amdgcn_s_barrier()
; #define SCHED __builtin_amdgcn_sched_barrier(0)
; #define STG_A(b, h, kt) stage_half_s(lds0 + ((b) * 2 + (h)) * HT_B, ((h) ? A1 : Ap) + (kt) * BK, off0, off1)
; #define STG_B(b, h, kt) stage_half_s(lds0 + (4 + (b) * 2 + (h)) * HT_B, ((h) ? B1p : Bp) + (kt) * BK, off0, off1)
; #define STG_A(b, h, kt) stage_half_s(lds0 + ((b) * 2 + (h)) * HT_B, ((h) ? A1 : Ap) + (kt) * BK, off0, off1)
; #define STG_B(b, h, kt) stage_half_s(lds0 + (4 + (b) * 2 + (h)) * HT_B, ((h) ? B1p : Bp) + (kt) * BK, off0, off1)
; template <bool HS>
; __device__ __forceinline__ void gemm_tile8(const u16* __restrict__ Ap, const u16* __restrict__ Bp, int K,
;                                            f32x4 (&acc)[2][2][4][2], char* shm, const int tid, const float* hsr = nullptr) {
;     ...
;   WAIT_V(0);
;   if (wr == 1) BAR;
;   BAR;
;   BAR;
;   for (int t = 0; t < nt - 2; t += 2) {
;     if constexpr (HS) {
;       if (t > 0 && (t & 7) == 0) {
;         const float* rt = hsr + ((t >> 3) - 1) * 256 + wr * 64 + fq * 4;
; #pragma unroll
;         for (int ai = 0; ai < 2; ++ai)
; #pragma unroll
;           for (int m = 0; m < 4; ++m) {
;             const f32x4 q4 = *(const f32x4*)(rt + ai * 128 + m * 16);
; #pragma unroll
;             for (int bj = 0; bj < 2; ++bj)
; #pragma unroll
;               for (int n = 0; n < 2; ++n) acc[ai][bj][m][n] *= q4;
;             SCHED;
;           }
;       }
;     }
;     LDB8(B0, 0, 0); SCHED; LDA8(0, 0); STG_A(1, 1, t + 1);
;     WAIT_L(8); BAR; WAIT_L(0); MMA8(0, 0, B0); BAR; SCHED;
;     LDB8(B1, 0, 1); STG_B(0, 0, t + 2);
;     BAR; WAIT_L(0); MMA8(0, 1, B1); BAR;
;     LDA8(0, 1); STG_A(0, 0, t + 2);
;     BAR; WAIT_L(0); MMA8(1, 0, B0); BAR; SCHED;
;     STG_B(0, 1, t + 2);
;     WAIT_V(6); BAR; MMA8(1, 1, B1); BAR;
;     LDB8(B0, 1, 0); SCHED; LDA8(1, 0); STG_A(0, 1, t + 2);
;     WAIT_L(8); BAR; WAIT_L(0); MMA8(0, 0, B0); BAR; SCHED;
;     LDB8(B1, 1, 1); STG_B(1, 0, t + 3);
;     BAR; WAIT_L(0); MMA8(0, 1, B1); BAR;
;     LDA8(1, 1); STG_A(1, 0, t + 3);
;     BAR; WAIT_L(0); MMA8(1, 0, B0); BAR; SCHED;
;     STG_B(1, 1, t + 3);
;     WAIT_V(6); BAR; MMA8(1, 1, B1); BAR;
.Lffn_in_kinit:
	v_readfirstlane_b32 s20, v130
	v_readfirstlane_b32 s21, v131
	v_readfirstlane_b32 s22, v132
	v_readfirstlane_b32 s23, v133
	s_mov_b32 s16, s5
	s_mov_b32 s17, s6
	s_mov_b32 s18, s12
	s_mov_b32 s19, s13
	s_barrier
	s_barrier
	ds_read_b128 v[146:149], v244
	ds_read_b128 v[150:153], v244 offset:1024
	ds_read_b128 v[154:157], v244 offset:2048
	ds_read_b128 v[158:161], v244 offset:3072
	ds_read_b128 v[162:165], v142
	ds_read_b128 v[166:169], v142 offset:1024
	ds_read_b128 v[170:173], v142 offset:2048
	ds_read_b128 v[174:177], v142 offset:3072
	ds_read_b128 v[180:183], v142 offset:4096
	ds_read_b128 v[184:187], v142 offset:5120
	ds_read_b128 v[188:191], v142 offset:6144
	ds_read_b128 v[192:195], v142 offset:7168
	ds_read_b128 v[196:199], v245
	ds_read_b128 v[200:203], v245 offset:1024
	ds_read_b128 v[204:207], v245 offset:2048
	ds_read_b128 v[208:211], v245 offset:3072
	s_add_u32 s0, s18, 0x80
	s_addc_u32 s1, s19, 0
	s_add_i32 s3, s7, 0xc000
	s_mov_b32 m0, s3
	s_nop 0
	global_load_lds_dwordx4 v144, s[0:1]
	s_add_i32 s3, s7, 0xe000
	s_mov_b32 m0, s3
	s_nop 0
	global_load_lds_dwordx4 v143, s[0:1]
	s_waitcnt vmcnt(8) lgkmcnt(0)
	s_barrier
	s_setprio 1
	v_mfma_f32_16x16x32_bf16 v[126:129], v[162:165], v[146:149], 0
	v_mfma_f32_16x16x32_bf16 v[122:125], v[162:165], v[154:157], 0
	v_mfma_f32_16x16x32_bf16 v[114:117], v[170:173], v[154:157], 0
	v_mfma_f32_16x16x32_bf16 v[118:121], v[170:173], v[146:149], 0
	v_mfma_f32_16x16x32_bf16 v[110:113], v[180:183], v[146:149], 0
	v_mfma_f32_16x16x32_bf16 v[106:109], v[180:183], v[154:157], 0
	v_mfma_f32_16x16x32_bf16 v[98:101], v[188:191], v[154:157], 0
	v_mfma_f32_16x16x32_bf16 v[102:105], v[188:191], v[146:149], 0
	v_mfma_f32_16x16x32_bf16 v[126:129], v[166:169], v[150:153], v[126:129]
	v_mfma_f32_16x16x32_bf16 v[122:125], v[166:169], v[158:161], v[122:125]
	v_mfma_f32_16x16x32_bf16 v[114:117], v[174:177], v[158:161], v[114:117]
	v_mfma_f32_16x16x32_bf16 v[118:121], v[174:177], v[150:153], v[118:121]
	v_mfma_f32_16x16x32_bf16 v[110:113], v[184:187], v[150:153], v[110:113]
	v_mfma_f32_16x16x32_bf16 v[106:109], v[184:187], v[158:161], v[106:109]
	v_mfma_f32_16x16x32_bf16 v[98:101], v[192:195], v[158:161], v[98:101]
	v_mfma_f32_16x16x32_bf16 v[102:105], v[192:195], v[150:153], v[102:105]
	v_mfma_f32_16x16x32_bf16 v[94:97], v[162:165], v[196:199], 0
	v_mfma_f32_16x16x32_bf16 v[90:93], v[162:165], v[204:207], 0
	v_mfma_f32_16x16x32_bf16 v[82:85], v[170:173], v[204:207], 0
	v_mfma_f32_16x16x32_bf16 v[86:89], v[170:173], v[196:199], 0
	v_mfma_f32_16x16x32_bf16 v[78:81], v[180:183], v[196:199], 0
	v_mfma_f32_16x16x32_bf16 v[74:77], v[180:183], v[204:207], 0
	v_mfma_f32_16x16x32_bf16 v[66:69], v[188:191], v[204:207], 0
	v_mfma_f32_16x16x32_bf16 v[70:73], v[188:191], v[196:199], 0
	v_mfma_f32_16x16x32_bf16 v[94:97], v[166:169], v[200:203], v[94:97]
	v_mfma_f32_16x16x32_bf16 v[90:93], v[166:169], v[208:211], v[90:93]
	v_mfma_f32_16x16x32_bf16 v[82:85], v[174:177], v[208:211], v[82:85]
	v_mfma_f32_16x16x32_bf16 v[86:89], v[174:177], v[200:203], v[86:89]
	v_mfma_f32_16x16x32_bf16 v[78:81], v[184:187], v[200:203], v[78:81]
	v_mfma_f32_16x16x32_bf16 v[74:77], v[184:187], v[208:211], v[74:77]
	v_mfma_f32_16x16x32_bf16 v[66:69], v[192:195], v[208:211], v[66:69]
	v_mfma_f32_16x16x32_bf16 v[70:73], v[192:195], v[200:203], v[70:73]
	s_setprio 0
	s_barrier
	ds_read_b128 v[162:165], v142 offset:16384
	ds_read_b128 v[166:169], v142 offset:17408
	ds_read_b128 v[170:173], v142 offset:18432
	ds_read_b128 v[174:177], v142 offset:19456
	ds_read_b128 v[180:183], v142 offset:20480
	ds_read_b128 v[184:187], v142 offset:21504
	ds_read_b128 v[188:191], v142 offset:22528
	ds_read_b128 v[192:195], v142 offset:23552
	s_add_u32 s0, s20, 0x100
	s_addc_u32 s1, s21, 0
	s_add_i32 s3, s7, 0x10000
	s_mov_b32 m0, s3
	s_nop 0
	global_load_lds_dwordx4 v144, s[0:1]
	s_add_i32 s3, s7, 0x12000
	s_mov_b32 m0, s3
	s_nop 0
	global_load_lds_dwordx4 v143, s[0:1]
	s_add_u32 s0, s16, 0x100
	s_addc_u32 s1, s17, 0
	s_mov_b32 m0, s7
	s_nop 0
	global_load_lds_dwordx4 v144, s[0:1]
	s_add_i32 s3, s7, 0x2000
	s_mov_b32 m0, s3
	s_nop 0
	global_load_lds_dwordx4 v143, s[0:1]
	s_add_u32 s0, s22, 0x100
	s_addc_u32 s1, s23, 0
	s_add_i32 s3, s7, 0x14000
	s_mov_b32 m0, s3
	s_nop 0
	global_load_lds_dwordx4 v144, s[0:1]
	s_add_i32 s3, s7, 0x16000
	s_mov_b32 m0, s3
	s_nop 0
	global_load_lds_dwordx4 v143, s[0:1]
	s_waitcnt vmcnt(8) lgkmcnt(0)
	s_barrier
	s_setprio 1
	v_mfma_f32_16x16x32_bf16 v[62:65], v[162:165], v[146:149], 0
	v_mfma_f32_16x16x32_bf16 v[58:61], v[162:165], v[154:157], 0
	v_mfma_f32_16x16x32_bf16 v[50:53], v[170:173], v[154:157], 0
	v_mfma_f32_16x16x32_bf16 v[54:57], v[170:173], v[146:149], 0
	v_mfma_f32_16x16x32_bf16 v[46:49], v[180:183], v[146:149], 0
	v_mfma_f32_16x16x32_bf16 v[42:45], v[180:183], v[154:157], 0
	v_mfma_f32_16x16x32_bf16 v[34:37], v[188:191], v[154:157], 0
	v_mfma_f32_16x16x32_bf16 v[38:41], v[188:191], v[146:149], 0
	v_mfma_f32_16x16x32_bf16 v[62:65], v[166:169], v[150:153], v[62:65]
	v_mfma_f32_16x16x32_bf16 v[58:61], v[166:169], v[158:161], v[58:61]
	v_mfma_f32_16x16x32_bf16 v[50:53], v[174:177], v[158:161], v[50:53]
	v_mfma_f32_16x16x32_bf16 v[54:57], v[174:177], v[150:153], v[54:57]
	v_mfma_f32_16x16x32_bf16 v[46:49], v[184:187], v[150:153], v[46:49]
	v_mfma_f32_16x16x32_bf16 v[42:45], v[184:187], v[158:161], v[42:45]
	v_mfma_f32_16x16x32_bf16 v[34:37], v[192:195], v[158:161], v[34:37]
	v_mfma_f32_16x16x32_bf16 v[38:41], v[192:195], v[150:153], v[38:41]
	v_mfma_f32_16x16x32_bf16 v[30:33], v[162:165], v[196:199], 0
	v_mfma_f32_16x16x32_bf16 v[26:29], v[162:165], v[204:207], 0
	v_mfma_f32_16x16x32_bf16 v[18:21], v[170:173], v[204:207], 0
	v_mfma_f32_16x16x32_bf16 v[22:25], v[170:173], v[196:199], 0
	v_mfma_f32_16x16x32_bf16 v[14:17], v[180:183], v[196:199], 0
	v_mfma_f32_16x16x32_bf16 v[10:13], v[180:183], v[204:207], 0
	v_mfma_f32_16x16x32_bf16 v[2:5], v[188:191], v[204:207], 0
	v_mfma_f32_16x16x32_bf16 v[6:9], v[188:191], v[196:199], 0
	v_mfma_f32_16x16x32_bf16 v[30:33], v[166:169], v[200:203], v[30:33]
	v_mfma_f32_16x16x32_bf16 v[26:29], v[166:169], v[208:211], v[26:29]
	v_mfma_f32_16x16x32_bf16 v[18:21], v[174:177], v[208:211], v[18:21]
	v_mfma_f32_16x16x32_bf16 v[22:25], v[174:177], v[200:203], v[22:25]
	v_mfma_f32_16x16x32_bf16 v[14:17], v[184:187], v[200:203], v[14:17]
	v_mfma_f32_16x16x32_bf16 v[10:13], v[184:187], v[208:211], v[10:13]
	v_mfma_f32_16x16x32_bf16 v[2:5], v[192:195], v[208:211], v[2:5]
	v_mfma_f32_16x16x32_bf16 v[6:9], v[192:195], v[200:203], v[6:9]
	s_setprio 0
	s_barrier
; #define WAIT_V(n) asm volatile("s_waitcnt vmcnt(" #n ")" ::: "memory")
; #define WAIT_L(n) asm volatile("s_waitcnt lgkmcnt(" #n ")" ::: "memory")
; #define BAR __builtin_amdgcn_s_barrier()
; #define SCHED __builtin_amdgcn_sched_barrier(0)
; #define STG_A(b, h, kt) stage_half_s(lds0 + ((b) * 2 + (h)) * HT_B, ((h) ? A1 : Ap) + (kt) * BK, off0, off1)
; #define STG_B(b, h, kt) stage_half_s(lds0 + (4 + (b) * 2 + (h)) * HT_B, ((h) ? B1p : Bp) + (kt) * BK, off0, off1)
; #define STG_A(b, h, kt) stage_half_s(lds0 + ((b) * 2 + (h)) * HT_B, ((h) ? A1 : Ap) + (kt) * BK, off0, off1)
; #define STG_B(b, h, kt) stage_half_s(lds0 + (4 + (b) * 2 + (h)) * HT_B, ((h) ? B1p : Bp) + (kt) * BK, off0, off1)
; #define LDA8(b, h) _Pragma("unroll") for (int m = 0; m < 4; ++m) _Pragma("unroll") for (int k = 0; k < 2; ++k) \
;     At[m][k] = *(const bf16x8*)(SA_(shm, b, h) + abase + (m * 2 + k) * 1024)
; #define LDB8(dst, b, h) _Pragma("unroll") for (int n = 0; n < 2; ++n) _Pragma("unroll") for (int k = 0; k < 2; ++k) \
;     dst[n][k] = *(const bf16x8*)(SB_(shm, b, h) + bbase + (n * 2 + k) * 1024)
; template <bool HS>
; __device__ __forceinline__ void gemm_tile8(const u16* __restrict__ Ap, const u16* __restrict__ Bp, int K,
;                                            f32x4 (&acc)[2][2][4][2], char* shm, const int tid, const float* hsr = nullptr) {
;     ...
;     LDB8(B0, 0, 0); SCHED; LDA8(0, 0); STG_A(1, 1, t + 1);
;     WAIT_L(8); BAR; WAIT_L(0); MMA8(0, 0, B0); BAR; SCHED;
;     LDB8(B1, 0, 1); STG_B(0, 0, t + 2);
;     BAR; WAIT_L(0); MMA8(0, 1, B1); BAR;
;     LDA8(0, 1); STG_A(0, 0, t + 2);
;     BAR; WAIT_L(0); MMA8(1, 0, B0); BAR; SCHED;
;     STG_B(0, 1, t + 2);
;     WAIT_V(6); BAR; MMA8(1, 1, B1); BAR;
;     LDB8(B0, 1, 0); SCHED; LDA8(1, 0); STG_A(0, 1, t + 2);
;     WAIT_L(8); BAR; WAIT_L(0); MMA8(0, 0, B0); BAR; SCHED;
;     LDB8(B1, 1, 1); STG_B(1, 0, t + 3);
;     BAR; WAIT_L(0); MMA8(0, 1, B1); BAR;
;     LDA8(1, 1); STG_A(1, 0, t + 3);
;     BAR; WAIT_L(0); MMA8(1, 0, B0); BAR; SCHED;
;     STG_B(1, 1, t + 3);
;     WAIT_V(6); BAR; MMA8(1, 1, B1); BAR;
	ds_read_b128 v[146:149], v246
	ds_read_b128 v[150:153], v246 offset:1024
	ds_read_b128 v[154:157], v246 offset:2048
	ds_read_b128 v[158:161], v246 offset:3072
	ds_read_b128 v[162:165], v142 offset:32768
	ds_read_b128 v[166:169], v142 offset:33792
	ds_read_b128 v[170:173], v142 offset:34816
	ds_read_b128 v[174:177], v142 offset:35840
	ds_read_b128 v[180:183], v142 offset:36864
	ds_read_b128 v[184:187], v142 offset:37888
	ds_read_b128 v[188:191], v142 offset:38912
	ds_read_b128 v[192:195], v142 offset:39936
	ds_read_b128 v[196:199], v247
	ds_read_b128 v[200:203], v247 offset:1024
	ds_read_b128 v[204:207], v247 offset:2048
	ds_read_b128 v[208:211], v247 offset:3072
	s_add_u32 s0, s18, 0x100
	s_addc_u32 s1, s19, 0
	s_add_i32 s3, s7, 0x4000
	s_mov_b32 m0, s3
	s_nop 0
	global_load_lds_dwordx4 v144, s[0:1]
	s_add_i32 s3, s7, 0x6000
	s_mov_b32 m0, s3
	s_nop 0
	global_load_lds_dwordx4 v143, s[0:1]
	s_waitcnt vmcnt(8) lgkmcnt(0)
	s_barrier
	s_setprio 1
	v_mfma_f32_16x16x32_bf16 v[126:129], v[162:165], v[146:149], v[126:129]
	v_mfma_f32_16x16x32_bf16 v[122:125], v[162:165], v[154:157], v[122:125]
	v_mfma_f32_16x16x32_bf16 v[114:117], v[170:173], v[154:157], v[114:117]
	v_mfma_f32_16x16x32_bf16 v[118:121], v[170:173], v[146:149], v[118:121]
	v_mfma_f32_16x16x32_bf16 v[110:113], v[180:183], v[146:149], v[110:113]
	v_mfma_f32_16x16x32_bf16 v[106:109], v[180:183], v[154:157], v[106:109]
	v_mfma_f32_16x16x32_bf16 v[98:101], v[188:191], v[154:157], v[98:101]
	v_mfma_f32_16x16x32_bf16 v[102:105], v[188:191], v[146:149], v[102:105]
	v_mfma_f32_16x16x32_bf16 v[126:129], v[166:169], v[150:153], v[126:129]
	v_mfma_f32_16x16x32_bf16 v[122:125], v[166:169], v[158:161], v[122:125]
	v_mfma_f32_16x16x32_bf16 v[114:117], v[174:177], v[158:161], v[114:117]
	v_mfma_f32_16x16x32_bf16 v[118:121], v[174:177], v[150:153], v[118:121]
	v_mfma_f32_16x16x32_bf16 v[110:113], v[184:187], v[150:153], v[110:113]
	v_mfma_f32_16x16x32_bf16 v[106:109], v[184:187], v[158:161], v[106:109]
	v_mfma_f32_16x16x32_bf16 v[98:101], v[192:195], v[158:161], v[98:101]
	v_mfma_f32_16x16x32_bf16 v[102:105], v[192:195], v[150:153], v[102:105]
	v_mfma_f32_16x16x32_bf16 v[94:97], v[162:165], v[196:199], v[94:97]
	v_mfma_f32_16x16x32_bf16 v[90:93], v[162:165], v[204:207], v[90:93]
	v_mfma_f32_16x16x32_bf16 v[82:85], v[170:173], v[204:207], v[82:85]
	v_mfma_f32_16x16x32_bf16 v[86:89], v[170:173], v[196:199], v[86:89]
	v_mfma_f32_16x16x32_bf16 v[78:81], v[180:183], v[196:199], v[78:81]
	v_mfma_f32_16x16x32_bf16 v[74:77], v[180:183], v[204:207], v[74:77]
	v_mfma_f32_16x16x32_bf16 v[66:69], v[188:191], v[204:207], v[66:69]
	v_mfma_f32_16x16x32_bf16 v[70:73], v[188:191], v[196:199], v[70:73]
	v_mfma_f32_16x16x32_bf16 v[94:97], v[166:169], v[200:203], v[94:97]
	v_mfma_f32_16x16x32_bf16 v[90:93], v[166:169], v[208:211], v[90:93]
	v_mfma_f32_16x16x32_bf16 v[82:85], v[174:177], v[208:211], v[82:85]
	v_mfma_f32_16x16x32_bf16 v[86:89], v[174:177], v[200:203], v[86:89]
	v_mfma_f32_16x16x32_bf16 v[78:81], v[184:187], v[200:203], v[78:81]
	v_mfma_f32_16x16x32_bf16 v[74:77], v[184:187], v[208:211], v[74:77]
	v_mfma_f32_16x16x32_bf16 v[66:69], v[192:195], v[208:211], v[66:69]
	v_mfma_f32_16x16x32_bf16 v[70:73], v[192:195], v[200:203], v[70:73]
	s_setprio 0
	s_barrier
	ds_read_b128 v[162:165], v142 offset:49152
	ds_read_b128 v[166:169], v142 offset:50176
	ds_read_b128 v[170:173], v142 offset:51200
	ds_read_b128 v[174:177], v142 offset:52224
	ds_read_b128 v[180:183], v142 offset:53248
	ds_read_b128 v[184:187], v142 offset:54272
	ds_read_b128 v[188:191], v142 offset:55296
	ds_read_b128 v[192:195], v142 offset:56320
	s_add_u32 s0, s20, 0x180
	s_addc_u32 s1, s21, 0
	s_add_i32 s3, s7, 0x18000
	s_mov_b32 m0, s3
	s_nop 0
	global_load_lds_dwordx4 v144, s[0:1]
	s_add_i32 s3, s7, 0x1a000
	s_mov_b32 m0, s3
	s_nop 0
	global_load_lds_dwordx4 v143, s[0:1]
	s_add_u32 s0, s16, 0x180
	s_addc_u32 s1, s17, 0
	s_add_i32 s3, s7, 0x8000
	s_mov_b32 m0, s3
	s_nop 0
	global_load_lds_dwordx4 v144, s[0:1]
	s_add_i32 s3, s7, 0xa000
	s_mov_b32 m0, s3
	s_nop 0
	global_load_lds_dwordx4 v143, s[0:1]
	s_add_u32 s0, s22, 0x180
	s_addc_u32 s1, s23, 0
	s_add_i32 s3, s7, 0x1c000
	s_mov_b32 m0, s3
	s_nop 0
	global_load_lds_dwordx4 v144, s[0:1]
	s_add_i32 s3, s7, 0x1e000
	s_mov_b32 m0, s3
	s_nop 0
	global_load_lds_dwordx4 v143, s[0:1]
	s_waitcnt vmcnt(8) lgkmcnt(0)
	s_barrier
	s_setprio 1
	v_mfma_f32_16x16x32_bf16 v[62:65], v[162:165], v[146:149], v[62:65]
	v_mfma_f32_16x16x32_bf16 v[58:61], v[162:165], v[154:157], v[58:61]
	v_mfma_f32_16x16x32_bf16 v[50:53], v[170:173], v[154:157], v[50:53]
	v_mfma_f32_16x16x32_bf16 v[54:57], v[170:173], v[146:149], v[54:57]
	v_mfma_f32_16x16x32_bf16 v[46:49], v[180:183], v[146:149], v[46:49]
	v_mfma_f32_16x16x32_bf16 v[42:45], v[180:183], v[154:157], v[42:45]
	v_mfma_f32_16x16x32_bf16 v[34:37], v[188:191], v[154:157], v[34:37]
	v_mfma_f32_16x16x32_bf16 v[38:41], v[188:191], v[146:149], v[38:41]
	v_mfma_f32_16x16x32_bf16 v[62:65], v[166:169], v[150:153], v[62:65]
	v_mfma_f32_16x16x32_bf16 v[58:61], v[166:169], v[158:161], v[58:61]
	v_mfma_f32_16x16x32_bf16 v[50:53], v[174:177], v[158:161], v[50:53]
	v_mfma_f32_16x16x32_bf16 v[54:57], v[174:177], v[150:153], v[54:57]
	v_mfma_f32_16x16x32_bf16 v[46:49], v[184:187], v[150:153], v[46:49]
	v_mfma_f32_16x16x32_bf16 v[42:45], v[184:187], v[158:161], v[42:45]
	v_mfma_f32_16x16x32_bf16 v[34:37], v[192:195], v[158:161], v[34:37]
	v_mfma_f32_16x16x32_bf16 v[38:41], v[192:195], v[150:153], v[38:41]
	v_mfma_f32_16x16x32_bf16 v[30:33], v[162:165], v[196:199], v[30:33]
	v_mfma_f32_16x16x32_bf16 v[26:29], v[162:165], v[204:207], v[26:29]
	v_mfma_f32_16x16x32_bf16 v[18:21], v[170:173], v[204:207], v[18:21]
	v_mfma_f32_16x16x32_bf16 v[22:25], v[170:173], v[196:199], v[22:25]
	v_mfma_f32_16x16x32_bf16 v[14:17], v[180:183], v[196:199], v[14:17]
	v_mfma_f32_16x16x32_bf16 v[10:13], v[180:183], v[204:207], v[10:13]
	v_mfma_f32_16x16x32_bf16 v[2:5], v[188:191], v[204:207], v[2:5]
	v_mfma_f32_16x16x32_bf16 v[6:9], v[188:191], v[196:199], v[6:9]
	v_mfma_f32_16x16x32_bf16 v[30:33], v[166:169], v[200:203], v[30:33]
	v_mfma_f32_16x16x32_bf16 v[26:29], v[166:169], v[208:211], v[26:29]
	v_mfma_f32_16x16x32_bf16 v[18:21], v[174:177], v[208:211], v[18:21]
	v_mfma_f32_16x16x32_bf16 v[22:25], v[174:177], v[200:203], v[22:25]
	v_mfma_f32_16x16x32_bf16 v[14:17], v[184:187], v[200:203], v[14:17]
	v_mfma_f32_16x16x32_bf16 v[10:13], v[184:187], v[208:211], v[10:13]
	v_mfma_f32_16x16x32_bf16 v[2:5], v[192:195], v[208:211], v[2:5]
	v_mfma_f32_16x16x32_bf16 v[6:9], v[192:195], v[200:203], v[6:9]
	s_setprio 0
	s_barrier
	s_add_u32 s16, s16, 0x100
	s_addc_u32 s17, s17, 0
	s_add_u32 s18, s18, 0x100
	s_addc_u32 s19, s19, 0
	s_add_u32 s20, s20, 0x100
	s_addc_u32 s21, s21, 0
	s_add_u32 s22, s22, 0x100
	s_addc_u32 s23, s23, 0
	s_mov_b32 s14, 6
; #define WAIT_V(n) asm volatile("s_waitcnt vmcnt(" #n ")" ::: "memory")
; #define WAIT_L(n) asm volatile("s_waitcnt lgkmcnt(" #n ")" ::: "memory")
; #define BAR __builtin_amdgcn_s_barrier()
; #define SCHED __builtin_amdgcn_sched_barrier(0)
; #define STG_A(b, h, kt) stage_half_s(lds0 + ((b) * 2 + (h)) * HT_B, ((h) ? A1 : Ap) + (kt) * BK, off0, off1)
; #define STG_B(b, h, kt) stage_half_s(lds0 + (4 + (b) * 2 + (h)) * HT_B, ((h) ? B1p : Bp) + (kt) * BK, off0, off1)
; #define STG_A(b, h, kt) stage_half_s(lds0 + ((b) * 2 + (h)) * HT_B, ((h) ? A1 : Ap) + (kt) * BK, off0, off1)
; #define STG_B(b, h, kt) stage_half_s(lds0 + (4 + (b) * 2 + (h)) * HT_B, ((h) ? B1p : Bp) + (kt) * BK, off0, off1)
; #define LDA8(b, h) _Pragma("unroll") for (int m = 0; m < 4; ++m) _Pragma("unroll") for (int k = 0; k < 2; ++k) \
;     At[m][k] = *(const bf16x8*)(SA_(shm, b, h) + abase + (m * 2 + k) * 1024)
; #define LDB8(dst, b, h) _Pragma("unroll") for (int n = 0; n < 2; ++n) _Pragma("unroll") for (int k = 0; k < 2; ++k) \
;     dst[n][k] = *(const bf16x8*)(SB_(shm, b, h) + bbase + (n * 2 + k) * 1024)
; template <bool HS>
; __device__ __forceinline__ void gemm_tile8(const u16* __restrict__ Ap, const u16* __restrict__ Bp, int K,
;                                            f32x4 (&acc)[2][2][4][2], char* shm, const int tid, const float* hsr = nullptr) {
;     ...
;     LDB8(B0, 0, 0); SCHED; LDA8(0, 0); STG_A(1, 1, t + 1);
;     WAIT_L(8); BAR; WAIT_L(0); MMA8(0, 0, B0); BAR; SCHED;
;     LDB8(B1, 0, 1); STG_B(0, 0, t + 2);
;     BAR; WAIT_L(0); MMA8(0, 1, B1); BAR;
;     LDA8(0, 1); STG_A(0, 0, t + 2);
;     BAR; WAIT_L(0); MMA8(1, 0, B0); BAR; SCHED;
;     STG_B(0, 1, t + 2);
;     WAIT_V(6); BAR; MMA8(1, 1, B1); BAR;
;     LDB8(B0, 1, 0); SCHED; LDA8(1, 0); STG_A(0, 1, t + 2);
;     WAIT_L(8); BAR; WAIT_L(0); MMA8(0, 0, B0); BAR; SCHED;
;     LDB8(B1, 1, 1); STG_B(1, 0, t + 3);
;     BAR; WAIT_L(0); MMA8(0, 1, B1); BAR;
;     LDA8(1, 1); STG_A(1, 0, t + 3);
;     BAR; WAIT_L(0); MMA8(1, 0, B0); BAR; SCHED;
;     STG_B(1, 1, t + 3);
;     WAIT_V(6); BAR; MMA8(1, 1, B1); BAR;
.Lk_ffn_in:
	ds_read_b128 v[146:149], v244
	ds_read_b128 v[150:153], v244 offset:1024
	ds_read_b128 v[154:157], v244 offset:2048
	ds_read_b128 v[158:161], v244 offset:3072
	ds_read_b128 v[162:165], v142
	ds_read_b128 v[166:169], v142 offset:1024
	ds_read_b128 v[170:173], v142 offset:2048
	ds_read_b128 v[174:177], v142 offset:3072
	ds_read_b128 v[180:183], v142 offset:4096
	ds_read_b128 v[184:187], v142 offset:5120
	ds_read_b128 v[188:191], v142 offset:6144
	ds_read_b128 v[192:195], v142 offset:7168
	ds_read_b128 v[196:199], v245
	ds_read_b128 v[200:203], v245 offset:1024
	ds_read_b128 v[204:207], v245 offset:2048
	ds_read_b128 v[208:211], v245 offset:3072
	s_add_u32 s0, s18, 0x80
	s_addc_u32 s1, s19, 0
	s_add_i32 s3, s7, 0xc000
	s_mov_b32 m0, s3
	s_nop 0
	global_load_lds_dwordx4 v144, s[0:1]
	s_add_i32 s3, s7, 0xe000
	s_mov_b32 m0, s3
	s_nop 0
	global_load_lds_dwordx4 v143, s[0:1]
	s_waitcnt vmcnt(8) lgkmcnt(0)
	s_barrier
	s_setprio 1
	v_mfma_f32_16x16x32_bf16 v[126:129], v[162:165], v[146:149], v[126:129]
	v_mfma_f32_16x16x32_bf16 v[122:125], v[162:165], v[154:157], v[122:125]
	v_mfma_f32_16x16x32_bf16 v[114:117], v[170:173], v[154:157], v[114:117]
	v_mfma_f32_16x16x32_bf16 v[118:121], v[170:173], v[146:149], v[118:121]
	v_mfma_f32_16x16x32_bf16 v[110:113], v[180:183], v[146:149], v[110:113]
	v_mfma_f32_16x16x32_bf16 v[106:109], v[180:183], v[154:157], v[106:109]
	v_mfma_f32_16x16x32_bf16 v[98:101], v[188:191], v[154:157], v[98:101]
	v_mfma_f32_16x16x32_bf16 v[102:105], v[188:191], v[146:149], v[102:105]
	v_mfma_f32_16x16x32_bf16 v[126:129], v[166:169], v[150:153], v[126:129]
	v_mfma_f32_16x16x32_bf16 v[122:125], v[166:169], v[158:161], v[122:125]
	v_mfma_f32_16x16x32_bf16 v[114:117], v[174:177], v[158:161], v[114:117]
	v_mfma_f32_16x16x32_bf16 v[118:121], v[174:177], v[150:153], v[118:121]
	v_mfma_f32_16x16x32_bf16 v[110:113], v[184:187], v[150:153], v[110:113]
	v_mfma_f32_16x16x32_bf16 v[106:109], v[184:187], v[158:161], v[106:109]
	v_mfma_f32_16x16x32_bf16 v[98:101], v[192:195], v[158:161], v[98:101]
	v_mfma_f32_16x16x32_bf16 v[102:105], v[192:195], v[150:153], v[102:105]
	v_mfma_f32_16x16x32_bf16 v[94:97], v[162:165], v[196:199], v[94:97]
	v_mfma_f32_16x16x32_bf16 v[90:93], v[162:165], v[204:207], v[90:93]
	v_mfma_f32_16x16x32_bf16 v[82:85], v[170:173], v[204:207], v[82:85]
	v_mfma_f32_16x16x32_bf16 v[86:89], v[170:173], v[196:199], v[86:89]
	v_mfma_f32_16x16x32_bf16 v[78:81], v[180:183], v[196:199], v[78:81]
	v_mfma_f32_16x16x32_bf16 v[74:77], v[180:183], v[204:207], v[74:77]
	v_mfma_f32_16x16x32_bf16 v[66:69], v[188:191], v[204:207], v[66:69]
	v_mfma_f32_16x16x32_bf16 v[70:73], v[188:191], v[196:199], v[70:73]
	v_mfma_f32_16x16x32_bf16 v[94:97], v[166:169], v[200:203], v[94:97]
	v_mfma_f32_16x16x32_bf16 v[90:93], v[166:169], v[208:211], v[90:93]
	v_mfma_f32_16x16x32_bf16 v[82:85], v[174:177], v[208:211], v[82:85]
	v_mfma_f32_16x16x32_bf16 v[86:89], v[174:177], v[200:203], v[86:89]
	v_mfma_f32_16x16x32_bf16 v[78:81], v[184:187], v[200:203], v[78:81]
	v_mfma_f32_16x16x32_bf16 v[74:77], v[184:187], v[208:211], v[74:77]
	v_mfma_f32_16x16x32_bf16 v[66:69], v[192:195], v[208:211], v[66:69]
	v_mfma_f32_16x16x32_bf16 v[70:73], v[192:195], v[200:203], v[70:73]
	s_setprio 0
	s_barrier
	ds_read_b128 v[162:165], v142 offset:16384
	ds_read_b128 v[166:169], v142 offset:17408
	ds_read_b128 v[170:173], v142 offset:18432
	ds_read_b128 v[174:177], v142 offset:19456
	ds_read_b128 v[180:183], v142 offset:20480
	ds_read_b128 v[184:187], v142 offset:21504
	ds_read_b128 v[188:191], v142 offset:22528
	ds_read_b128 v[192:195], v142 offset:23552
	s_add_u32 s0, s20, 0x100
	s_addc_u32 s1, s21, 0
	s_add_i32 s3, s7, 0x10000
	s_mov_b32 m0, s3
	s_nop 0
	global_load_lds_dwordx4 v144, s[0:1]
	s_add_i32 s3, s7, 0x12000
	s_mov_b32 m0, s3
	s_nop 0
	global_load_lds_dwordx4 v143, s[0:1]
	s_add_u32 s0, s16, 0x100
	s_addc_u32 s1, s17, 0
	s_mov_b32 m0, s7
	s_nop 0
	global_load_lds_dwordx4 v144, s[0:1]
	s_add_i32 s3, s7, 0x2000
	s_mov_b32 m0, s3
	s_nop 0
	global_load_lds_dwordx4 v143, s[0:1]
	s_add_u32 s0, s22, 0x100
	s_addc_u32 s1, s23, 0
	s_add_i32 s3, s7, 0x14000
	s_mov_b32 m0, s3
	s_nop 0
	global_load_lds_dwordx4 v144, s[0:1]
	s_add_i32 s3, s7, 0x16000
	s_mov_b32 m0, s3
	s_nop 0
	global_load_lds_dwordx4 v143, s[0:1]
	s_waitcnt vmcnt(8) lgkmcnt(0)
	s_barrier
	s_setprio 1
	v_mfma_f32_16x16x32_bf16 v[62:65], v[162:165], v[146:149], v[62:65]
	v_mfma_f32_16x16x32_bf16 v[58:61], v[162:165], v[154:157], v[58:61]
	v_mfma_f32_16x16x32_bf16 v[50:53], v[170:173], v[154:157], v[50:53]
	v_mfma_f32_16x16x32_bf16 v[54:57], v[170:173], v[146:149], v[54:57]
	v_mfma_f32_16x16x32_bf16 v[46:49], v[180:183], v[146:149], v[46:49]
	v_mfma_f32_16x16x32_bf16 v[42:45], v[180:183], v[154:157], v[42:45]
	v_mfma_f32_16x16x32_bf16 v[34:37], v[188:191], v[154:157], v[34:37]
	v_mfma_f32_16x16x32_bf16 v[38:41], v[188:191], v[146:149], v[38:41]
	v_mfma_f32_16x16x32_bf16 v[62:65], v[166:169], v[150:153], v[62:65]
	v_mfma_f32_16x16x32_bf16 v[58:61], v[166:169], v[158:161], v[58:61]
	v_mfma_f32_16x16x32_bf16 v[50:53], v[174:177], v[158:161], v[50:53]
	v_mfma_f32_16x16x32_bf16 v[54:57], v[174:177], v[150:153], v[54:57]
	v_mfma_f32_16x16x32_bf16 v[46:49], v[184:187], v[150:153], v[46:49]
	v_mfma_f32_16x16x32_bf16 v[42:45], v[184:187], v[158:161], v[42:45]
	v_mfma_f32_16x16x32_bf16 v[34:37], v[192:195], v[158:161], v[34:37]
	v_mfma_f32_16x16x32_bf16 v[38:41], v[192:195], v[150:153], v[38:41]
	v_mfma_f32_16x16x32_bf16 v[30:33], v[162:165], v[196:199], v[30:33]
	v_mfma_f32_16x16x32_bf16 v[26:29], v[162:165], v[204:207], v[26:29]
	v_mfma_f32_16x16x32_bf16 v[18:21], v[170:173], v[204:207], v[18:21]
	v_mfma_f32_16x16x32_bf16 v[22:25], v[170:173], v[196:199], v[22:25]
	v_mfma_f32_16x16x32_bf16 v[14:17], v[180:183], v[196:199], v[14:17]
	v_mfma_f32_16x16x32_bf16 v[10:13], v[180:183], v[204:207], v[10:13]
	v_mfma_f32_16x16x32_bf16 v[2:5], v[188:191], v[204:207], v[2:5]
	v_mfma_f32_16x16x32_bf16 v[6:9], v[188:191], v[196:199], v[6:9]
	v_mfma_f32_16x16x32_bf16 v[30:33], v[166:169], v[200:203], v[30:33]
	v_mfma_f32_16x16x32_bf16 v[26:29], v[166:169], v[208:211], v[26:29]
	v_mfma_f32_16x16x32_bf16 v[18:21], v[174:177], v[208:211], v[18:21]
	v_mfma_f32_16x16x32_bf16 v[22:25], v[174:177], v[200:203], v[22:25]
	v_mfma_f32_16x16x32_bf16 v[14:17], v[184:187], v[200:203], v[14:17]
	v_mfma_f32_16x16x32_bf16 v[10:13], v[184:187], v[208:211], v[10:13]
	v_mfma_f32_16x16x32_bf16 v[2:5], v[192:195], v[208:211], v[2:5]
	v_mfma_f32_16x16x32_bf16 v[6:9], v[192:195], v[200:203], v[6:9]
	s_setprio 0
	s_barrier
; #define WAIT_V(n) asm volatile("s_waitcnt vmcnt(" #n ")" ::: "memory")
; #define WAIT_L(n) asm volatile("s_waitcnt lgkmcnt(" #n ")" ::: "memory")
; #define BAR __builtin_amdgcn_s_barrier()
; #define SCHED __builtin_amdgcn_sched_barrier(0)
; #define STG_A(b, h, kt) stage_half_s(lds0 + ((b) * 2 + (h)) * HT_B, ((h) ? A1 : Ap) + (kt) * BK, off0, off1)
; #define STG_B(b, h, kt) stage_half_s(lds0 + (4 + (b) * 2 + (h)) * HT_B, ((h) ? B1p : Bp) + (kt) * BK, off0, off1)
; #define STG_A(b, h, kt) stage_half_s(lds0 + ((b) * 2 + (h)) * HT_B, ((h) ? A1 : Ap) + (kt) * BK, off0, off1)
; #define STG_B(b, h, kt) stage_half_s(lds0 + (4 + (b) * 2 + (h)) * HT_B, ((h) ? B1p : Bp) + (kt) * BK, off0, off1)
; #define LDA8(b, h) _Pragma("unroll") for (int m = 0; m < 4; ++m) _Pragma("unroll") for (int k = 0; k < 2; ++k) \
;     At[m][k] = *(const bf16x8*)(SA_(shm, b, h) + abase + (m * 2 + k) * 1024)
; #define LDB8(dst, b, h) _Pragma("unroll") for (int n = 0; n < 2; ++n) _Pragma("unroll") for (int k = 0; k < 2; ++k) \
;     dst[n][k] = *(const bf16x8*)(SB_(shm, b, h) + bbase + (n * 2 + k) * 1024)
; template <bool HS>
; __device__ __forceinline__ void gemm_tile8(const u16* __restrict__ Ap, const u16* __restrict__ Bp, int K,
;                                            f32x4 (&acc)[2][2][4][2], char* shm, const int tid, const float* hsr = nullptr) {
;     ...
;     LDB8(B0, 0, 0); SCHED; LDA8(0, 0); STG_A(1, 1, t + 1);
;     WAIT_L(8); BAR; WAIT_L(0); MMA8(0, 0, B0); BAR; SCHED;
;     LDB8(B1, 0, 1); STG_B(0, 0, t + 2);
;     BAR; WAIT_L(0); MMA8(0, 1, B1); BAR;
;     LDA8(0, 1); STG_A(0, 0, t + 2);
;     BAR; WAIT_L(0); MMA8(1, 0, B0); BAR; SCHED;
;     STG_B(0, 1, t + 2);
;     WAIT_V(6); BAR; MMA8(1, 1, B1); BAR;
;     LDB8(B0, 1, 0); SCHED; LDA8(1, 0); STG_A(0, 1, t + 2);
;     WAIT_L(8); BAR; WAIT_L(0); MMA8(0, 0, B0); BAR; SCHED;
;     LDB8(B1, 1, 1); STG_B(1, 0, t + 3);
;     BAR; WAIT_L(0); MMA8(0, 1, B1); BAR;
;     LDA8(1, 1); STG_A(1, 0, t + 3);
;     BAR; WAIT_L(0); MMA8(1, 0, B0); BAR; SCHED;
;     STG_B(1, 1, t + 3);
;     WAIT_V(6); BAR; MMA8(1, 1, B1); BAR;
	ds_read_b128 v[146:149], v246
	ds_read_b128 v[150:153], v246 offset:1024
	ds_read_b128 v[154:157], v246 offset:2048
	ds_read_b128 v[158:161], v246 offset:3072
	ds_read_b128 v[162:165], v142 offset:32768
	ds_read_b128 v[166:169], v142 offset:33792
	ds_read_b128 v[170:173], v142 offset:34816
	ds_read_b128 v[174:177], v142 offset:35840
	ds_read_b128 v[180:183], v142 offset:36864
	ds_read_b128 v[184:187], v142 offset:37888
	ds_read_b128 v[188:191], v142 offset:38912
	ds_read_b128 v[192:195], v142 offset:39936
	ds_read_b128 v[196:199], v247
	ds_read_b128 v[200:203], v247 offset:1024
	ds_read_b128 v[204:207], v247 offset:2048
	ds_read_b128 v[208:211], v247 offset:3072
	s_add_u32 s0, s18, 0x100
	s_addc_u32 s1, s19, 0
	s_add_i32 s3, s7, 0x4000
	s_mov_b32 m0, s3
	s_nop 0
	global_load_lds_dwordx4 v144, s[0:1]
	s_add_i32 s3, s7, 0x6000
	s_mov_b32 m0, s3
	s_nop 0
	global_load_lds_dwordx4 v143, s[0:1]
	s_waitcnt vmcnt(8) lgkmcnt(0)
	s_barrier
	s_setprio 1
	v_mfma_f32_16x16x32_bf16 v[126:129], v[162:165], v[146:149], v[126:129]
	v_mfma_f32_16x16x32_bf16 v[122:125], v[162:165], v[154:157], v[122:125]
	v_mfma_f32_16x16x32_bf16 v[114:117], v[170:173], v[154:157], v[114:117]
	v_mfma_f32_16x16x32_bf16 v[118:121], v[170:173], v[146:149], v[118:121]
	v_mfma_f32_16x16x32_bf16 v[110:113], v[180:183], v[146:149], v[110:113]
	v_mfma_f32_16x16x32_bf16 v[106:109], v[180:183], v[154:157], v[106:109]
	v_mfma_f32_16x16x32_bf16 v[98:101], v[188:191], v[154:157], v[98:101]
	v_mfma_f32_16x16x32_bf16 v[102:105], v[188:191], v[146:149], v[102:105]
	v_mfma_f32_16x16x32_bf16 v[126:129], v[166:169], v[150:153], v[126:129]
	v_mfma_f32_16x16x32_bf16 v[122:125], v[166:169], v[158:161], v[122:125]
	v_mfma_f32_16x16x32_bf16 v[114:117], v[174:177], v[158:161], v[114:117]
	v_mfma_f32_16x16x32_bf16 v[118:121], v[174:177], v[150:153], v[118:121]
	v_mfma_f32_16x16x32_bf16 v[110:113], v[184:187], v[150:153], v[110:113]
	v_mfma_f32_16x16x32_bf16 v[106:109], v[184:187], v[158:161], v[106:109]
	v_mfma_f32_16x16x32_bf16 v[98:101], v[192:195], v[158:161], v[98:101]
	v_mfma_f32_16x16x32_bf16 v[102:105], v[192:195], v[150:153], v[102:105]
	v_mfma_f32_16x16x32_bf16 v[94:97], v[162:165], v[196:199], v[94:97]
	v_mfma_f32_16x16x32_bf16 v[90:93], v[162:165], v[204:207], v[90:93]
	v_mfma_f32_16x16x32_bf16 v[82:85], v[170:173], v[204:207], v[82:85]
	v_mfma_f32_16x16x32_bf16 v[86:89], v[170:173], v[196:199], v[86:89]
	v_mfma_f32_16x16x32_bf16 v[78:81], v[180:183], v[196:199], v[78:81]
	v_mfma_f32_16x16x32_bf16 v[74:77], v[180:183], v[204:207], v[74:77]
	v_mfma_f32_16x16x32_bf16 v[66:69], v[188:191], v[204:207], v[66:69]
	v_mfma_f32_16x16x32_bf16 v[70:73], v[188:191], v[196:199], v[70:73]
	v_mfma_f32_16x16x32_bf16 v[94:97], v[166:169], v[200:203], v[94:97]
	v_mfma_f32_16x16x32_bf16 v[90:93], v[166:169], v[208:211], v[90:93]
	v_mfma_f32_16x16x32_bf16 v[82:85], v[174:177], v[208:211], v[82:85]
	v_mfma_f32_16x16x32_bf16 v[86:89], v[174:177], v[200:203], v[86:89]
	v_mfma_f32_16x16x32_bf16 v[78:81], v[184:187], v[200:203], v[78:81]
	v_mfma_f32_16x16x32_bf16 v[74:77], v[184:187], v[208:211], v[74:77]
	v_mfma_f32_16x16x32_bf16 v[66:69], v[192:195], v[208:211], v[66:69]
	v_mfma_f32_16x16x32_bf16 v[70:73], v[192:195], v[200:203], v[70:73]
	s_setprio 0
	s_barrier
	ds_read_b128 v[162:165], v142 offset:49152
	ds_read_b128 v[166:169], v142 offset:50176
	ds_read_b128 v[170:173], v142 offset:51200
	ds_read_b128 v[174:177], v142 offset:52224
	ds_read_b128 v[180:183], v142 offset:53248
	ds_read_b128 v[184:187], v142 offset:54272
	ds_read_b128 v[188:191], v142 offset:55296
	ds_read_b128 v[192:195], v142 offset:56320
	s_add_u32 s0, s20, 0x180
	s_addc_u32 s1, s21, 0
	s_add_i32 s3, s7, 0x18000
	s_mov_b32 m0, s3
	s_nop 0
	global_load_lds_dwordx4 v144, s[0:1]
	s_add_i32 s3, s7, 0x1a000
	s_mov_b32 m0, s3
	s_nop 0
	global_load_lds_dwordx4 v143, s[0:1]
	s_add_u32 s0, s16, 0x180
	s_addc_u32 s1, s17, 0
	s_add_i32 s3, s7, 0x8000
	s_mov_b32 m0, s3
	s_nop 0
	global_load_lds_dwordx4 v144, s[0:1]
	s_add_i32 s3, s7, 0xa000
	s_mov_b32 m0, s3
	s_nop 0
	global_load_lds_dwordx4 v143, s[0:1]
	s_add_u32 s0, s22, 0x180
	s_addc_u32 s1, s23, 0
	s_add_i32 s3, s7, 0x1c000
	s_mov_b32 m0, s3
	s_nop 0
	global_load_lds_dwordx4 v144, s[0:1]
	s_add_i32 s3, s7, 0x1e000
	s_mov_b32 m0, s3
	s_nop 0
	global_load_lds_dwordx4 v143, s[0:1]
	s_waitcnt vmcnt(8) lgkmcnt(0)
	s_barrier
	s_setprio 1
	v_mfma_f32_16x16x32_bf16 v[62:65], v[162:165], v[146:149], v[62:65]
	v_mfma_f32_16x16x32_bf16 v[58:61], v[162:165], v[154:157], v[58:61]
	v_mfma_f32_16x16x32_bf16 v[50:53], v[170:173], v[154:157], v[50:53]
	v_mfma_f32_16x16x32_bf16 v[54:57], v[170:173], v[146:149], v[54:57]
	v_mfma_f32_16x16x32_bf16 v[46:49], v[180:183], v[146:149], v[46:49]
	v_mfma_f32_16x16x32_bf16 v[42:45], v[180:183], v[154:157], v[42:45]
	v_mfma_f32_16x16x32_bf16 v[34:37], v[188:191], v[154:157], v[34:37]
	v_mfma_f32_16x16x32_bf16 v[38:41], v[188:191], v[146:149], v[38:41]
	v_mfma_f32_16x16x32_bf16 v[62:65], v[166:169], v[150:153], v[62:65]
	v_mfma_f32_16x16x32_bf16 v[58:61], v[166:169], v[158:161], v[58:61]
	v_mfma_f32_16x16x32_bf16 v[50:53], v[174:177], v[158:161], v[50:53]
	v_mfma_f32_16x16x32_bf16 v[54:57], v[174:177], v[150:153], v[54:57]
	v_mfma_f32_16x16x32_bf16 v[46:49], v[184:187], v[150:153], v[46:49]
	v_mfma_f32_16x16x32_bf16 v[42:45], v[184:187], v[158:161], v[42:45]
	v_mfma_f32_16x16x32_bf16 v[34:37], v[192:195], v[158:161], v[34:37]
	v_mfma_f32_16x16x32_bf16 v[38:41], v[192:195], v[150:153], v[38:41]
	v_mfma_f32_16x16x32_bf16 v[30:33], v[162:165], v[196:199], v[30:33]
	v_mfma_f32_16x16x32_bf16 v[26:29], v[162:165], v[204:207], v[26:29]
	v_mfma_f32_16x16x32_bf16 v[18:21], v[170:173], v[204:207], v[18:21]
	v_mfma_f32_16x16x32_bf16 v[22:25], v[170:173], v[196:199], v[22:25]
	v_mfma_f32_16x16x32_bf16 v[14:17], v[180:183], v[196:199], v[14:17]
	v_mfma_f32_16x16x32_bf16 v[10:13], v[180:183], v[204:207], v[10:13]
	v_mfma_f32_16x16x32_bf16 v[2:5], v[188:191], v[204:207], v[2:5]
	v_mfma_f32_16x16x32_bf16 v[6:9], v[188:191], v[196:199], v[6:9]
	v_mfma_f32_16x16x32_bf16 v[30:33], v[166:169], v[200:203], v[30:33]
	v_mfma_f32_16x16x32_bf16 v[26:29], v[166:169], v[208:211], v[26:29]
	v_mfma_f32_16x16x32_bf16 v[18:21], v[174:177], v[208:211], v[18:21]
	v_mfma_f32_16x16x32_bf16 v[22:25], v[174:177], v[200:203], v[22:25]
	v_mfma_f32_16x16x32_bf16 v[14:17], v[184:187], v[200:203], v[14:17]
	v_mfma_f32_16x16x32_bf16 v[10:13], v[184:187], v[208:211], v[10:13]
	v_mfma_f32_16x16x32_bf16 v[2:5], v[192:195], v[208:211], v[2:5]
	v_mfma_f32_16x16x32_bf16 v[6:9], v[192:195], v[200:203], v[6:9]
	s_setprio 0
	s_barrier
; #define WAIT_V(n) asm volatile("s_waitcnt vmcnt(" #n ")" ::: "memory")
; #define WAIT_L(n) asm volatile("s_waitcnt lgkmcnt(" #n ")" ::: "memory")
; #define BAR __builtin_amdgcn_s_barrier()
; #define SCHED __builtin_amdgcn_sched_barrier(0)
; #define STG_A(b, h, kt) stage_half_s(lds0 + ((b) * 2 + (h)) * HT_B, ((h) ? A1 : Ap) + (kt) * BK, off0, off1)
; #define STG_B(b, h, kt) stage_half_s(lds0 + (4 + (b) * 2 + (h)) * HT_B, ((h) ? B1p : Bp) + (kt) * BK, off0, off1)
; #define STG_A(b, h, kt) stage_half_s(lds0 + ((b) * 2 + (h)) * HT_B, ((h) ? A1 : Ap) + (kt) * BK, off0, off1)
; #define STG_B(b, h, kt) stage_half_s(lds0 + (4 + (b) * 2 + (h)) * HT_B, ((h) ? B1p : Bp) + (kt) * BK, off0, off1)
; #define LDA8(b, h) _Pragma("unroll") for (int m = 0; m < 4; ++m) _Pragma("unroll") for (int k = 0; k < 2; ++k) \
;     At[m][k] = *(const bf16x8*)(SA_(shm, b, h) + abase + (m * 2 + k) * 1024)
; #define LDB8(dst, b, h) _Pragma("unroll") for (int n = 0; n < 2; ++n) _Pragma("unroll") for (int k = 0; k < 2; ++k) \
;     dst[n][k] = *(const bf16x8*)(SB_(shm, b, h) + bbase + (n * 2 + k) * 1024)
; template <bool HS>
; __device__ __forceinline__ void gemm_tile8(const u16* __restrict__ Ap, const u16* __restrict__ Bp, int K,
;                                            f32x4 (&acc)[2][2][4][2], char* shm, const int tid, const float* hsr = nullptr) {
;     ...
;     LDB8(B0, 0, 0); SCHED; LDA8(0, 0); STG_A(1, 1, t + 1);
;     WAIT_L(8); BAR; WAIT_L(0); MMA8(0, 0, B0); BAR; SCHED;
;     LDB8(B1, 0, 1); STG_B(0, 0, t + 2);
;     BAR; WAIT_L(0); MMA8(0, 1, B1); BAR;
;     LDA8(0, 1); STG_A(0, 0, t + 2);
;     BAR; WAIT_L(0); MMA8(1, 0, B0); BAR; SCHED;
;     STG_B(0, 1, t + 2);
;     WAIT_V(6); BAR; MMA8(1, 1, B1); BAR;
;     LDB8(B0, 1, 0); SCHED; LDA8(1, 0); STG_A(0, 1, t + 2);
;     WAIT_L(8); BAR; WAIT_L(0); MMA8(0, 0, B0); BAR; SCHED;
;     LDB8(B1, 1, 1); STG_B(1, 0, t + 3);
;     BAR; WAIT_L(0); MMA8(0, 1, B1); BAR;
;     LDA8(1, 1); STG_A(1, 0, t + 3);
;     BAR; WAIT_L(0); MMA8(1, 0, B0); BAR; SCHED;
;     STG_B(1, 1, t + 3);
;     WAIT_V(6); BAR; MMA8(1, 1, B1); BAR;
;   }
;   { LDB8(B0, 0, 0); LDA8(0, 0); STG_A(1, 1, nt - 1);
;     BAR; WAIT_L(0); MMA8(0, 0, B0); BAR;
;     LDB8(B1, 0, 1); BAR; WAIT_L(0); MMA8(0, 1, B1); BAR;
;     LDA8(0, 1); WAIT_V(4); BAR; WAIT_L(0); MMA8(1, 0, B0); MMA8(1, 1, B1); BAR; }
	s_add_u32 s16, s16, 0x100
	s_addc_u32 s17, s17, 0
	s_add_u32 s18, s18, 0x100
	s_addc_u32 s19, s19, 0
	s_add_u32 s20, s20, 0x100
	s_addc_u32 s21, s21, 0
	s_add_u32 s22, s22, 0x100
	s_addc_u32 s23, s23, 0
	s_sub_i32 s14, s14, 1
	s_cmp_lg_u32 s14, 0
	s_cbranch_scc1 .Lk_ffn_in
	ds_read_b128 v[146:149], v244
	ds_read_b128 v[150:153], v244 offset:1024
	ds_read_b128 v[154:157], v244 offset:2048
	ds_read_b128 v[158:161], v244 offset:3072
	ds_read_b128 v[162:165], v142
	ds_read_b128 v[166:169], v142 offset:1024
	ds_read_b128 v[170:173], v142 offset:2048
	ds_read_b128 v[174:177], v142 offset:3072
	ds_read_b128 v[180:183], v142 offset:4096
	ds_read_b128 v[184:187], v142 offset:5120
	ds_read_b128 v[188:191], v142 offset:6144
	ds_read_b128 v[192:195], v142 offset:7168
	ds_read_b128 v[196:199], v245
	ds_read_b128 v[200:203], v245 offset:1024
	ds_read_b128 v[204:207], v245 offset:2048
	ds_read_b128 v[208:211], v245 offset:3072
	s_add_u32 s0, s18, 0x80
	s_addc_u32 s1, s19, 0
	s_add_i32 s3, s7, 0xc000
	s_mov_b32 m0, s3
	s_nop 0
	global_load_lds_dwordx4 v144, s[0:1]
	s_add_i32 s3, s7, 0xe000
	s_mov_b32 m0, s3
	s_nop 0
	global_load_lds_dwordx4 v143, s[0:1]
	s_waitcnt vmcnt(8) lgkmcnt(0)
	s_barrier
	s_setprio 1
	v_mfma_f32_16x16x32_bf16 v[126:129], v[162:165], v[146:149], v[126:129]
	v_mfma_f32_16x16x32_bf16 v[122:125], v[162:165], v[154:157], v[122:125]
	v_mfma_f32_16x16x32_bf16 v[114:117], v[170:173], v[154:157], v[114:117]
	v_mfma_f32_16x16x32_bf16 v[118:121], v[170:173], v[146:149], v[118:121]
	v_mfma_f32_16x16x32_bf16 v[110:113], v[180:183], v[146:149], v[110:113]
	v_mfma_f32_16x16x32_bf16 v[106:109], v[180:183], v[154:157], v[106:109]
	v_mfma_f32_16x16x32_bf16 v[98:101], v[188:191], v[154:157], v[98:101]
	v_mfma_f32_16x16x32_bf16 v[102:105], v[188:191], v[146:149], v[102:105]
	v_mfma_f32_16x16x32_bf16 v[126:129], v[166:169], v[150:153], v[126:129]
	v_mfma_f32_16x16x32_bf16 v[122:125], v[166:169], v[158:161], v[122:125]
	v_mfma_f32_16x16x32_bf16 v[114:117], v[174:177], v[158:161], v[114:117]
	v_mfma_f32_16x16x32_bf16 v[118:121], v[174:177], v[150:153], v[118:121]
	v_mfma_f32_16x16x32_bf16 v[110:113], v[184:187], v[150:153], v[110:113]
	v_mfma_f32_16x16x32_bf16 v[106:109], v[184:187], v[158:161], v[106:109]
	v_mfma_f32_16x16x32_bf16 v[98:101], v[192:195], v[158:161], v[98:101]
	v_mfma_f32_16x16x32_bf16 v[102:105], v[192:195], v[150:153], v[102:105]
	v_mfma_f32_16x16x32_bf16 v[94:97], v[162:165], v[196:199], v[94:97]
	v_mfma_f32_16x16x32_bf16 v[90:93], v[162:165], v[204:207], v[90:93]
	v_mfma_f32_16x16x32_bf16 v[82:85], v[170:173], v[204:207], v[82:85]
	v_mfma_f32_16x16x32_bf16 v[86:89], v[170:173], v[196:199], v[86:89]
	v_mfma_f32_16x16x32_bf16 v[78:81], v[180:183], v[196:199], v[78:81]
	v_mfma_f32_16x16x32_bf16 v[74:77], v[180:183], v[204:207], v[74:77]
	v_mfma_f32_16x16x32_bf16 v[66:69], v[188:191], v[204:207], v[66:69]
	v_mfma_f32_16x16x32_bf16 v[70:73], v[188:191], v[196:199], v[70:73]
	v_mfma_f32_16x16x32_bf16 v[94:97], v[166:169], v[200:203], v[94:97]
	v_mfma_f32_16x16x32_bf16 v[90:93], v[166:169], v[208:211], v[90:93]
	v_mfma_f32_16x16x32_bf16 v[82:85], v[174:177], v[208:211], v[82:85]
	v_mfma_f32_16x16x32_bf16 v[86:89], v[174:177], v[200:203], v[86:89]
	v_mfma_f32_16x16x32_bf16 v[78:81], v[184:187], v[200:203], v[78:81]
	v_mfma_f32_16x16x32_bf16 v[74:77], v[184:187], v[208:211], v[74:77]
	v_mfma_f32_16x16x32_bf16 v[66:69], v[192:195], v[208:211], v[66:69]
	v_mfma_f32_16x16x32_bf16 v[70:73], v[192:195], v[200:203], v[70:73]
	s_setprio 0
	s_barrier
	ds_read_b128 v[162:165], v142 offset:16384
	ds_read_b128 v[166:169], v142 offset:17408
	ds_read_b128 v[170:173], v142 offset:18432
	ds_read_b128 v[174:177], v142 offset:19456
	ds_read_b128 v[180:183], v142 offset:20480
	ds_read_b128 v[184:187], v142 offset:21504
	ds_read_b128 v[188:191], v142 offset:22528
	ds_read_b128 v[192:195], v142 offset:23552
	s_waitcnt vmcnt(2) lgkmcnt(0)
	s_barrier
	s_setprio 1
	v_mfma_f32_16x16x32_bf16 v[62:65], v[162:165], v[146:149], v[62:65]
	v_mfma_f32_16x16x32_bf16 v[58:61], v[162:165], v[154:157], v[58:61]
	v_mfma_f32_16x16x32_bf16 v[50:53], v[170:173], v[154:157], v[50:53]
	v_mfma_f32_16x16x32_bf16 v[54:57], v[170:173], v[146:149], v[54:57]
	v_mfma_f32_16x16x32_bf16 v[46:49], v[180:183], v[146:149], v[46:49]
	v_mfma_f32_16x16x32_bf16 v[42:45], v[180:183], v[154:157], v[42:45]
	v_mfma_f32_16x16x32_bf16 v[34:37], v[188:191], v[154:157], v[34:37]
	v_mfma_f32_16x16x32_bf16 v[38:41], v[188:191], v[146:149], v[38:41]
	v_mfma_f32_16x16x32_bf16 v[62:65], v[166:169], v[150:153], v[62:65]
	v_mfma_f32_16x16x32_bf16 v[58:61], v[166:169], v[158:161], v[58:61]
	v_mfma_f32_16x16x32_bf16 v[50:53], v[174:177], v[158:161], v[50:53]
	v_mfma_f32_16x16x32_bf16 v[54:57], v[174:177], v[150:153], v[54:57]
	v_mfma_f32_16x16x32_bf16 v[46:49], v[184:187], v[150:153], v[46:49]
	v_mfma_f32_16x16x32_bf16 v[42:45], v[184:187], v[158:161], v[42:45]
	v_mfma_f32_16x16x32_bf16 v[34:37], v[192:195], v[158:161], v[34:37]
	v_mfma_f32_16x16x32_bf16 v[38:41], v[192:195], v[150:153], v[38:41]
	v_mfma_f32_16x16x32_bf16 v[30:33], v[162:165], v[196:199], v[30:33]
	v_mfma_f32_16x16x32_bf16 v[26:29], v[162:165], v[204:207], v[26:29]
	v_mfma_f32_16x16x32_bf16 v[18:21], v[170:173], v[204:207], v[18:21]
	v_mfma_f32_16x16x32_bf16 v[22:25], v[170:173], v[196:199], v[22:25]
	v_mfma_f32_16x16x32_bf16 v[14:17], v[180:183], v[196:199], v[14:17]
	v_mfma_f32_16x16x32_bf16 v[10:13], v[180:183], v[204:207], v[10:13]
	v_mfma_f32_16x16x32_bf16 v[2:5], v[188:191], v[204:207], v[2:5]
	v_mfma_f32_16x16x32_bf16 v[6:9], v[188:191], v[196:199], v[6:9]
	v_mfma_f32_16x16x32_bf16 v[30:33], v[166:169], v[200:203], v[30:33]
	v_mfma_f32_16x16x32_bf16 v[26:29], v[166:169], v[208:211], v[26:29]
	v_mfma_f32_16x16x32_bf16 v[18:21], v[174:177], v[208:211], v[18:21]
	v_mfma_f32_16x16x32_bf16 v[22:25], v[174:177], v[200:203], v[22:25]
	v_mfma_f32_16x16x32_bf16 v[14:17], v[184:187], v[200:203], v[14:17]
	v_mfma_f32_16x16x32_bf16 v[10:13], v[184:187], v[208:211], v[10:13]
	v_mfma_f32_16x16x32_bf16 v[2:5], v[192:195], v[208:211], v[2:5]
	v_mfma_f32_16x16x32_bf16 v[6:9], v[192:195], v[200:203], v[6:9]
	s_setprio 0
	s_barrier
; #define WAIT_V(n) asm volatile("s_waitcnt vmcnt(" #n ")" ::: "memory")
; #define WAIT_L(n) asm volatile("s_waitcnt lgkmcnt(" #n ")" ::: "memory")
; #define BAR __builtin_amdgcn_s_barrier()
; #define STG_A(b, h, kt) stage_half_s(lds0 + ((b) * 2 + (h)) * HT_B, ((h) ? A1 : Ap) + (kt) * BK, off0, off1)
; #define STG_A(b, h, kt) stage_half_s(lds0 + ((b) * 2 + (h)) * HT_B, ((h) ? A1 : Ap) + (kt) * BK, off0, off1)
; #define LDA8(b, h) _Pragma("unroll") for (int m = 0; m < 4; ++m) _Pragma("unroll") for (int k = 0; k < 2; ++k) \
;     At[m][k] = *(const bf16x8*)(SA_(shm, b, h) + abase + (m * 2 + k) * 1024)
; #define LDB8(dst, b, h) _Pragma("unroll") for (int n = 0; n < 2; ++n) _Pragma("unroll") for (int k = 0; k < 2; ++k) \
;     dst[n][k] = *(const bf16x8*)(SB_(shm, b, h) + bbase + (n * 2 + k) * 1024)
; #define MMA8(ai, bj, Bx) do { __builtin_amdgcn_s_setprio(1); \
;     _Pragma("unroll") for (int m = 0; m < 4; ++m) _Pragma("unroll") for (int n = 0; n < 2; ++n) _Pragma("unroll") for (int k = 0; k < 2; ++k) \
;       acc[ai][bj][m][n] = __builtin_amdgcn_mfma_f32_16x16x32_bf16(At[m][k], Bx[n][k], acc[ai][bj][m][n], 0, 0, 0); \
;     __builtin_amdgcn_s_setprio(0); } while (0)
; template <bool HS>
; __device__ __forceinline__ void gemm_tile8(const u16* __restrict__ Ap, const u16* __restrict__ Bp, int K,
;                                            f32x4 (&acc)[2][2][4][2], char* shm, const int tid, const float* hsr = nullptr) {
;     ...
;   { LDB8(B0, 0, 0); LDA8(0, 0); STG_A(1, 1, nt - 1);
;     BAR; WAIT_L(0); MMA8(0, 0, B0); BAR;
;     LDB8(B1, 0, 1); BAR; WAIT_L(0); MMA8(0, 1, B1); BAR;
;     LDA8(0, 1); WAIT_V(4); BAR; WAIT_L(0); MMA8(1, 0, B0); MMA8(1, 1, B1); BAR; }
;   { LDB8(B0, 1, 0); LDA8(1, 0); WAIT_V(2); BAR; WAIT_L(0); MMA8(0, 0, B0); BAR;
;     LDB8(B1, 1, 1); WAIT_V(0); BAR; WAIT_L(0); MMA8(0, 1, B1); BAR;
;     LDA8(1, 1); BAR; WAIT_L(0); MMA8(1, 0, B0); MMA8(1, 1, B1); BAR; }
;   if (wr == 0) BAR;
	ds_read_b128 v[146:149], v246
	ds_read_b128 v[150:153], v246 offset:1024
	ds_read_b128 v[154:157], v246 offset:2048
	ds_read_b128 v[158:161], v246 offset:3072
	ds_read_b128 v[162:165], v142 offset:32768
	ds_read_b128 v[166:169], v142 offset:33792
	ds_read_b128 v[170:173], v142 offset:34816
	ds_read_b128 v[174:177], v142 offset:35840
	ds_read_b128 v[180:183], v142 offset:36864
	ds_read_b128 v[184:187], v142 offset:37888
	ds_read_b128 v[188:191], v142 offset:38912
	ds_read_b128 v[192:195], v142 offset:39936
	ds_read_b128 v[196:199], v247
	ds_read_b128 v[200:203], v247 offset:1024
	ds_read_b128 v[204:207], v247 offset:2048
	ds_read_b128 v[208:211], v247 offset:3072
	s_waitcnt vmcnt(0) lgkmcnt(0)
	s_barrier
	s_setprio 1
	v_mfma_f32_16x16x32_bf16 v[126:129], v[162:165], v[146:149], v[126:129]
	v_mfma_f32_16x16x32_bf16 v[122:125], v[162:165], v[154:157], v[122:125]
	v_mfma_f32_16x16x32_bf16 v[114:117], v[170:173], v[154:157], v[114:117]
	v_mfma_f32_16x16x32_bf16 v[118:121], v[170:173], v[146:149], v[118:121]
	v_mfma_f32_16x16x32_bf16 v[110:113], v[180:183], v[146:149], v[110:113]
	v_mfma_f32_16x16x32_bf16 v[106:109], v[180:183], v[154:157], v[106:109]
	v_mfma_f32_16x16x32_bf16 v[98:101], v[188:191], v[154:157], v[98:101]
	v_mfma_f32_16x16x32_bf16 v[102:105], v[188:191], v[146:149], v[102:105]
	v_mfma_f32_16x16x32_bf16 v[126:129], v[166:169], v[150:153], v[126:129]
	v_mfma_f32_16x16x32_bf16 v[122:125], v[166:169], v[158:161], v[122:125]
	v_mfma_f32_16x16x32_bf16 v[114:117], v[174:177], v[158:161], v[114:117]
	v_mfma_f32_16x16x32_bf16 v[118:121], v[174:177], v[150:153], v[118:121]
	v_mfma_f32_16x16x32_bf16 v[110:113], v[184:187], v[150:153], v[110:113]
	v_mfma_f32_16x16x32_bf16 v[106:109], v[184:187], v[158:161], v[106:109]
	v_mfma_f32_16x16x32_bf16 v[98:101], v[192:195], v[158:161], v[98:101]
	v_mfma_f32_16x16x32_bf16 v[102:105], v[192:195], v[150:153], v[102:105]
	v_mfma_f32_16x16x32_bf16 v[94:97], v[162:165], v[196:199], v[94:97]
	v_mfma_f32_16x16x32_bf16 v[90:93], v[162:165], v[204:207], v[90:93]
	v_mfma_f32_16x16x32_bf16 v[82:85], v[170:173], v[204:207], v[82:85]
	v_mfma_f32_16x16x32_bf16 v[86:89], v[170:173], v[196:199], v[86:89]
	v_mfma_f32_16x16x32_bf16 v[78:81], v[180:183], v[196:199], v[78:81]
	v_mfma_f32_16x16x32_bf16 v[74:77], v[180:183], v[204:207], v[74:77]
	v_mfma_f32_16x16x32_bf16 v[66:69], v[188:191], v[204:207], v[66:69]
	v_mfma_f32_16x16x32_bf16 v[70:73], v[188:191], v[196:199], v[70:73]
	v_mfma_f32_16x16x32_bf16 v[94:97], v[166:169], v[200:203], v[94:97]
	v_mfma_f32_16x16x32_bf16 v[90:93], v[166:169], v[208:211], v[90:93]
	v_mfma_f32_16x16x32_bf16 v[82:85], v[174:177], v[208:211], v[82:85]
	v_mfma_f32_16x16x32_bf16 v[86:89], v[174:177], v[200:203], v[86:89]
	v_mfma_f32_16x16x32_bf16 v[78:81], v[184:187], v[200:203], v[78:81]
	v_mfma_f32_16x16x32_bf16 v[74:77], v[184:187], v[208:211], v[74:77]
	v_mfma_f32_16x16x32_bf16 v[66:69], v[192:195], v[208:211], v[66:69]
	v_mfma_f32_16x16x32_bf16 v[70:73], v[192:195], v[200:203], v[70:73]
	s_setprio 0
	s_barrier
	ds_read_b128 v[162:165], v142 offset:49152
	ds_read_b128 v[166:169], v142 offset:50176
	ds_read_b128 v[170:173], v142 offset:51200
	ds_read_b128 v[174:177], v142 offset:52224
	ds_read_b128 v[180:183], v142 offset:53248
	ds_read_b128 v[184:187], v142 offset:54272
	ds_read_b128 v[188:191], v142 offset:55296
	ds_read_b128 v[192:195], v142 offset:56320
	s_waitcnt lgkmcnt(0)
	s_barrier
	s_setprio 1
	v_mfma_f32_16x16x32_bf16 v[62:65], v[162:165], v[146:149], v[62:65]
	v_mfma_f32_16x16x32_bf16 v[58:61], v[162:165], v[154:157], v[58:61]
	v_mfma_f32_16x16x32_bf16 v[50:53], v[170:173], v[154:157], v[50:53]
	v_mfma_f32_16x16x32_bf16 v[54:57], v[170:173], v[146:149], v[54:57]
	v_mfma_f32_16x16x32_bf16 v[46:49], v[180:183], v[146:149], v[46:49]
	v_mfma_f32_16x16x32_bf16 v[42:45], v[180:183], v[154:157], v[42:45]
	v_mfma_f32_16x16x32_bf16 v[34:37], v[188:191], v[154:157], v[34:37]
	v_mfma_f32_16x16x32_bf16 v[38:41], v[188:191], v[146:149], v[38:41]
	v_mfma_f32_16x16x32_bf16 v[62:65], v[166:169], v[150:153], v[62:65]
	v_mfma_f32_16x16x32_bf16 v[58:61], v[166:169], v[158:161], v[58:61]
	v_mfma_f32_16x16x32_bf16 v[50:53], v[174:177], v[158:161], v[50:53]
	v_mfma_f32_16x16x32_bf16 v[54:57], v[174:177], v[150:153], v[54:57]
	v_mfma_f32_16x16x32_bf16 v[46:49], v[184:187], v[150:153], v[46:49]
	v_mfma_f32_16x16x32_bf16 v[42:45], v[184:187], v[158:161], v[42:45]
	v_mfma_f32_16x16x32_bf16 v[34:37], v[192:195], v[158:161], v[34:37]
	v_mfma_f32_16x16x32_bf16 v[38:41], v[192:195], v[150:153], v[38:41]
	v_mfma_f32_16x16x32_bf16 v[30:33], v[162:165], v[196:199], v[30:33]
	v_mfma_f32_16x16x32_bf16 v[26:29], v[162:165], v[204:207], v[26:29]
	v_mfma_f32_16x16x32_bf16 v[18:21], v[170:173], v[204:207], v[18:21]
	v_mfma_f32_16x16x32_bf16 v[22:25], v[170:173], v[196:199], v[22:25]
	v_mfma_f32_16x16x32_bf16 v[14:17], v[180:183], v[196:199], v[14:17]
	v_mfma_f32_16x16x32_bf16 v[10:13], v[180:183], v[204:207], v[10:13]
	v_mfma_f32_16x16x32_bf16 v[2:5], v[188:191], v[204:207], v[2:5]
	v_mfma_f32_16x16x32_bf16 v[6:9], v[188:191], v[196:199], v[6:9]
	v_mfma_f32_16x16x32_bf16 v[30:33], v[166:169], v[200:203], v[30:33]
	v_mfma_f32_16x16x32_bf16 v[26:29], v[166:169], v[208:211], v[26:29]
	v_mfma_f32_16x16x32_bf16 v[18:21], v[174:177], v[208:211], v[18:21]
	v_mfma_f32_16x16x32_bf16 v[22:25], v[174:177], v[200:203], v[22:25]
	v_mfma_f32_16x16x32_bf16 v[14:17], v[184:187], v[200:203], v[14:17]
	v_mfma_f32_16x16x32_bf16 v[10:13], v[184:187], v[208:211], v[10:13]
	v_mfma_f32_16x16x32_bf16 v[2:5], v[192:195], v[208:211], v[2:5]
	v_mfma_f32_16x16x32_bf16 v[6:9], v[192:195], v[200:203], v[6:9]
	s_setprio 0
	s_movk_i32 s0, 0x100
	v_cmp_gt_u32_e32 vcc, s0, v0
	s_barrier
	s_and_saveexec_b64 s[0:1], vcc
	s_cbranch_execz .LBB0_862
	s_barrier
